# carry scan and hyena epilogues: flat_load/flat_store on global pointers replaced by global_load/global_store (no lgkmcnt limit of 15 in flight)
# speedup vs baseline: 1.0035x; 1.0006x over previous
.LBB0_486:
	v_add_u32_e32 v0, s2, v154
	v_add_u32_e32 v165, s2, v155
	s_waitcnt lgkmcnt(0)
	v_mfma_f32_16x16x32_bf16 v[10:13], v[126:129], v[134:137], v[10:13]
	v_add_u32_e32 v166, 0x10140, v165
	v_mfma_f32_16x16x32_bf16 v[6:9], v[122:125], v[134:137], v[6:9]
	ds_read_b128 v[122:125], v0
	ds_read_b128 v[126:129], v0 offset:32
	ds_read_b128 v[166:169], v166
	v_mfma_f32_16x16x32_bf16 v[130:133], v[70:73], v[134:137], v[130:133]
	v_mfma_f32_16x16x32_bf16 v[62:65], v[66:69], v[134:137], v[62:65]
	v_mfma_f32_16x16x32_bf16 v[58:61], v[78:81], v[134:137], v[58:61]
	v_mfma_f32_16x16x32_bf16 v[54:57], v[74:77], v[134:137], v[54:57]
	v_mfma_f32_16x16x32_bf16 v[50:53], v[86:89], v[134:137], v[50:53]
	v_mfma_f32_16x16x32_bf16 v[46:49], v[82:85], v[134:137], v[46:49]
	v_mfma_f32_16x16x32_bf16 v[42:45], v[94:97], v[134:137], v[42:45]
	v_mfma_f32_16x16x32_bf16 v[38:41], v[90:93], v[134:137], v[38:41]
	v_mfma_f32_16x16x32_bf16 v[34:37], v[102:105], v[134:137], v[34:37]
	v_mfma_f32_16x16x32_bf16 v[30:33], v[98:101], v[134:137], v[30:33]
	v_mfma_f32_16x16x32_bf16 v[26:29], v[110:113], v[134:137], v[26:29]
	v_mfma_f32_16x16x32_bf16 v[22:25], v[106:109], v[134:137], v[22:25]
	v_mfma_f32_16x16x32_bf16 v[18:21], v[118:121], v[134:137], v[18:21]
	v_mfma_f32_16x16x32_bf16 v[14:17], v[114:117], v[134:137], v[14:17]
	v_add_u32_e32 v134, 0x10180, v165
	s_waitcnt lgkmcnt(0)
	v_mfma_f32_16x16x32_bf16 v[10:13], v[118:121], v[166:169], v[10:13]
	v_mfma_f32_16x16x32_bf16 v[6:9], v[114:117], v[166:169], v[6:9]
	ds_read_b128 v[114:117], v0 offset:64
	ds_read_b128 v[118:121], v0 offset:96
	ds_read_b128 v[134:137], v134
	v_mfma_f32_16x16x32_bf16 v[130:133], v[126:129], v[166:169], v[130:133]
	v_mfma_f32_16x16x32_bf16 v[62:65], v[122:125], v[166:169], v[62:65]
	v_mfma_f32_16x16x32_bf16 v[58:61], v[70:73], v[166:169], v[58:61]
	v_mfma_f32_16x16x32_bf16 v[54:57], v[66:69], v[166:169], v[54:57]
	v_mfma_f32_16x16x32_bf16 v[50:53], v[78:81], v[166:169], v[50:53]
	v_mfma_f32_16x16x32_bf16 v[46:49], v[74:77], v[166:169], v[46:49]
	v_mfma_f32_16x16x32_bf16 v[42:45], v[86:89], v[166:169], v[42:45]
	v_mfma_f32_16x16x32_bf16 v[38:41], v[82:85], v[166:169], v[38:41]
	v_mfma_f32_16x16x32_bf16 v[34:37], v[94:97], v[166:169], v[34:37]
	v_mfma_f32_16x16x32_bf16 v[30:33], v[90:93], v[166:169], v[30:33]
	v_mfma_f32_16x16x32_bf16 v[26:29], v[102:105], v[166:169], v[26:29]
	v_mfma_f32_16x16x32_bf16 v[22:25], v[98:101], v[166:169], v[22:25]
	v_mfma_f32_16x16x32_bf16 v[18:21], v[110:113], v[166:169], v[18:21]
	v_mfma_f32_16x16x32_bf16 v[14:17], v[106:109], v[166:169], v[14:17]
	s_waitcnt lgkmcnt(0)
	v_mfma_f32_16x16x32_bf16 v[10:13], v[110:113], v[134:137], v[10:13]
	v_add_u32_e32 v166, 0x101c0, v165
	v_mfma_f32_16x16x32_bf16 v[6:9], v[106:109], v[134:137], v[6:9]
	ds_read_b128 v[106:109], v0 offset:128
	ds_read_b128 v[110:113], v0 offset:160
	ds_read_b128 v[166:169], v166
	v_mfma_f32_16x16x32_bf16 v[130:133], v[118:121], v[134:137], v[130:133]
	v_mfma_f32_16x16x32_bf16 v[62:65], v[114:117], v[134:137], v[62:65]
	v_mfma_f32_16x16x32_bf16 v[58:61], v[126:129], v[134:137], v[58:61]
	v_mfma_f32_16x16x32_bf16 v[54:57], v[122:125], v[134:137], v[54:57]
	v_mfma_f32_16x16x32_bf16 v[50:53], v[70:73], v[134:137], v[50:53]
	v_mfma_f32_16x16x32_bf16 v[46:49], v[66:69], v[134:137], v[46:49]
	v_mfma_f32_16x16x32_bf16 v[42:45], v[78:81], v[134:137], v[42:45]
	v_mfma_f32_16x16x32_bf16 v[38:41], v[74:77], v[134:137], v[38:41]
	v_mfma_f32_16x16x32_bf16 v[34:37], v[86:89], v[134:137], v[34:37]
	v_mfma_f32_16x16x32_bf16 v[30:33], v[82:85], v[134:137], v[30:33]
	v_mfma_f32_16x16x32_bf16 v[26:29], v[94:97], v[134:137], v[26:29]
	v_mfma_f32_16x16x32_bf16 v[22:25], v[90:93], v[134:137], v[22:25]
	v_mfma_f32_16x16x32_bf16 v[18:21], v[102:105], v[134:137], v[18:21]
	v_mfma_f32_16x16x32_bf16 v[14:17], v[98:101], v[134:137], v[14:17]
	v_add_u32_e32 v134, 0x10200, v165
	s_waitcnt lgkmcnt(0)
	v_mfma_f32_16x16x32_bf16 v[10:13], v[102:105], v[166:169], v[10:13]
	v_mfma_f32_16x16x32_bf16 v[6:9], v[98:101], v[166:169], v[6:9]
	ds_read_b128 v[98:101], v0 offset:192
	ds_read_b128 v[102:105], v0 offset:224
	ds_read_b128 v[134:137], v134
	v_mfma_f32_16x16x32_bf16 v[130:133], v[110:113], v[166:169], v[130:133]
	v_mfma_f32_16x16x32_bf16 v[62:65], v[106:109], v[166:169], v[62:65]
	v_mfma_f32_16x16x32_bf16 v[58:61], v[118:121], v[166:169], v[58:61]
	v_mfma_f32_16x16x32_bf16 v[54:57], v[114:117], v[166:169], v[54:57]
	v_mfma_f32_16x16x32_bf16 v[50:53], v[126:129], v[166:169], v[50:53]
	v_mfma_f32_16x16x32_bf16 v[46:49], v[122:125], v[166:169], v[46:49]
	v_mfma_f32_16x16x32_bf16 v[42:45], v[70:73], v[166:169], v[42:45]
	v_mfma_f32_16x16x32_bf16 v[38:41], v[66:69], v[166:169], v[38:41]
	v_mfma_f32_16x16x32_bf16 v[34:37], v[78:81], v[166:169], v[34:37]
	v_mfma_f32_16x16x32_bf16 v[30:33], v[74:77], v[166:169], v[30:33]
	v_mfma_f32_16x16x32_bf16 v[26:29], v[86:89], v[166:169], v[26:29]
	v_mfma_f32_16x16x32_bf16 v[22:25], v[82:85], v[166:169], v[22:25]
	v_mfma_f32_16x16x32_bf16 v[18:21], v[94:97], v[166:169], v[18:21]
	v_mfma_f32_16x16x32_bf16 v[14:17], v[90:93], v[166:169], v[14:17]
	s_waitcnt lgkmcnt(0)
	v_mfma_f32_16x16x32_bf16 v[10:13], v[94:97], v[134:137], v[10:13]
	v_add_u32_e32 v166, 0x10240, v165
	v_mfma_f32_16x16x32_bf16 v[6:9], v[90:93], v[134:137], v[6:9]
	ds_read_b128 v[90:93], v0 offset:256
	ds_read_b128 v[94:97], v0 offset:288
	ds_read_b128 v[166:169], v166
	v_mfma_f32_16x16x32_bf16 v[130:133], v[102:105], v[134:137], v[130:133]
	v_mfma_f32_16x16x32_bf16 v[62:65], v[98:101], v[134:137], v[62:65]
	v_mfma_f32_16x16x32_bf16 v[58:61], v[110:113], v[134:137], v[58:61]
	v_mfma_f32_16x16x32_bf16 v[54:57], v[106:109], v[134:137], v[54:57]
	v_mfma_f32_16x16x32_bf16 v[50:53], v[118:121], v[134:137], v[50:53]
	v_mfma_f32_16x16x32_bf16 v[46:49], v[114:117], v[134:137], v[46:49]
	v_mfma_f32_16x16x32_bf16 v[42:45], v[126:129], v[134:137], v[42:45]
	v_mfma_f32_16x16x32_bf16 v[38:41], v[122:125], v[134:137], v[38:41]
	v_mfma_f32_16x16x32_bf16 v[34:37], v[70:73], v[134:137], v[34:37]
	v_mfma_f32_16x16x32_bf16 v[30:33], v[66:69], v[134:137], v[30:33]
	v_mfma_f32_16x16x32_bf16 v[26:29], v[78:81], v[134:137], v[26:29]
	v_mfma_f32_16x16x32_bf16 v[22:25], v[74:77], v[134:137], v[22:25]
	v_mfma_f32_16x16x32_bf16 v[18:21], v[86:89], v[134:137], v[18:21]
	v_mfma_f32_16x16x32_bf16 v[14:17], v[82:85], v[134:137], v[14:17]
	v_add_u32_e32 v134, 0x10280, v165
	s_waitcnt lgkmcnt(0)
	v_mfma_f32_16x16x32_bf16 v[10:13], v[86:89], v[166:169], v[10:13]
	v_mfma_f32_16x16x32_bf16 v[6:9], v[82:85], v[166:169], v[6:9]
	ds_read_b128 v[82:85], v0 offset:320
	ds_read_b128 v[86:89], v0 offset:352
	ds_read_b128 v[134:137], v134
	v_mfma_f32_16x16x32_bf16 v[130:133], v[94:97], v[166:169], v[130:133]
	v_mfma_f32_16x16x32_bf16 v[62:65], v[90:93], v[166:169], v[62:65]
	v_mfma_f32_16x16x32_bf16 v[58:61], v[102:105], v[166:169], v[58:61]
	v_mfma_f32_16x16x32_bf16 v[54:57], v[98:101], v[166:169], v[54:57]
	v_mfma_f32_16x16x32_bf16 v[50:53], v[110:113], v[166:169], v[50:53]
	v_mfma_f32_16x16x32_bf16 v[46:49], v[106:109], v[166:169], v[46:49]
	v_mfma_f32_16x16x32_bf16 v[42:45], v[118:121], v[166:169], v[42:45]
	v_mfma_f32_16x16x32_bf16 v[38:41], v[114:117], v[166:169], v[38:41]
	v_mfma_f32_16x16x32_bf16 v[34:37], v[126:129], v[166:169], v[34:37]
	v_mfma_f32_16x16x32_bf16 v[30:33], v[122:125], v[166:169], v[30:33]
	v_mfma_f32_16x16x32_bf16 v[26:29], v[70:73], v[166:169], v[26:29]
	v_mfma_f32_16x16x32_bf16 v[22:25], v[66:69], v[166:169], v[22:25]
	v_mfma_f32_16x16x32_bf16 v[18:21], v[78:81], v[166:169], v[18:21]
	v_mfma_f32_16x16x32_bf16 v[14:17], v[74:77], v[166:169], v[14:17]
	s_waitcnt lgkmcnt(0)
	v_mfma_f32_16x16x32_bf16 v[10:13], v[78:81], v[134:137], v[10:13]
	v_add_u32_e32 v166, 0x102c0, v165
	v_mfma_f32_16x16x32_bf16 v[6:9], v[74:77], v[134:137], v[6:9]
	ds_read_b128 v[74:77], v0 offset:384
	ds_read_b128 v[78:81], v0 offset:416
	ds_read_b128 v[166:169], v166
	v_mfma_f32_16x16x32_bf16 v[130:133], v[86:89], v[134:137], v[130:133]
	v_mfma_f32_16x16x32_bf16 v[62:65], v[82:85], v[134:137], v[62:65]
	v_mfma_f32_16x16x32_bf16 v[58:61], v[94:97], v[134:137], v[58:61]
	v_mfma_f32_16x16x32_bf16 v[54:57], v[90:93], v[134:137], v[54:57]
	v_mfma_f32_16x16x32_bf16 v[50:53], v[102:105], v[134:137], v[50:53]
	v_mfma_f32_16x16x32_bf16 v[46:49], v[98:101], v[134:137], v[46:49]
	v_mfma_f32_16x16x32_bf16 v[42:45], v[110:113], v[134:137], v[42:45]
	v_mfma_f32_16x16x32_bf16 v[38:41], v[106:109], v[134:137], v[38:41]
	v_mfma_f32_16x16x32_bf16 v[34:37], v[118:121], v[134:137], v[34:37]
	v_mfma_f32_16x16x32_bf16 v[30:33], v[114:117], v[134:137], v[30:33]
	v_mfma_f32_16x16x32_bf16 v[26:29], v[126:129], v[134:137], v[26:29]
	v_mfma_f32_16x16x32_bf16 v[22:25], v[122:125], v[134:137], v[22:25]
	v_mfma_f32_16x16x32_bf16 v[18:21], v[70:73], v[134:137], v[18:21]
	v_mfma_f32_16x16x32_bf16 v[14:17], v[66:69], v[134:137], v[14:17]
	s_waitcnt lgkmcnt(0)
	v_mfma_f32_16x16x32_bf16 v[10:13], v[70:73], v[166:169], v[10:13]
	v_mfma_f32_16x16x32_bf16 v[6:9], v[66:69], v[166:169], v[6:9]
	ds_read_b128 v[66:69], v0 offset:448
	ds_read_b128 v[70:73], v0 offset:480
	v_add_u32_e32 v0, 0x10300, v165
	ds_read_b128 v[134:137], v0
	v_mfma_f32_16x16x32_bf16 v[130:133], v[78:81], v[166:169], v[130:133]
	v_mfma_f32_16x16x32_bf16 v[62:65], v[74:77], v[166:169], v[62:65]
	v_mfma_f32_16x16x32_bf16 v[58:61], v[86:89], v[166:169], v[58:61]
	v_mfma_f32_16x16x32_bf16 v[54:57], v[82:85], v[166:169], v[54:57]
	v_mfma_f32_16x16x32_bf16 v[50:53], v[94:97], v[166:169], v[50:53]
	v_mfma_f32_16x16x32_bf16 v[46:49], v[90:93], v[166:169], v[46:49]
	v_mfma_f32_16x16x32_bf16 v[42:45], v[102:105], v[166:169], v[42:45]
	v_mfma_f32_16x16x32_bf16 v[38:41], v[98:101], v[166:169], v[38:41]
	v_mfma_f32_16x16x32_bf16 v[34:37], v[110:113], v[166:169], v[34:37]
	v_mfma_f32_16x16x32_bf16 v[30:33], v[106:109], v[166:169], v[30:33]
	v_mfma_f32_16x16x32_bf16 v[26:29], v[118:121], v[166:169], v[26:29]
	v_mfma_f32_16x16x32_bf16 v[22:25], v[114:117], v[166:169], v[22:25]
	v_mfma_f32_16x16x32_bf16 v[18:21], v[126:129], v[166:169], v[18:21]
	v_mfma_f32_16x16x32_bf16 v[14:17], v[122:125], v[166:169], v[14:17]
	s_addk_i32 s2, 0x200
	s_cmpk_lg_i32 s2, 0x1000
	s_cbranch_scc1 .LBB0_486
	s_add_u32 s2, s74, s58
	s_addc_u32 s3, s75, s59
	v_mov_b32_e32 v0, 0
	s_waitcnt lgkmcnt(2)
	global_load_dword v66, v0, s[2:3]
	s_waitcnt lgkmcnt(0)
	global_load_dword v134, v0, s[2:3] offset:2048
	global_load_dword v72, v0, s[44:45] offset:2048
	global_load_dword v74, v0, s[48:49] offset:2048
	global_load_dword v70, v158, s[44:45]
	global_load_dword v68, v157, s[44:45] offset:2048
	s_lshl_b64 s[2:3], s[50:51], 16
	v_lshl_add_u64 v[82:83], v[144:145], 0, s[2:3]
	global_load_dwordx2 v[84:85], v[82:83], off
	global_load_dwordx2 v[136:137], v[82:83], off offset:32
	global_load_dwordx2 v[128:129], v[82:83], off offset:64
	global_load_dwordx2 v[124:125], v[82:83], off offset:96
	global_load_dwordx2 v[120:121], v[82:83], off offset:128
	global_load_dwordx2 v[116:117], v[82:83], off offset:160
	global_load_dwordx2 v[112:113], v[82:83], off offset:192
	global_load_dwordx2 v[108:109], v[82:83], off offset:224
	global_load_dwordx2 v[104:105], v[82:83], off offset:256
	global_load_dwordx2 v[100:101], v[82:83], off offset:288
	global_load_dwordx2 v[94:95], v[82:83], off offset:320
	global_load_dwordx2 v[90:91], v[82:83], off offset:352
	v_lshl_add_u64 v[76:77], v[146:147], 1, v[82:83]
	global_load_ushort v67, v[76:77], off
	global_load_dwordx2 v[86:87], v[82:83], off offset:384
	global_load_dwordx2 v[80:81], v[82:83], off offset:416
	global_load_dwordx2 v[78:79], v[82:83], off offset:448
	s_nop 0
	global_load_dwordx2 v[76:77], v[82:83], off offset:480
	v_lshl_add_u64 v[82:83], v[82:83], 0, v[140:141]
	global_load_ushort v89, v[82:83], off offset:480
	s_waitcnt vmcnt(0) lgkmcnt(0)
	ds_bpermute_b32 v69, v162, v85
	v_cndmask_b32_e64 v71, v84, v136, s[12:13]
	v_cndmask_b32_e64 v73, v137, v85, s[10:11]
	v_cndmask_b32_e64 v82, v129, v137, s[10:11]
	v_cndmask_b32_e64 v92, v124, v120, s[12:13]
	s_waitcnt lgkmcnt(0)
	v_lshrrev_b32_e32 v69, 16, v69
	v_cndmask_b32_e64 v99, v113, v117, s[10:11]
	v_cndmask_b32_e64 v102, v112, v108, s[12:13]
	v_cndmask_b32_e64 v93, v121, v125, s[10:11]
	v_cndmask_b32_e64 v111, v101, v105, s[10:11]
	v_cndmask_b32_e64 v115, v95, v101, s[10:11]
	v_cndmask_b32_e64 v119, v91, v95, s[10:11]
	v_cndmask_b32_e64 v67, v67, 0, s[8:9]
	v_cndmask_b32_e64 v96, v120, v116, s[12:13]
	v_cndmask_b32_e64 v103, v109, v113, s[10:11]
	ds_bpermute_b32 v165, v163, v92
	ds_bpermute_b32 v92, v162, v99
	ds_bpermute_b32 v99, v163, v102
	ds_bpermute_b32 v102, v162, v111
	ds_bpermute_b32 v111, v162, v115
	ds_bpermute_b32 v115, v162, v119
	v_cndmask_b32_e64 v119, v69, v67, s[12:13]
	v_cndmask_b32_e64 v67, v87, v91, s[10:11]
	ds_bpermute_b32 v123, v163, v71
	ds_bpermute_b32 v71, v162, v73
	ds_bpermute_b32 v73, v162, v82
	ds_bpermute_b32 v82, v162, v93
	ds_bpermute_b32 v93, v163, v96
	ds_bpermute_b32 v96, v162, v103
	ds_bpermute_b32 v67, v162, v67
	v_cndmask_b32_e64 v75, v136, v128, s[12:13]
	v_cndmask_b32_e64 v88, v125, v129, s[10:11]
	v_cndmask_b32_e64 v114, v100, v94, s[12:13]
	ds_bpermute_b32 v127, v163, v75
	ds_bpermute_b32 v75, v162, v88
	ds_bpermute_b32 v186, v163, v114
	s_waitcnt lgkmcnt(8)
	v_and_b32_e32 v170, 0xffff0000, v71
	s_waitcnt lgkmcnt(4)
	v_and_b32_e32 v114, 0xffff0000, v96
	v_cndmask_b32_e64 v71, v81, v87, s[10:11]
	s_waitcnt lgkmcnt(3)
	v_and_b32_e32 v96, 0xffff0000, v67
	v_cndmask_b32_e64 v67, v86, v80, s[12:13]
	v_cndmask_b32_e64 v97, v117, v121, s[10:11]
	v_and_b32_e32 v172, 0xffff0000, v73
	ds_bpermute_b32 v71, v162, v71
	ds_bpermute_b32 v73, v163, v67
	v_cndmask_b32_e64 v67, v79, v81, s[10:11]
	ds_bpermute_b32 v88, v162, v97
	ds_bpermute_b32 v67, v162, v67
	v_cndmask_b32_e64 v69, v90, v86, s[12:13]
	v_cndmask_b32_e64 v83, v128, v124, s[12:13]
	v_cndmask_b32_e64 v118, v94, v90, s[12:13]
	s_waitcnt lgkmcnt(5)
	v_and_b32_e32 v174, 0xffff0000, v75
	ds_bpermute_b32 v75, v163, v69
	v_cndmask_b32_e64 v69, v80, v78, s[12:13]
	ds_bpermute_b32 v135, v163, v83
	ds_bpermute_b32 v83, v163, v118
	v_and_b32_e32 v118, 0xffff0000, v92
	s_waitcnt lgkmcnt(6)
	v_and_b32_e32 v92, 0xffff0000, v71
	ds_bpermute_b32 v71, v163, v69
	v_and_b32_e32 v167, 0xffff0000, v85
	s_waitcnt lgkmcnt(5)
	v_and_b32_e32 v122, 0xffff0000, v88
	v_cndmask_b32_e64 v69, v77, v79, s[10:11]
	s_waitcnt lgkmcnt(4)
	v_and_b32_e32 v88, 0xffff0000, v67
	ds_bpermute_b32 v67, v163, v76
	v_lshlrev_b32_e32 v178, 16, v85
	v_and_b32_e32 v166, 16, v85
	v_mov_b32_e32 v179, v167
	v_and_b32_e32 v126, 0xffff0000, v82
	ds_bpermute_b32 v82, v162, v69
	v_cndmask_b32_e64 v69, v78, v76, s[12:13]
	v_pk_mov_b32 v[180:181], v[166:167], v[178:179] op_sel:[1,0]
	ds_bpermute_b32 v69, v163, v69
	v_and_b32_e32 v176, 0xffff0000, v84
	v_mov_b32_e32 v177, v181
	s_waitcnt lgkmcnt(6)
	v_pk_fma_f32 v[166:167], v[72:73], v[176:177], v[74:75] op_sel_hi:[0,1,0]
	v_cndmask_b32_e64 v89, v89, 0, s[14:15]
	s_waitcnt lgkmcnt(3)
	v_pk_fma_f32 v[182:183], v[70:71], v[178:179], v[166:167] op_sel_hi:[0,1,1]
	ds_read2_b64 v[166:169], v164 offset1:4
	s_waitcnt lgkmcnt(3)
	v_cndmask_b32_e64 v67, v67, v89, s[10:11]
	v_lshlrev_b32_e32 v89, 16, v123
	v_mov_b32_e32 v181, v89
	s_waitcnt lgkmcnt(1)
	v_pk_fma_f32 v[180:181], v[68:69], v[180:181], v[182:183] op_sel_hi:[0,1,1]
	v_lshlrev_b32_e32 v182, 16, v119
	v_lshlrev_b32_e32 v183, 16, v84
	v_pk_fma_f32 v[84:85], v[72:73], v[182:183], v[74:75] op_sel_hi:[0,1,0]
	v_pk_mov_b32 v[182:183], v[182:183], v[176:177] op_sel:[1,0]
	s_waitcnt lgkmcnt(0)
	v_lshlrev_b32_e32 v184, 16, v166
	v_and_b32_e32 v185, 0xffff0000, v166
	v_pk_fma_f32 v[84:85], v[70:71], v[182:183], v[84:85] op_sel_hi:[0,1,1]
	v_mov_b32_e32 v177, v178
	v_pk_fma_f32 v[130:131], v[66:67], v[184:185], v[130:131] op_sel_hi:[0,1,1]
	v_pk_fma_f32 v[84:85], v[68:69], v[176:177], v[84:85] op_sel_hi:[0,1,1]
	v_pk_mul_f32 v[84:85], v[84:85], v[130:131]
	v_lshlrev_b32_e32 v130, 16, v167
	v_and_b32_e32 v131, 0xffff0000, v167
	v_pk_fma_f32 v[130:131], v[66:67], v[130:131], v[132:133] op_sel_hi:[0,1,1]
	v_and_b32_e32 v167, 0xffff0000, v137
	v_pk_mul_f32 v[130:131], v[180:181], v[130:131]
	v_lshlrev_b32_e32 v132, 16, v137
	v_and_b32_e32 v166, 16, v137
	v_mov_b32_e32 v133, v167
	v_cvt_pk_bf16_f32 v84, v84, v85
	v_cvt_pk_bf16_f32 v85, v130, v131
	v_lshlrev_b32_e32 v171, 16, v136
	v_and_b32_e32 v130, 0xffff0000, v136
	v_pk_mov_b32 v[136:137], v[166:167], v[132:133] op_sel:[1,0]
	v_lshlrev_b32_e32 v89, 16, v127
	v_mov_b32_e32 v131, v137
	v_pk_fma_f32 v[166:167], v[72:73], v[130:131], v[74:75] op_sel_hi:[0,1,0]
	v_mov_b32_e32 v137, v89
	v_pk_fma_f32 v[166:167], v[70:71], v[132:133], v[166:167] op_sel_hi:[0,1,1]
	v_pk_fma_f32 v[136:137], v[68:69], v[136:137], v[166:167] op_sel_hi:[0,1,1]
	v_pk_fma_f32 v[166:167], v[72:73], v[170:171], v[74:75] op_sel_hi:[0,1,0]
	v_pk_mov_b32 v[170:171], v[170:171], v[130:131] op_sel:[1,0]
	v_lshlrev_b32_e32 v176, 16, v168
	v_and_b32_e32 v177, 0xffff0000, v168
	v_pk_fma_f32 v[166:167], v[70:71], v[170:171], v[166:167] op_sel_hi:[0,1,1]
	v_mov_b32_e32 v131, v132
	v_pk_fma_f32 v[62:63], v[66:67], v[176:177], v[62:63] op_sel_hi:[0,1,1]
	v_pk_fma_f32 v[130:131], v[68:69], v[130:131], v[166:167] op_sel_hi:[0,1,1]
	v_pk_mul_f32 v[62:63], v[130:131], v[62:63]
	v_lshlrev_b32_e32 v130, 16, v169
	v_and_b32_e32 v131, 0xffff0000, v169
	v_pk_fma_f32 v[64:65], v[66:67], v[130:131], v[64:65] op_sel_hi:[0,1,1]
	v_pk_mul_f32 v[64:65], v[136:137], v[64:65]
	ds_read2_b64 v[130:133], v164 offset0:8 offset1:12
	v_and_b32_e32 v137, 0xffff0000, v129
	v_cvt_pk_bf16_f32 v62, v62, v63
	v_cvt_pk_bf16_f32 v63, v64, v65
	v_lshlrev_b32_e32 v173, 16, v128
	v_and_b32_e32 v64, 0xffff0000, v128
	v_lshlrev_b32_e32 v128, 16, v129
	v_and_b32_e32 v136, 16, v129
	v_mov_b32_e32 v129, v137
	v_pk_mov_b32 v[136:137], v[136:137], v[128:129] op_sel:[1,0]
	v_lshlrev_b32_e32 v89, 16, v135
	v_mov_b32_e32 v65, v137
	v_pk_fma_f32 v[166:167], v[72:73], v[64:65], v[74:75] op_sel_hi:[0,1,0]
	v_mov_b32_e32 v137, v89
	v_pk_fma_f32 v[166:167], v[70:71], v[128:129], v[166:167] op_sel_hi:[0,1,1]
	s_waitcnt lgkmcnt(0)
	v_lshlrev_b32_e32 v168, 16, v130
	v_and_b32_e32 v169, 0xffff0000, v130
	v_pk_fma_f32 v[136:137], v[68:69], v[136:137], v[166:167] op_sel_hi:[0,1,1]
	v_pk_fma_f32 v[166:167], v[72:73], v[172:173], v[74:75] op_sel_hi:[0,1,0]
	v_pk_fma_f32 v[58:59], v[66:67], v[168:169], v[58:59] op_sel_hi:[0,1,1]
	v_pk_mov_b32 v[168:169], v[172:173], v[64:65] op_sel:[1,0]
	v_mov_b32_e32 v65, v128
	v_pk_fma_f32 v[166:167], v[70:71], v[168:169], v[166:167] op_sel_hi:[0,1,1]
	v_pk_fma_f32 v[64:65], v[68:69], v[64:65], v[166:167] op_sel_hi:[0,1,1]
	v_pk_mul_f32 v[58:59], v[64:65], v[58:59]
	v_lshlrev_b32_e32 v64, 16, v131
	v_and_b32_e32 v65, 0xffff0000, v131
	v_pk_fma_f32 v[60:61], v[66:67], v[64:65], v[60:61] op_sel_hi:[0,1,1]
	v_and_b32_e32 v129, 0xffff0000, v125
	v_pk_mul_f32 v[60:61], v[136:137], v[60:61]
	v_lshlrev_b32_e32 v64, 16, v125
	v_and_b32_e32 v128, 16, v125
	v_mov_b32_e32 v65, v129
	v_cvt_pk_bf16_f32 v58, v58, v59
	v_cvt_pk_bf16_f32 v59, v60, v61
	v_lshlrev_b32_e32 v175, 16, v124
	v_and_b32_e32 v60, 0xffff0000, v124
	v_pk_mov_b32 v[124:125], v[128:129], v[64:65] op_sel:[1,0]
	v_lshlrev_b32_e32 v89, 16, v165
	v_mov_b32_e32 v61, v125
	v_pk_fma_f32 v[128:129], v[72:73], v[60:61], v[74:75] op_sel_hi:[0,1,0]
	v_mov_b32_e32 v125, v89
	v_pk_fma_f32 v[128:129], v[70:71], v[64:65], v[128:129] op_sel_hi:[0,1,1]
	v_lshlrev_b32_e32 v130, 16, v132
	v_and_b32_e32 v131, 0xffff0000, v132
	v_pk_fma_f32 v[124:125], v[68:69], v[124:125], v[128:129] op_sel_hi:[0,1,1]
	v_pk_fma_f32 v[128:129], v[72:73], v[174:175], v[74:75] op_sel_hi:[0,1,0]
	v_pk_fma_f32 v[54:55], v[66:67], v[130:131], v[54:55] op_sel_hi:[0,1,1]
	v_pk_mov_b32 v[130:131], v[174:175], v[60:61] op_sel:[1,0]
	v_mov_b32_e32 v61, v64
	v_pk_fma_f32 v[128:129], v[70:71], v[130:131], v[128:129] op_sel_hi:[0,1,1]
	v_pk_fma_f32 v[60:61], v[68:69], v[60:61], v[128:129] op_sel_hi:[0,1,1]
	v_pk_mul_f32 v[54:55], v[60:61], v[54:55]
	v_lshlrev_b32_e32 v60, 16, v133
	v_and_b32_e32 v61, 0xffff0000, v133
	ds_read2_b64 v[128:131], v164 offset0:16 offset1:20
	v_and_b32_e32 v65, 0xffff0000, v121
	v_pk_fma_f32 v[56:57], v[66:67], v[60:61], v[56:57] op_sel_hi:[0,1,1]
	v_lshlrev_b32_e32 v60, 16, v121
	v_and_b32_e32 v64, 16, v121
	v_mov_b32_e32 v61, v65
	v_pk_mul_f32 v[56:57], v[124:125], v[56:57]
	v_pk_mov_b32 v[64:65], v[64:65], v[60:61] op_sel:[1,0]
	v_cvt_pk_bf16_f32 v54, v54, v55
	v_cvt_pk_bf16_f32 v55, v56, v57
	v_and_b32_e32 v56, 0xffff0000, v120
	v_mov_b32_e32 v57, v65
	v_lshlrev_b32_e32 v89, 16, v93
	v_lshlrev_b32_e32 v127, 16, v120
	v_pk_fma_f32 v[120:121], v[72:73], v[56:57], v[74:75] op_sel_hi:[0,1,0]
	v_mov_b32_e32 v65, v89
	v_pk_fma_f32 v[120:121], v[70:71], v[60:61], v[120:121] op_sel_hi:[0,1,1]
	s_waitcnt lgkmcnt(0)
	v_lshlrev_b32_e32 v124, 16, v128
	v_and_b32_e32 v125, 0xffff0000, v128
	v_cndmask_b32_e64 v98, v116, v112, s[12:13]
	v_pk_fma_f32 v[64:65], v[68:69], v[64:65], v[120:121] op_sel_hi:[0,1,1]
	v_pk_fma_f32 v[120:121], v[72:73], v[126:127], v[74:75] op_sel_hi:[0,1,0]
	v_pk_fma_f32 v[50:51], v[66:67], v[124:125], v[50:51] op_sel_hi:[0,1,1]
	v_pk_mov_b32 v[124:125], v[126:127], v[56:57] op_sel:[1,0]
	ds_bpermute_b32 v97, v163, v98
	v_pk_fma_f32 v[120:121], v[70:71], v[124:125], v[120:121] op_sel_hi:[0,1,1]
	v_mov_b32_e32 v57, v60
	v_pk_fma_f32 v[56:57], v[68:69], v[56:57], v[120:121] op_sel_hi:[0,1,1]
	v_pk_mul_f32 v[50:51], v[56:57], v[50:51]
	v_lshlrev_b32_e32 v56, 16, v129
	v_and_b32_e32 v57, 0xffff0000, v129
	v_and_b32_e32 v61, 0xffff0000, v117
	v_pk_fma_f32 v[52:53], v[66:67], v[56:57], v[52:53] op_sel_hi:[0,1,1]
	v_lshlrev_b32_e32 v56, 16, v117
	v_and_b32_e32 v60, 16, v117
	v_mov_b32_e32 v57, v61
	v_pk_mul_f32 v[52:53], v[64:65], v[52:53]
	v_pk_mov_b32 v[60:61], v[60:61], v[56:57] op_sel:[1,0]
	v_cvt_pk_bf16_f32 v50, v50, v51
	v_cvt_pk_bf16_f32 v51, v52, v53
	s_waitcnt lgkmcnt(0)
	v_lshlrev_b32_e32 v64, 16, v97
	v_and_b32_e32 v52, 0xffff0000, v116
	v_mov_b32_e32 v53, v61
	v_mov_b32_e32 v61, v64
	v_pk_fma_f32 v[64:65], v[72:73], v[52:53], v[74:75] op_sel_hi:[0,1,0]
	v_lshlrev_b32_e32 v123, 16, v116
	v_pk_fma_f32 v[64:65], v[70:71], v[56:57], v[64:65] op_sel_hi:[0,1,1]
	v_lshlrev_b32_e32 v116, 16, v130
	v_and_b32_e32 v117, 0xffff0000, v130
	v_pk_fma_f32 v[60:61], v[68:69], v[60:61], v[64:65] op_sel_hi:[0,1,1]
	v_pk_fma_f32 v[64:65], v[72:73], v[122:123], v[74:75] op_sel_hi:[0,1,0]
	v_pk_fma_f32 v[46:47], v[66:67], v[116:117], v[46:47] op_sel_hi:[0,1,1]
	v_pk_mov_b32 v[116:117], v[122:123], v[52:53] op_sel:[1,0]
	v_mov_b32_e32 v53, v56
	v_pk_fma_f32 v[64:65], v[70:71], v[116:117], v[64:65] op_sel_hi:[0,1,1]
	v_pk_fma_f32 v[52:53], v[68:69], v[52:53], v[64:65] op_sel_hi:[0,1,1]
	v_pk_mul_f32 v[46:47], v[52:53], v[46:47]
	v_lshlrev_b32_e32 v52, 16, v131
	v_and_b32_e32 v53, 0xffff0000, v131
	ds_read2_b64 v[120:123], v164 offset0:24 offset1:28
	v_and_b32_e32 v57, 0xffff0000, v113
	v_pk_fma_f32 v[48:49], v[66:67], v[52:53], v[48:49] op_sel_hi:[0,1,1]
	v_lshlrev_b32_e32 v52, 16, v113
	v_and_b32_e32 v56, 16, v113
	v_mov_b32_e32 v53, v57
	v_pk_mul_f32 v[48:49], v[60:61], v[48:49]
	v_pk_mov_b32 v[56:57], v[56:57], v[52:53] op_sel:[1,0]
	v_cvt_pk_bf16_f32 v46, v46, v47
	v_cvt_pk_bf16_f32 v47, v48, v49
	v_lshlrev_b32_e32 v60, 16, v99
	v_and_b32_e32 v48, 0xffff0000, v112
	v_mov_b32_e32 v49, v57
	v_mov_b32_e32 v57, v60
	v_pk_fma_f32 v[60:61], v[72:73], v[48:49], v[74:75] op_sel_hi:[0,1,0]
	v_lshlrev_b32_e32 v119, 16, v112
	v_pk_fma_f32 v[60:61], v[70:71], v[52:53], v[60:61] op_sel_hi:[0,1,1]
	s_waitcnt lgkmcnt(0)
	v_lshlrev_b32_e32 v64, 16, v120
	v_and_b32_e32 v65, 0xffff0000, v120
	v_cndmask_b32_e64 v106, v108, v104, s[12:13]
	v_pk_fma_f32 v[56:57], v[68:69], v[56:57], v[60:61] op_sel_hi:[0,1,1]
	v_pk_fma_f32 v[60:61], v[72:73], v[118:119], v[74:75] op_sel_hi:[0,1,0]
	v_pk_fma_f32 v[42:43], v[66:67], v[64:65], v[42:43] op_sel_hi:[0,1,1]
	v_pk_mov_b32 v[64:65], v[118:119], v[48:49] op_sel:[1,0]
	ds_bpermute_b32 v103, v163, v106
	v_pk_fma_f32 v[60:61], v[70:71], v[64:65], v[60:61] op_sel_hi:[0,1,1]
	v_mov_b32_e32 v49, v52
	v_cndmask_b32_e64 v107, v105, v109, s[10:11]
	v_pk_fma_f32 v[48:49], v[68:69], v[48:49], v[60:61] op_sel_hi:[0,1,1]
	ds_bpermute_b32 v98, v162, v107
	v_pk_mul_f32 v[42:43], v[48:49], v[42:43]
	v_lshlrev_b32_e32 v48, 16, v121
	v_and_b32_e32 v49, 0xffff0000, v121
	v_and_b32_e32 v53, 0xffff0000, v109
	v_pk_fma_f32 v[44:45], v[66:67], v[48:49], v[44:45] op_sel_hi:[0,1,1]
	v_lshlrev_b32_e32 v48, 16, v109
	v_and_b32_e32 v52, 16, v109
	v_mov_b32_e32 v49, v53
	v_pk_mul_f32 v[44:45], v[56:57], v[44:45]
	v_pk_mov_b32 v[52:53], v[52:53], v[48:49] op_sel:[1,0]
	v_cvt_pk_bf16_f32 v42, v42, v43
	v_cvt_pk_bf16_f32 v43, v44, v45
	s_waitcnt lgkmcnt(1)
	v_lshlrev_b32_e32 v56, 16, v103
	v_and_b32_e32 v44, 0xffff0000, v108
	v_mov_b32_e32 v45, v53
	v_cndmask_b32_e64 v110, v104, v100, s[12:13]
	v_mov_b32_e32 v53, v56
	v_pk_fma_f32 v[56:57], v[72:73], v[44:45], v[74:75] op_sel_hi:[0,1,0]
	ds_bpermute_b32 v107, v163, v110
	s_waitcnt lgkmcnt(1)
	v_and_b32_e32 v110, 0xffff0000, v98
	v_and_b32_e32 v98, 0xffff0000, v115
	v_lshlrev_b32_e32 v115, 16, v108
	v_pk_fma_f32 v[56:57], v[70:71], v[48:49], v[56:57] op_sel_hi:[0,1,1]
	v_lshlrev_b32_e32 v60, 16, v122
	v_and_b32_e32 v61, 0xffff0000, v122
	v_pk_fma_f32 v[52:53], v[68:69], v[52:53], v[56:57] op_sel_hi:[0,1,1]
	v_pk_fma_f32 v[56:57], v[72:73], v[114:115], v[74:75] op_sel_hi:[0,1,0]
	v_pk_fma_f32 v[38:39], v[66:67], v[60:61], v[38:39] op_sel_hi:[0,1,1]
	v_pk_mov_b32 v[60:61], v[114:115], v[44:45] op_sel:[1,0]
	v_mov_b32_e32 v45, v48
	v_pk_fma_f32 v[56:57], v[70:71], v[60:61], v[56:57] op_sel_hi:[0,1,1]
	v_pk_fma_f32 v[44:45], v[68:69], v[44:45], v[56:57] op_sel_hi:[0,1,1]
	v_pk_mul_f32 v[38:39], v[44:45], v[38:39]
	v_lshlrev_b32_e32 v44, 16, v123
	v_and_b32_e32 v45, 0xffff0000, v123
	ds_read2_b64 v[112:115], v164 offset0:32 offset1:36
	v_and_b32_e32 v49, 0xffff0000, v105
	v_pk_fma_f32 v[40:41], v[66:67], v[44:45], v[40:41] op_sel_hi:[0,1,1]
	v_lshlrev_b32_e32 v44, 16, v105
	v_and_b32_e32 v48, 16, v105
	v_mov_b32_e32 v45, v49
	v_pk_mul_f32 v[40:41], v[52:53], v[40:41]
	v_pk_mov_b32 v[48:49], v[48:49], v[44:45] op_sel:[1,0]
	v_cvt_pk_bf16_f32 v38, v38, v39
	v_cvt_pk_bf16_f32 v39, v40, v41
	s_waitcnt lgkmcnt(1)
	v_lshlrev_b32_e32 v52, 16, v107
	v_and_b32_e32 v40, 0xffff0000, v104
	v_mov_b32_e32 v41, v49
	v_mov_b32_e32 v49, v52
	v_pk_fma_f32 v[52:53], v[72:73], v[40:41], v[74:75] op_sel_hi:[0,1,0]
	v_and_b32_e32 v106, 0xffff0000, v102
	v_and_b32_e32 v102, 0xffff0000, v111
	v_lshlrev_b32_e32 v111, 16, v104
	v_pk_fma_f32 v[52:53], v[70:71], v[44:45], v[52:53] op_sel_hi:[0,1,1]
	s_waitcnt lgkmcnt(0)
	v_lshlrev_b32_e32 v56, 16, v112
	v_and_b32_e32 v57, 0xffff0000, v112
	v_pk_fma_f32 v[48:49], v[68:69], v[48:49], v[52:53] op_sel_hi:[0,1,1]
	v_pk_fma_f32 v[52:53], v[72:73], v[110:111], v[74:75] op_sel_hi:[0,1,0]
	v_pk_fma_f32 v[34:35], v[66:67], v[56:57], v[34:35] op_sel_hi:[0,1,1]
	v_pk_mov_b32 v[56:57], v[110:111], v[40:41] op_sel:[1,0]
	v_mov_b32_e32 v41, v44
	v_pk_fma_f32 v[52:53], v[70:71], v[56:57], v[52:53] op_sel_hi:[0,1,1]
	v_pk_fma_f32 v[40:41], v[68:69], v[40:41], v[52:53] op_sel_hi:[0,1,1]
	v_pk_mul_f32 v[34:35], v[40:41], v[34:35]
	v_lshlrev_b32_e32 v40, 16, v113
	v_and_b32_e32 v41, 0xffff0000, v113
	v_and_b32_e32 v45, 0xffff0000, v101
	v_pk_fma_f32 v[36:37], v[66:67], v[40:41], v[36:37] op_sel_hi:[0,1,1]
	v_lshlrev_b32_e32 v40, 16, v101
	v_and_b32_e32 v44, 16, v101
	v_mov_b32_e32 v41, v45
	v_pk_mul_f32 v[36:37], v[48:49], v[36:37]
	v_pk_mov_b32 v[44:45], v[44:45], v[40:41] op_sel:[1,0]
	v_cvt_pk_bf16_f32 v34, v34, v35
	v_cvt_pk_bf16_f32 v35, v36, v37
	v_lshlrev_b32_e32 v48, 16, v186
	v_and_b32_e32 v36, 0xffff0000, v100
	v_mov_b32_e32 v37, v45
	v_mov_b32_e32 v45, v48
	v_pk_fma_f32 v[48:49], v[72:73], v[36:37], v[74:75] op_sel_hi:[0,1,0]
	v_lshlrev_b32_e32 v107, 16, v100
	v_pk_fma_f32 v[48:49], v[70:71], v[40:41], v[48:49] op_sel_hi:[0,1,1]
	v_lshlrev_b32_e32 v52, 16, v114
	v_and_b32_e32 v53, 0xffff0000, v114
	v_pk_fma_f32 v[44:45], v[68:69], v[44:45], v[48:49] op_sel_hi:[0,1,1]
	v_pk_fma_f32 v[48:49], v[72:73], v[106:107], v[74:75] op_sel_hi:[0,1,0]
	v_pk_fma_f32 v[30:31], v[66:67], v[52:53], v[30:31] op_sel_hi:[0,1,1]
	v_pk_mov_b32 v[52:53], v[106:107], v[36:37] op_sel:[1,0]
	v_mov_b32_e32 v37, v40
	v_pk_fma_f32 v[48:49], v[70:71], v[52:53], v[48:49] op_sel_hi:[0,1,1]
	v_pk_fma_f32 v[36:37], v[68:69], v[36:37], v[48:49] op_sel_hi:[0,1,1]
	v_pk_mul_f32 v[30:31], v[36:37], v[30:31]
	v_lshlrev_b32_e32 v36, 16, v115
	v_and_b32_e32 v37, 0xffff0000, v115
	ds_read2_b64 v[104:107], v164 offset0:40 offset1:44
	v_and_b32_e32 v41, 0xffff0000, v95
	v_pk_fma_f32 v[32:33], v[66:67], v[36:37], v[32:33] op_sel_hi:[0,1,1]
	v_lshlrev_b32_e32 v36, 16, v95
	v_and_b32_e32 v40, 16, v95
	v_mov_b32_e32 v37, v41
	v_pk_mul_f32 v[32:33], v[44:45], v[32:33]
	v_pk_mov_b32 v[40:41], v[40:41], v[36:37] op_sel:[1,0]
	v_cvt_pk_bf16_f32 v30, v30, v31
	v_cvt_pk_bf16_f32 v31, v32, v33
	v_lshlrev_b32_e32 v44, 16, v83
	v_and_b32_e32 v32, 0xffff0000, v94
	v_mov_b32_e32 v33, v41
	v_mov_b32_e32 v41, v44
	v_pk_fma_f32 v[44:45], v[72:73], v[32:33], v[74:75] op_sel_hi:[0,1,0]
	v_lshlrev_b32_e32 v103, 16, v94
	v_pk_fma_f32 v[44:45], v[70:71], v[36:37], v[44:45] op_sel_hi:[0,1,1]
	s_waitcnt lgkmcnt(0)
	v_lshlrev_b32_e32 v48, 16, v104
	v_and_b32_e32 v49, 0xffff0000, v104
	v_pk_fma_f32 v[40:41], v[68:69], v[40:41], v[44:45] op_sel_hi:[0,1,1]
	v_pk_fma_f32 v[44:45], v[72:73], v[102:103], v[74:75] op_sel_hi:[0,1,0]
	v_pk_fma_f32 v[26:27], v[66:67], v[48:49], v[26:27] op_sel_hi:[0,1,1]
	v_pk_mov_b32 v[48:49], v[102:103], v[32:33] op_sel:[1,0]
	v_mov_b32_e32 v33, v36
	v_pk_fma_f32 v[44:45], v[70:71], v[48:49], v[44:45] op_sel_hi:[0,1,1]
	v_pk_fma_f32 v[32:33], v[68:69], v[32:33], v[44:45] op_sel_hi:[0,1,1]
	v_pk_mul_f32 v[26:27], v[32:33], v[26:27]
	v_lshlrev_b32_e32 v32, 16, v105
	v_and_b32_e32 v33, 0xffff0000, v105
	v_and_b32_e32 v37, 0xffff0000, v91
	v_pk_fma_f32 v[28:29], v[66:67], v[32:33], v[28:29] op_sel_hi:[0,1,1]
	v_lshlrev_b32_e32 v32, 16, v91
	v_and_b32_e32 v36, 16, v91
	v_mov_b32_e32 v33, v37
	v_pk_mul_f32 v[28:29], v[40:41], v[28:29]
	v_pk_mov_b32 v[36:37], v[36:37], v[32:33] op_sel:[1,0]
	v_cvt_pk_bf16_f32 v26, v26, v27
	v_cvt_pk_bf16_f32 v27, v28, v29
	v_lshlrev_b32_e32 v40, 16, v75
	v_and_b32_e32 v28, 0xffff0000, v90
	v_mov_b32_e32 v29, v37
	v_mov_b32_e32 v37, v40
	v_pk_fma_f32 v[40:41], v[72:73], v[28:29], v[74:75] op_sel_hi:[0,1,0]
	v_lshlrev_b32_e32 v99, 16, v90
	v_pk_fma_f32 v[40:41], v[70:71], v[32:33], v[40:41] op_sel_hi:[0,1,1]
	v_lshlrev_b32_e32 v44, 16, v106
	v_and_b32_e32 v45, 0xffff0000, v106
	v_pk_fma_f32 v[36:37], v[68:69], v[36:37], v[40:41] op_sel_hi:[0,1,1]
	v_pk_fma_f32 v[40:41], v[72:73], v[98:99], v[74:75] op_sel_hi:[0,1,0]
	v_pk_fma_f32 v[22:23], v[66:67], v[44:45], v[22:23] op_sel_hi:[0,1,1]
	v_pk_mov_b32 v[44:45], v[98:99], v[28:29] op_sel:[1,0]
	v_mov_b32_e32 v29, v32
	v_pk_fma_f32 v[40:41], v[70:71], v[44:45], v[40:41] op_sel_hi:[0,1,1]
	v_pk_fma_f32 v[28:29], v[68:69], v[28:29], v[40:41] op_sel_hi:[0,1,1]
	v_pk_mul_f32 v[22:23], v[28:29], v[22:23]
	v_and_b32_e32 v41, 0xffff0000, v87
	v_cvt_pk_bf16_f32 v28, v22, v23
	v_lshlrev_b32_e32 v22, 16, v107
	v_and_b32_e32 v23, 0xffff0000, v107
	v_pk_fma_f32 v[22:23], v[66:67], v[22:23], v[24:25] op_sel_hi:[0,1,1]
	v_pk_mul_f32 v[22:23], v[36:37], v[22:23]
	v_lshlrev_b32_e32 v36, 16, v87
	v_cvt_pk_bf16_f32 v29, v22, v23
	ds_read2_b64 v[22:25], v164 offset0:48 offset1:52
	v_and_b32_e32 v40, 16, v87
	v_mov_b32_e32 v37, v41
	v_pk_mov_b32 v[40:41], v[40:41], v[36:37] op_sel:[1,0]
	v_lshlrev_b32_e32 v44, 16, v73
	v_and_b32_e32 v32, 0xffff0000, v86
	v_mov_b32_e32 v33, v41
	v_mov_b32_e32 v41, v44
	v_pk_fma_f32 v[44:45], v[72:73], v[32:33], v[74:75] op_sel_hi:[0,1,0]
	v_lshlrev_b32_e32 v97, 16, v86
	v_pk_fma_f32 v[44:45], v[70:71], v[36:37], v[44:45] op_sel_hi:[0,1,1]
	s_waitcnt lgkmcnt(0)
	v_lshlrev_b32_e32 v48, 16, v22
	v_and_b32_e32 v49, 0xffff0000, v22
	v_pk_fma_f32 v[40:41], v[68:69], v[40:41], v[44:45] op_sel_hi:[0,1,1]
	v_pk_fma_f32 v[44:45], v[72:73], v[96:97], v[74:75] op_sel_hi:[0,1,0]
	v_pk_fma_f32 v[18:19], v[66:67], v[48:49], v[18:19] op_sel_hi:[0,1,1]
	v_pk_mov_b32 v[48:49], v[96:97], v[32:33] op_sel:[1,0]
	v_mov_b32_e32 v33, v36
	v_pk_fma_f32 v[44:45], v[70:71], v[48:49], v[44:45] op_sel_hi:[0,1,1]
	v_pk_fma_f32 v[32:33], v[68:69], v[32:33], v[44:45] op_sel_hi:[0,1,1]
	v_pk_mul_f32 v[18:19], v[32:33], v[18:19]
	v_lshlrev_b32_e32 v22, 16, v23
	v_and_b32_e32 v23, 0xffff0000, v23
	v_and_b32_e32 v33, 0xffff0000, v81
	v_pk_fma_f32 v[20:21], v[66:67], v[22:23], v[20:21] op_sel_hi:[0,1,1]
	v_lshlrev_b32_e32 v22, 16, v81
	v_and_b32_e32 v32, 16, v81
	v_mov_b32_e32 v23, v33
	v_pk_mul_f32 v[20:21], v[40:41], v[20:21]
	v_pk_mov_b32 v[32:33], v[32:33], v[22:23] op_sel:[1,0]
	v_cvt_pk_bf16_f32 v18, v18, v19
	v_cvt_pk_bf16_f32 v19, v20, v21
	v_lshlrev_b32_e32 v36, 16, v71
	v_and_b32_e32 v20, 0xffff0000, v80
	v_mov_b32_e32 v21, v33
	v_mov_b32_e32 v33, v36
	v_pk_fma_f32 v[36:37], v[72:73], v[20:21], v[74:75] op_sel_hi:[0,1,0]
	v_lshlrev_b32_e32 v93, 16, v80
	v_pk_fma_f32 v[36:37], v[70:71], v[22:23], v[36:37] op_sel_hi:[0,1,1]
	v_lshlrev_b32_e32 v40, 16, v24
	v_and_b32_e32 v41, 0xffff0000, v24
	v_pk_fma_f32 v[32:33], v[68:69], v[32:33], v[36:37] op_sel_hi:[0,1,1]
	v_pk_fma_f32 v[36:37], v[72:73], v[92:93], v[74:75] op_sel_hi:[0,1,0]
	v_pk_fma_f32 v[14:15], v[66:67], v[40:41], v[14:15] op_sel_hi:[0,1,1]
	v_pk_mov_b32 v[40:41], v[92:93], v[20:21] op_sel:[1,0]
	v_mov_b32_e32 v21, v22
	v_pk_fma_f32 v[36:37], v[70:71], v[40:41], v[36:37] op_sel_hi:[0,1,1]
	v_pk_fma_f32 v[20:21], v[68:69], v[20:21], v[36:37] op_sel_hi:[0,1,1]
	v_pk_mul_f32 v[14:15], v[20:21], v[14:15]
	v_lshlrev_b32_e32 v24, 16, v79
	v_cvt_pk_bf16_f32 v20, v14, v15
	v_lshlrev_b32_e32 v14, 16, v25
	v_and_b32_e32 v15, 0xffff0000, v25
	v_pk_fma_f32 v[14:15], v[66:67], v[14:15], v[16:17] op_sel_hi:[0,1,1]
	v_pk_mul_f32 v[14:15], v[32:33], v[14:15]
	v_and_b32_e32 v33, 0xffff0000, v79
	v_cvt_pk_bf16_f32 v21, v14, v15
	ds_read2_b64 v[14:17], v164 offset0:56 offset1:60
	v_and_b32_e32 v32, 16, v79
	v_mov_b32_e32 v25, v33
	v_pk_mov_b32 v[32:33], v[32:33], v[24:25] op_sel:[1,0]
	v_lshlrev_b32_e32 v36, 16, v69
	v_and_b32_e32 v22, 0xffff0000, v78
	v_mov_b32_e32 v23, v33
	v_mov_b32_e32 v33, v36
	v_pk_fma_f32 v[36:37], v[72:73], v[22:23], v[74:75] op_sel_hi:[0,1,0]
	v_lshlrev_b32_e32 v89, 16, v78
	v_pk_fma_f32 v[36:37], v[70:71], v[24:25], v[36:37] op_sel_hi:[0,1,1]
	s_waitcnt lgkmcnt(0)
	v_lshlrev_b32_e32 v40, 16, v14
	v_and_b32_e32 v41, 0xffff0000, v14
	v_pk_fma_f32 v[32:33], v[68:69], v[32:33], v[36:37] op_sel_hi:[0,1,1]
	v_pk_fma_f32 v[36:37], v[72:73], v[88:89], v[74:75] op_sel_hi:[0,1,0]
	v_pk_fma_f32 v[10:11], v[66:67], v[40:41], v[10:11] op_sel_hi:[0,1,1]
	v_pk_mov_b32 v[40:41], v[88:89], v[22:23] op_sel:[1,0]
	v_mov_b32_e32 v23, v24
	v_pk_fma_f32 v[36:37], v[70:71], v[40:41], v[36:37] op_sel_hi:[0,1,1]
	v_pk_fma_f32 v[22:23], v[68:69], v[22:23], v[36:37] op_sel_hi:[0,1,1]
	v_pk_mul_f32 v[10:11], v[22:23], v[10:11]
	v_lshlrev_b32_e32 v14, 16, v15
	v_and_b32_e32 v15, 0xffff0000, v15
	v_and_b32_e32 v23, 0xffff0000, v77
	v_pk_fma_f32 v[12:13], v[66:67], v[14:15], v[12:13] op_sel_hi:[0,1,1]
	v_lshlrev_b32_e32 v14, 16, v77
	v_and_b32_e32 v22, 16, v77
	v_mov_b32_e32 v15, v23
	v_pk_mul_f32 v[12:13], v[32:33], v[12:13]
	v_pk_mov_b32 v[22:23], v[22:23], v[14:15] op_sel:[1,0]
	v_cvt_pk_bf16_f32 v10, v10, v11
	v_cvt_pk_bf16_f32 v11, v12, v13
	v_lshlrev_b32_e32 v24, 16, v67
	v_and_b32_e32 v12, 0xffff0000, v76
	v_mov_b32_e32 v13, v23
	v_mov_b32_e32 v23, v24
	v_pk_fma_f32 v[24:25], v[72:73], v[12:13], v[74:75] op_sel_hi:[0,1,0]
	v_and_b32_e32 v82, 0xffff0000, v82
	v_lshlrev_b32_e32 v83, 16, v76
	v_pk_fma_f32 v[24:25], v[70:71], v[14:15], v[24:25] op_sel_hi:[0,1,1]
	v_lshlrev_b32_e32 v32, 16, v16
	v_and_b32_e32 v33, 0xffff0000, v16
	v_pk_fma_f32 v[22:23], v[68:69], v[22:23], v[24:25] op_sel_hi:[0,1,1]
	v_pk_fma_f32 v[24:25], v[72:73], v[82:83], v[74:75] op_sel_hi:[0,1,0]
	v_pk_fma_f32 v[6:7], v[66:67], v[32:33], v[6:7] op_sel_hi:[0,1,1]
	v_pk_mov_b32 v[32:33], v[82:83], v[12:13] op_sel:[1,0]
	v_mov_b32_e32 v13, v14
	v_pk_fma_f32 v[24:25], v[70:71], v[32:33], v[24:25] op_sel_hi:[0,1,1]
	v_pk_fma_f32 v[12:13], v[68:69], v[12:13], v[24:25] op_sel_hi:[0,1,1]
	v_pk_mul_f32 v[6:7], v[12:13], v[6:7]
	v_lshlrev_b32_e32 v12, 16, v17
	v_and_b32_e32 v13, 0xffff0000, v17
	v_pk_fma_f32 v[8:9], v[66:67], v[12:13], v[8:9] op_sel_hi:[0,1,1]
	v_pk_mul_f32 v[8:9], v[22:23], v[8:9]
	v_cvt_pk_bf16_f32 v6, v6, v7
	v_cvt_pk_bf16_f32 v7, v8, v9
	s_barrier
	ds_write2_b64 v164, v[84:85], v[62:63] offset1:4
	ds_write2_b64 v164, v[58:59], v[54:55] offset0:8 offset1:12
	ds_write2_b64 v164, v[50:51], v[46:47] offset0:16 offset1:20
	ds_write2_b64 v164, v[42:43], v[38:39] offset0:24 offset1:28
	ds_write2_b64 v164, v[34:35], v[30:31] offset0:32 offset1:36
	ds_write2_b64 v164, v[26:27], v[28:29] offset0:40 offset1:44
	ds_write2_b64 v164, v[18:19], v[20:21] offset0:48 offset1:52
	ds_write2_b64 v164, v[10:11], v[6:7] offset0:56 offset1:60
	ds_write_b128 v160, v[2:5]
	v_mov_b32_e32 v6, 0
	v_mov_b32_e32 v7, 0
	v_mov_b32_e32 v8, 0
	v_mov_b32_e32 v9, 0
	s_waitcnt lgkmcnt(0)
	s_barrier
	s_and_saveexec_b64 s[50:51], s[4:5]
	ds_read_b128 v[6:9], v160 offset:16
	s_or_b64 exec, exec, s[50:51]
	v_perm_b32 v11, v3, v4, s65
	v_perm_b32 v12, v4, v5, s65
	s_waitcnt lgkmcnt(0)
	v_perm_b32 v13, v5, v6, s65
	v_perm_b32 v10, v2, v3, s65
	v_pk_mov_b32 v[14:15], v[2:3], v[4:5] op_sel:[1,0]
	v_pk_mov_b32 v[16:17], v[4:5], v[6:7] op_sel:[1,0]
	v_perm_b32 v21, v6, v7, s65
	v_mov_b32_e32 v18, v11
	v_mov_b32_e32 v19, v12
	v_mov_b32_e32 v20, v13
	ds_write_b128 v160, v[10:13] offset:8224
	ds_write_b128 v160, v[14:17] offset:16448
	ds_write_b128 v160, v[18:21] offset:24672
	ds_write_b128 v160, v[4:7] offset:32896
	v_perm_b32 v5, v7, v8, s65
	v_mov_b32_e32 v2, v12
	v_mov_b32_e32 v3, v13
	v_mov_b32_e32 v4, v21
	v_pk_mov_b32 v[18:19], v[6:7], v[8:9] op_sel:[1,0]
	v_perm_b32 v9, v8, v9, s65
	v_mov_b32_e32 v6, v13
	v_mov_b32_e32 v7, v21
	v_mov_b32_e32 v8, v5
	ds_write_b128 v160, v[2:5] offset:41120
	ds_write_b128 v160, v[16:19] offset:49344
	ds_write_b128 v160, v[6:9] offset:57568
	s_waitcnt lgkmcnt(0)
	s_barrier
	ds_read_b128 v[64:67], v161 offset:4096
	ds_read_b128 v[60:63], v161 offset:4064
	ds_read_b128 v[72:75], v161 offset:4032
	ds_read_b128 v[68:71], v161 offset:4000
	ds_read_b128 v[80:83], v161 offset:3968
	ds_read_b128 v[76:79], v161 offset:3936
	ds_read_b128 v[88:91], v161 offset:3904
	ds_read_b128 v[84:87], v161 offset:3872
	ds_read_b128 v[96:99], v161 offset:3840
	ds_read_b128 v[92:95], v161 offset:3808
	ds_read_b128 v[104:107], v161 offset:3776
	ds_read_b128 v[100:103], v161 offset:3744
	ds_read_b128 v[112:115], v161 offset:3712
	ds_read_b128 v[108:111], v161 offset:3680
	ds_read_b128 v[116:119], v161 offset:3616
	ds_read_b128 v[120:123], v161 offset:3648
	ds_read_b128 v[128:131], v1
	s_mov_b32 s2, 0
	v_mov_b32_e32 v1, v0
	v_mov_b32_e32 v2, v0
	v_mov_b32_e32 v3, v0
	v_mov_b32_e32 v4, v0
	v_mov_b32_e32 v5, v0
	v_mov_b32_e32 v6, v0
	v_mov_b32_e32 v7, v0
	v_mov_b32_e32 v8, v0
	v_mov_b32_e32 v9, v0
	v_mov_b32_e32 v10, v0
	v_mov_b32_e32 v11, v0
	v_mov_b32_e32 v12, v0
	v_mov_b32_e32 v13, v0
	v_mov_b32_e32 v14, v0
	v_mov_b32_e32 v15, v0
	v_mov_b32_e32 v16, v0
	v_mov_b32_e32 v17, v0
	v_mov_b32_e32 v18, v0
	v_mov_b32_e32 v19, v0
	v_mov_b32_e32 v20, v0
	v_mov_b32_e32 v21, v0
	v_mov_b32_e32 v22, v0
	v_mov_b32_e32 v23, v0
	v_mov_b32_e32 v24, v0
	v_mov_b32_e32 v25, v0
	v_mov_b32_e32 v26, v0
	v_mov_b32_e32 v27, v0
	v_mov_b32_e32 v28, v0
	v_mov_b32_e32 v29, v0
	v_mov_b32_e32 v30, v0
	v_mov_b32_e32 v31, v0
	v_mov_b32_e32 v32, v0
	v_mov_b32_e32 v33, v0
	v_mov_b32_e32 v34, v0
	v_mov_b32_e32 v35, v0
	v_mov_b32_e32 v36, v0
	v_mov_b32_e32 v37, v0
	v_mov_b32_e32 v38, v0
	v_mov_b32_e32 v39, v0
	v_mov_b32_e32 v40, v0
	v_mov_b32_e32 v41, v0
	v_mov_b32_e32 v42, v0
	v_mov_b32_e32 v43, v0
	v_mov_b32_e32 v44, v0
	v_mov_b32_e32 v45, v0
	v_mov_b32_e32 v46, v0
	v_mov_b32_e32 v47, v0
	v_mov_b32_e32 v48, v0
	v_mov_b32_e32 v49, v0
	v_mov_b32_e32 v50, v0
	v_mov_b32_e32 v51, v0
	v_mov_b32_e32 v52, v0
	v_mov_b32_e32 v53, v0
	v_mov_b32_e32 v54, v0
	v_mov_b32_e32 v55, v0
	v_mov_b32_e32 v56, v0
	v_mov_b32_e32 v57, v0
	v_mov_b32_e32 v58, v0
	v_mov_b32_e32 v59, v0
	v_mov_b32_e32 v124, v0
	v_mov_b32_e32 v125, v0
	v_mov_b32_e32 v126, v0
	v_mov_b32_e32 v127, v0
.LBB0_490:
	v_add_u32_e32 v132, s2, v154
	v_add_u32_e32 v133, s2, v155
	s_waitcnt lgkmcnt(0)
	v_mfma_f32_16x16x32_bf16 v[4:7], v[120:123], v[128:131], v[4:7]
	v_add_u32_e32 v135, 0x10140, v133
	v_mfma_f32_16x16x32_bf16 v[0:3], v[116:119], v[128:131], v[0:3]
	ds_read_b128 v[116:119], v132
	ds_read_b128 v[120:123], v132 offset:32
	ds_read_b128 v[166:169], v135
	v_mfma_f32_16x16x32_bf16 v[124:127], v[64:67], v[128:131], v[124:127]
	v_mfma_f32_16x16x32_bf16 v[56:59], v[60:63], v[128:131], v[56:59]
	v_mfma_f32_16x16x32_bf16 v[52:55], v[72:75], v[128:131], v[52:55]
	v_mfma_f32_16x16x32_bf16 v[48:51], v[68:71], v[128:131], v[48:51]
	v_mfma_f32_16x16x32_bf16 v[44:47], v[80:83], v[128:131], v[44:47]
	v_mfma_f32_16x16x32_bf16 v[40:43], v[76:79], v[128:131], v[40:43]
	v_mfma_f32_16x16x32_bf16 v[36:39], v[88:91], v[128:131], v[36:39]
	v_mfma_f32_16x16x32_bf16 v[32:35], v[84:87], v[128:131], v[32:35]
	v_mfma_f32_16x16x32_bf16 v[28:31], v[96:99], v[128:131], v[28:31]
	v_mfma_f32_16x16x32_bf16 v[24:27], v[92:95], v[128:131], v[24:27]
	v_mfma_f32_16x16x32_bf16 v[20:23], v[104:107], v[128:131], v[20:23]
	v_mfma_f32_16x16x32_bf16 v[16:19], v[100:103], v[128:131], v[16:19]
	v_mfma_f32_16x16x32_bf16 v[12:15], v[112:115], v[128:131], v[12:15]
	v_mfma_f32_16x16x32_bf16 v[8:11], v[108:111], v[128:131], v[8:11]
	v_add_u32_e32 v128, 0x10180, v133
	s_waitcnt lgkmcnt(0)
	v_mfma_f32_16x16x32_bf16 v[4:7], v[112:115], v[166:169], v[4:7]
	v_mfma_f32_16x16x32_bf16 v[0:3], v[108:111], v[166:169], v[0:3]
	ds_read_b128 v[108:111], v132 offset:64
	ds_read_b128 v[112:115], v132 offset:96
	ds_read_b128 v[128:131], v128
	v_mfma_f32_16x16x32_bf16 v[124:127], v[120:123], v[166:169], v[124:127]
	v_mfma_f32_16x16x32_bf16 v[56:59], v[116:119], v[166:169], v[56:59]
	v_mfma_f32_16x16x32_bf16 v[52:55], v[64:67], v[166:169], v[52:55]
	v_mfma_f32_16x16x32_bf16 v[48:51], v[60:63], v[166:169], v[48:51]
	v_mfma_f32_16x16x32_bf16 v[44:47], v[72:75], v[166:169], v[44:47]
	v_mfma_f32_16x16x32_bf16 v[40:43], v[68:71], v[166:169], v[40:43]
	v_mfma_f32_16x16x32_bf16 v[36:39], v[80:83], v[166:169], v[36:39]
	v_mfma_f32_16x16x32_bf16 v[32:35], v[76:79], v[166:169], v[32:35]
	v_mfma_f32_16x16x32_bf16 v[28:31], v[88:91], v[166:169], v[28:31]
	v_mfma_f32_16x16x32_bf16 v[24:27], v[84:87], v[166:169], v[24:27]
	v_mfma_f32_16x16x32_bf16 v[20:23], v[96:99], v[166:169], v[20:23]
	v_mfma_f32_16x16x32_bf16 v[16:19], v[92:95], v[166:169], v[16:19]
	v_mfma_f32_16x16x32_bf16 v[12:15], v[104:107], v[166:169], v[12:15]
	v_mfma_f32_16x16x32_bf16 v[8:11], v[100:103], v[166:169], v[8:11]
	s_waitcnt lgkmcnt(0)
	v_mfma_f32_16x16x32_bf16 v[4:7], v[104:107], v[128:131], v[4:7]
	v_add_u32_e32 v135, 0x101c0, v133
	v_mfma_f32_16x16x32_bf16 v[0:3], v[100:103], v[128:131], v[0:3]
	ds_read_b128 v[100:103], v132 offset:128
	ds_read_b128 v[104:107], v132 offset:160
	ds_read_b128 v[166:169], v135
	v_mfma_f32_16x16x32_bf16 v[124:127], v[112:115], v[128:131], v[124:127]
	v_mfma_f32_16x16x32_bf16 v[56:59], v[108:111], v[128:131], v[56:59]
	v_mfma_f32_16x16x32_bf16 v[52:55], v[120:123], v[128:131], v[52:55]
	v_mfma_f32_16x16x32_bf16 v[48:51], v[116:119], v[128:131], v[48:51]
	v_mfma_f32_16x16x32_bf16 v[44:47], v[64:67], v[128:131], v[44:47]
	v_mfma_f32_16x16x32_bf16 v[40:43], v[60:63], v[128:131], v[40:43]
	v_mfma_f32_16x16x32_bf16 v[36:39], v[72:75], v[128:131], v[36:39]
	v_mfma_f32_16x16x32_bf16 v[32:35], v[68:71], v[128:131], v[32:35]
	v_mfma_f32_16x16x32_bf16 v[28:31], v[80:83], v[128:131], v[28:31]
	v_mfma_f32_16x16x32_bf16 v[24:27], v[76:79], v[128:131], v[24:27]
	v_mfma_f32_16x16x32_bf16 v[20:23], v[88:91], v[128:131], v[20:23]
	v_mfma_f32_16x16x32_bf16 v[16:19], v[84:87], v[128:131], v[16:19]
	v_mfma_f32_16x16x32_bf16 v[12:15], v[96:99], v[128:131], v[12:15]
	v_mfma_f32_16x16x32_bf16 v[8:11], v[92:95], v[128:131], v[8:11]
	v_add_u32_e32 v128, 0x10200, v133
	s_waitcnt lgkmcnt(0)
	v_mfma_f32_16x16x32_bf16 v[4:7], v[96:99], v[166:169], v[4:7]
	v_mfma_f32_16x16x32_bf16 v[0:3], v[92:95], v[166:169], v[0:3]
	ds_read_b128 v[92:95], v132 offset:192
	ds_read_b128 v[96:99], v132 offset:224
	ds_read_b128 v[128:131], v128
	v_mfma_f32_16x16x32_bf16 v[124:127], v[104:107], v[166:169], v[124:127]
	v_mfma_f32_16x16x32_bf16 v[56:59], v[100:103], v[166:169], v[56:59]
	v_mfma_f32_16x16x32_bf16 v[52:55], v[112:115], v[166:169], v[52:55]
	v_mfma_f32_16x16x32_bf16 v[48:51], v[108:111], v[166:169], v[48:51]
	v_mfma_f32_16x16x32_bf16 v[44:47], v[120:123], v[166:169], v[44:47]
	v_mfma_f32_16x16x32_bf16 v[40:43], v[116:119], v[166:169], v[40:43]
	v_mfma_f32_16x16x32_bf16 v[36:39], v[64:67], v[166:169], v[36:39]
	v_mfma_f32_16x16x32_bf16 v[32:35], v[60:63], v[166:169], v[32:35]
	v_mfma_f32_16x16x32_bf16 v[28:31], v[72:75], v[166:169], v[28:31]
	v_mfma_f32_16x16x32_bf16 v[24:27], v[68:71], v[166:169], v[24:27]
	v_mfma_f32_16x16x32_bf16 v[20:23], v[80:83], v[166:169], v[20:23]
	v_mfma_f32_16x16x32_bf16 v[16:19], v[76:79], v[166:169], v[16:19]
	v_mfma_f32_16x16x32_bf16 v[12:15], v[88:91], v[166:169], v[12:15]
	v_mfma_f32_16x16x32_bf16 v[8:11], v[84:87], v[166:169], v[8:11]
	s_waitcnt lgkmcnt(0)
	v_mfma_f32_16x16x32_bf16 v[4:7], v[88:91], v[128:131], v[4:7]
	v_add_u32_e32 v135, 0x10240, v133
	v_mfma_f32_16x16x32_bf16 v[0:3], v[84:87], v[128:131], v[0:3]
	ds_read_b128 v[84:87], v132 offset:256
	ds_read_b128 v[88:91], v132 offset:288
	ds_read_b128 v[166:169], v135
	v_mfma_f32_16x16x32_bf16 v[124:127], v[96:99], v[128:131], v[124:127]
	v_mfma_f32_16x16x32_bf16 v[56:59], v[92:95], v[128:131], v[56:59]
	v_mfma_f32_16x16x32_bf16 v[52:55], v[104:107], v[128:131], v[52:55]
	v_mfma_f32_16x16x32_bf16 v[48:51], v[100:103], v[128:131], v[48:51]
	v_mfma_f32_16x16x32_bf16 v[44:47], v[112:115], v[128:131], v[44:47]
	v_mfma_f32_16x16x32_bf16 v[40:43], v[108:111], v[128:131], v[40:43]
	v_mfma_f32_16x16x32_bf16 v[36:39], v[120:123], v[128:131], v[36:39]
	v_mfma_f32_16x16x32_bf16 v[32:35], v[116:119], v[128:131], v[32:35]
	v_mfma_f32_16x16x32_bf16 v[28:31], v[64:67], v[128:131], v[28:31]
	v_mfma_f32_16x16x32_bf16 v[24:27], v[60:63], v[128:131], v[24:27]
	v_mfma_f32_16x16x32_bf16 v[20:23], v[72:75], v[128:131], v[20:23]
	v_mfma_f32_16x16x32_bf16 v[16:19], v[68:71], v[128:131], v[16:19]
	v_mfma_f32_16x16x32_bf16 v[12:15], v[80:83], v[128:131], v[12:15]
	v_mfma_f32_16x16x32_bf16 v[8:11], v[76:79], v[128:131], v[8:11]
	v_add_u32_e32 v128, 0x10280, v133
	s_waitcnt lgkmcnt(0)
	v_mfma_f32_16x16x32_bf16 v[4:7], v[80:83], v[166:169], v[4:7]
	v_mfma_f32_16x16x32_bf16 v[0:3], v[76:79], v[166:169], v[0:3]
	ds_read_b128 v[76:79], v132 offset:320
	ds_read_b128 v[80:83], v132 offset:352
	ds_read_b128 v[128:131], v128
	v_mfma_f32_16x16x32_bf16 v[124:127], v[88:91], v[166:169], v[124:127]
	v_mfma_f32_16x16x32_bf16 v[56:59], v[84:87], v[166:169], v[56:59]
	v_mfma_f32_16x16x32_bf16 v[52:55], v[96:99], v[166:169], v[52:55]
	v_mfma_f32_16x16x32_bf16 v[48:51], v[92:95], v[166:169], v[48:51]
	v_mfma_f32_16x16x32_bf16 v[44:47], v[104:107], v[166:169], v[44:47]
	v_mfma_f32_16x16x32_bf16 v[40:43], v[100:103], v[166:169], v[40:43]
	v_mfma_f32_16x16x32_bf16 v[36:39], v[112:115], v[166:169], v[36:39]
	v_mfma_f32_16x16x32_bf16 v[32:35], v[108:111], v[166:169], v[32:35]
	v_mfma_f32_16x16x32_bf16 v[28:31], v[120:123], v[166:169], v[28:31]
	v_mfma_f32_16x16x32_bf16 v[24:27], v[116:119], v[166:169], v[24:27]
	v_mfma_f32_16x16x32_bf16 v[20:23], v[64:67], v[166:169], v[20:23]
	v_mfma_f32_16x16x32_bf16 v[16:19], v[60:63], v[166:169], v[16:19]
	v_mfma_f32_16x16x32_bf16 v[12:15], v[72:75], v[166:169], v[12:15]
	v_mfma_f32_16x16x32_bf16 v[8:11], v[68:71], v[166:169], v[8:11]
	s_waitcnt lgkmcnt(0)
	v_mfma_f32_16x16x32_bf16 v[4:7], v[72:75], v[128:131], v[4:7]
	v_add_u32_e32 v135, 0x102c0, v133
	v_mfma_f32_16x16x32_bf16 v[0:3], v[68:71], v[128:131], v[0:3]
	ds_read_b128 v[68:71], v132 offset:384
	ds_read_b128 v[72:75], v132 offset:416
	ds_read_b128 v[166:169], v135
	v_mfma_f32_16x16x32_bf16 v[124:127], v[80:83], v[128:131], v[124:127]
	v_mfma_f32_16x16x32_bf16 v[56:59], v[76:79], v[128:131], v[56:59]
	v_mfma_f32_16x16x32_bf16 v[52:55], v[88:91], v[128:131], v[52:55]
	v_mfma_f32_16x16x32_bf16 v[48:51], v[84:87], v[128:131], v[48:51]
	v_mfma_f32_16x16x32_bf16 v[44:47], v[96:99], v[128:131], v[44:47]
	v_mfma_f32_16x16x32_bf16 v[40:43], v[92:95], v[128:131], v[40:43]
	v_mfma_f32_16x16x32_bf16 v[36:39], v[104:107], v[128:131], v[36:39]
	v_mfma_f32_16x16x32_bf16 v[32:35], v[100:103], v[128:131], v[32:35]
	v_mfma_f32_16x16x32_bf16 v[28:31], v[112:115], v[128:131], v[28:31]
	v_mfma_f32_16x16x32_bf16 v[24:27], v[108:111], v[128:131], v[24:27]
	v_mfma_f32_16x16x32_bf16 v[20:23], v[120:123], v[128:131], v[20:23]
	v_mfma_f32_16x16x32_bf16 v[16:19], v[116:119], v[128:131], v[16:19]
	v_mfma_f32_16x16x32_bf16 v[12:15], v[64:67], v[128:131], v[12:15]
	v_mfma_f32_16x16x32_bf16 v[8:11], v[60:63], v[128:131], v[8:11]
	v_add_u32_e32 v128, 0x10300, v133
	s_waitcnt lgkmcnt(0)
	v_mfma_f32_16x16x32_bf16 v[4:7], v[64:67], v[166:169], v[4:7]
	v_mfma_f32_16x16x32_bf16 v[0:3], v[60:63], v[166:169], v[0:3]
	ds_read_b128 v[60:63], v132 offset:448
	ds_read_b128 v[64:67], v132 offset:480
	ds_read_b128 v[128:131], v128
	v_mfma_f32_16x16x32_bf16 v[124:127], v[72:75], v[166:169], v[124:127]
	v_mfma_f32_16x16x32_bf16 v[56:59], v[68:71], v[166:169], v[56:59]
	v_mfma_f32_16x16x32_bf16 v[52:55], v[80:83], v[166:169], v[52:55]
	v_mfma_f32_16x16x32_bf16 v[48:51], v[76:79], v[166:169], v[48:51]
	v_mfma_f32_16x16x32_bf16 v[44:47], v[88:91], v[166:169], v[44:47]
	v_mfma_f32_16x16x32_bf16 v[40:43], v[84:87], v[166:169], v[40:43]
	v_mfma_f32_16x16x32_bf16 v[36:39], v[96:99], v[166:169], v[36:39]
	v_mfma_f32_16x16x32_bf16 v[32:35], v[92:95], v[166:169], v[32:35]
	v_mfma_f32_16x16x32_bf16 v[28:31], v[104:107], v[166:169], v[28:31]
	v_mfma_f32_16x16x32_bf16 v[24:27], v[100:103], v[166:169], v[24:27]
	v_mfma_f32_16x16x32_bf16 v[20:23], v[112:115], v[166:169], v[20:23]
	v_mfma_f32_16x16x32_bf16 v[16:19], v[108:111], v[166:169], v[16:19]
	v_mfma_f32_16x16x32_bf16 v[12:15], v[120:123], v[166:169], v[12:15]
	v_mfma_f32_16x16x32_bf16 v[8:11], v[116:119], v[166:169], v[8:11]
	s_addk_i32 s2, 0x200
	s_cmpk_lg_i32 s2, 0x1000
	s_cbranch_scc1 .LBB0_490
	s_waitcnt lgkmcnt(2)
	v_lshl_add_u64 v[60:61], v[144:145], 0, s[42:43]
	v_lshl_add_u64 v[76:77], v[60:61], 0, s[38:39]
	s_waitcnt lgkmcnt(1)
	global_load_dword v64, v158, s[44:45] offset:2048
	global_load_dword v62, v159, s[44:45]
	global_load_dword v66, v156, s[44:45]
	global_load_dword v68, v156, s[48:49]
	v_lshl_add_u64 v[60:61], v[148:149], 0, s[42:43]
	global_load_dwordx2 v[122:123], v[76:77], off
	s_waitcnt lgkmcnt(0)
	global_load_dwordx2 v[128:129], v[76:77], off offset:32
	global_load_dwordx2 v[120:121], v[76:77], off offset:64
	global_load_dwordx2 v[116:117], v[76:77], off offset:96
	global_load_dwordx2 v[112:113], v[76:77], off offset:128
	global_load_dwordx2 v[108:109], v[76:77], off offset:160
	global_load_dwordx2 v[104:105], v[76:77], off offset:192
	global_load_dwordx2 v[100:101], v[76:77], off offset:224
	global_load_dwordx2 v[96:97], v[76:77], off offset:256
	global_load_dwordx2 v[92:93], v[76:77], off offset:288
	global_load_dwordx2 v[86:87], v[76:77], off offset:320
	global_load_dwordx2 v[82:83], v[76:77], off offset:352
	global_load_dwordx2 v[78:79], v[76:77], off offset:384
	v_lshl_add_u64 v[70:71], v[146:147], 1, v[76:77]
	global_load_ushort v63, v[70:71], off
	global_load_dwordx2 v[74:75], v[76:77], off offset:416
	global_load_dwordx2 v[72:73], v[76:77], off offset:448
	s_nop 0
	global_load_dwordx2 v[70:71], v[76:77], off offset:480
	v_lshl_add_u64 v[76:77], v[76:77], 0, v[140:141]
	global_load_ushort v85, v[76:77], off offset:480
	ds_read_b64 v[166:167], v164
	s_add_i32 s40, s40, s92
	s_cmpk_lt_i32 s40, 0x200
	s_waitcnt lgkmcnt(0)
	v_lshlrev_b32_e32 v176, 16, v166
	v_and_b32_e32 v177, 0xffff0000, v166
	s_waitcnt vmcnt(0)
	ds_bpermute_b32 v65, v162, v123
	v_cndmask_b32_e64 v67, v122, v128, s[12:13]
	v_cndmask_b32_e64 v69, v129, v123, s[10:11]
	v_cndmask_b32_e64 v77, v121, v129, s[10:11]
	v_cndmask_b32_e64 v88, v113, v117, s[10:11]
	ds_bpermute_b32 v119, v163, v67
	ds_bpermute_b32 v67, v162, v69
	ds_bpermute_b32 v69, v162, v77
	ds_bpermute_b32 v77, v162, v88
	s_waitcnt lgkmcnt(4)
	v_lshrrev_b32_e32 v65, 16, v65
	v_cndmask_b32_e64 v84, v116, v112, s[12:13]
	v_cndmask_b32_e64 v63, v63, 0, s[8:9]
	v_cndmask_b32_e64 v94, v105, v109, s[10:11]
	v_cndmask_b32_e64 v137, v65, v63, s[12:13]
	v_cndmask_b32_e64 v63, v82, v78, s[12:13]
	v_cndmask_b32_e64 v65, v75, v79, s[10:11]
	ds_bpermute_b32 v135, v163, v84
	ds_bpermute_b32 v84, v162, v94
	s_waitcnt lgkmcnt(2)
	v_and_b32_e32 v118, 0xffff0000, v77
	ds_bpermute_b32 v65, v162, v65
	ds_bpermute_b32 v77, v163, v63
	v_cndmask_b32_e64 v63, v78, v74, s[12:13]
	v_cndmask_b32_e64 v76, v128, v120, s[12:13]
	v_cndmask_b32_e64 v80, v120, v116, s[12:13]
	v_cndmask_b32_e64 v81, v117, v121, s[10:11]
	v_cndmask_b32_e64 v90, v109, v113, s[10:11]
	v_and_b32_e32 v132, 0xffff0000, v69
	ds_bpermute_b32 v69, v163, v63
	v_cndmask_b32_e64 v63, v73, v75, s[10:11]
	ds_bpermute_b32 v131, v163, v76
	ds_bpermute_b32 v133, v163, v80
	ds_bpermute_b32 v76, v162, v81
	ds_bpermute_b32 v80, v162, v90
	ds_bpermute_b32 v63, v162, v63
	v_cndmask_b32_e64 v107, v92, v86, s[12:13]
	v_cndmask_b32_e64 v110, v87, v93, s[10:11]
	ds_bpermute_b32 v165, v163, v107
	ds_bpermute_b32 v107, v162, v110
	s_waitcnt lgkmcnt(10)
	v_and_b32_e32 v110, 0xffff0000, v84
	s_waitcnt lgkmcnt(9)
	v_and_b32_e32 v84, 0xffff0000, v65
	v_cndmask_b32_e64 v65, v74, v72, s[12:13]
	v_cndmask_b32_e64 v111, v86, v82, s[12:13]
	v_cndmask_b32_e64 v114, v83, v87, s[10:11]
	v_and_b32_e32 v130, 0xffff0000, v67
	ds_bpermute_b32 v67, v163, v65
	v_cndmask_b32_e64 v65, v71, v73, s[10:11]
	ds_bpermute_b32 v81, v163, v111
	ds_bpermute_b32 v111, v162, v114
	s_waitcnt lgkmcnt(7)
	v_and_b32_e32 v136, 0xffff0000, v76
	s_waitcnt lgkmcnt(6)
	v_and_b32_e32 v114, 0xffff0000, v80
	ds_bpermute_b32 v76, v162, v65
	s_waitcnt lgkmcnt(6)
	v_and_b32_e32 v80, 0xffff0000, v63
	ds_bpermute_b32 v63, v163, v70
	v_cndmask_b32_e64 v65, v72, v70, s[12:13]
	ds_bpermute_b32 v65, v163, v65
	v_and_b32_e32 v173, 0xffff0000, v123
	v_lshlrev_b32_e32 v170, 16, v123
	v_and_b32_e32 v172, 16, v123
	v_mov_b32_e32 v171, v173
	v_pk_mov_b32 v[172:173], v[172:173], v[170:171] op_sel:[1,0]
	v_cndmask_b32_e64 v85, v85, 0, s[14:15]
	v_and_b32_e32 v168, 0xffff0000, v122
	v_mov_b32_e32 v169, v173
	s_waitcnt lgkmcnt(1)
	v_cndmask_b32_e64 v63, v63, v85, s[10:11]
	v_lshlrev_b32_e32 v85, 16, v119
	v_pk_fma_f32 v[174:175], v[66:67], v[168:169], v[68:69] op_sel_hi:[0,1,0]
	v_mov_b32_e32 v173, v85
	s_waitcnt lgkmcnt(0)
	v_pk_fma_f32 v[174:175], v[64:65], v[170:171], v[174:175] op_sel_hi:[0,1,1]
	v_pk_fma_f32 v[172:173], v[62:63], v[172:173], v[174:175] op_sel_hi:[0,1,1]
	v_lshlrev_b32_e32 v174, 16, v137
	v_lshlrev_b32_e32 v175, 16, v122
	v_pk_fma_f32 v[122:123], v[66:67], v[174:175], v[68:69] op_sel_hi:[0,1,0]
	v_pk_mov_b32 v[174:175], v[174:175], v[168:169] op_sel:[1,0]
	v_mov_b32_e32 v169, v170
	v_pk_fma_f32 v[122:123], v[64:65], v[174:175], v[122:123] op_sel_hi:[0,1,1]
	v_pk_fma_f32 v[124:125], v[134:135], v[176:177], v[124:125] op_sel_hi:[0,1,1]
	v_pk_fma_f32 v[122:123], v[62:63], v[168:169], v[122:123] op_sel_hi:[0,1,1]
	v_pk_mul_f32 v[122:123], v[122:123], v[124:125]
	v_lshlrev_b32_e32 v124, 16, v167
	v_and_b32_e32 v125, 0xffff0000, v167
	v_pk_fma_f32 v[124:125], v[134:135], v[124:125], v[126:127] op_sel_hi:[0,1,1]
	v_pk_mul_f32 v[124:125], v[172:173], v[124:125]
	v_cvt_pk_bf16_f32 v122, v122, v123
	v_cvt_pk_bf16_f32 v123, v124, v125
	v_and_b32_e32 v167, 0xffff0000, v129
	global_store_dwordx2 v[60:61], v[122:123], off
	v_lshlrev_b32_e32 v126, 16, v129
	v_and_b32_e32 v166, 16, v129
	v_mov_b32_e32 v127, v167
	ds_read_b64 v[122:123], v164 offset:32
	v_lshlrev_b32_e32 v85, 16, v131
	v_lshlrev_b32_e32 v131, 16, v128
	v_and_b32_e32 v124, 0xffff0000, v128
	v_pk_mov_b32 v[128:129], v[166:167], v[126:127] op_sel:[1,0]
	s_waitcnt lgkmcnt(0)
	v_lshlrev_b32_e32 v168, 16, v122
	v_mov_b32_e32 v125, v129
	v_pk_fma_f32 v[166:167], v[66:67], v[124:125], v[68:69] op_sel_hi:[0,1,0]
	v_mov_b32_e32 v129, v85
	v_pk_fma_f32 v[166:167], v[64:65], v[126:127], v[166:167] op_sel_hi:[0,1,1]
	v_pk_fma_f32 v[128:129], v[62:63], v[128:129], v[166:167] op_sel_hi:[0,1,1]
	v_pk_fma_f32 v[166:167], v[66:67], v[130:131], v[68:69] op_sel_hi:[0,1,0]
	v_pk_mov_b32 v[130:131], v[130:131], v[124:125] op_sel:[1,0]
	v_and_b32_e32 v169, 0xffff0000, v122
	v_pk_fma_f32 v[130:131], v[64:65], v[130:131], v[166:167] op_sel_hi:[0,1,1]
	v_mov_b32_e32 v125, v126
	v_lshlrev_b32_e32 v122, 16, v123
	v_and_b32_e32 v123, 0xffff0000, v123
	v_pk_fma_f32 v[56:57], v[134:135], v[168:169], v[56:57] op_sel_hi:[0,1,1]
	v_pk_fma_f32 v[124:125], v[62:63], v[124:125], v[130:131] op_sel_hi:[0,1,1]
	v_pk_fma_f32 v[58:59], v[134:135], v[122:123], v[58:59] op_sel_hi:[0,1,1]
	v_pk_mul_f32 v[56:57], v[124:125], v[56:57]
	v_pk_mul_f32 v[58:59], v[128:129], v[58:59]
	v_cvt_pk_bf16_f32 v56, v56, v57
	v_cvt_pk_bf16_f32 v57, v58, v59
	global_store_dwordx2 v[60:61], v[56:57], off offset:32
	ds_read_b64 v[56:57], v164 offset:64
	v_and_b32_e32 v123, 0xffff0000, v121
	v_lshlrev_b32_e32 v85, 16, v133
	v_lshlrev_b32_e32 v133, 16, v120
	v_and_b32_e32 v58, 0xffff0000, v120
	v_lshlrev_b32_e32 v120, 16, v121
	v_and_b32_e32 v122, 16, v121
	v_mov_b32_e32 v121, v123
	v_pk_mov_b32 v[122:123], v[122:123], v[120:121] op_sel:[1,0]
	s_waitcnt lgkmcnt(0)
	v_lshlrev_b32_e32 v126, 16, v56
	v_mov_b32_e32 v59, v123
	v_pk_fma_f32 v[124:125], v[66:67], v[58:59], v[68:69] op_sel_hi:[0,1,0]
	v_mov_b32_e32 v123, v85
	v_pk_fma_f32 v[124:125], v[64:65], v[120:121], v[124:125] op_sel_hi:[0,1,1]
	v_and_b32_e32 v127, 0xffff0000, v56
	v_pk_fma_f32 v[122:123], v[62:63], v[122:123], v[124:125] op_sel_hi:[0,1,1]
	v_pk_fma_f32 v[124:125], v[66:67], v[132:133], v[68:69] op_sel_hi:[0,1,0]
	v_pk_fma_f32 v[52:53], v[134:135], v[126:127], v[52:53] op_sel_hi:[0,1,1]
	v_pk_mov_b32 v[126:127], v[132:133], v[58:59] op_sel:[1,0]
	v_mov_b32_e32 v59, v120
	v_pk_fma_f32 v[124:125], v[64:65], v[126:127], v[124:125] op_sel_hi:[0,1,1]
	v_lshlrev_b32_e32 v56, 16, v57
	v_and_b32_e32 v57, 0xffff0000, v57
	v_pk_fma_f32 v[58:59], v[62:63], v[58:59], v[124:125] op_sel_hi:[0,1,1]
	v_pk_fma_f32 v[54:55], v[134:135], v[56:57], v[54:55] op_sel_hi:[0,1,1]
	v_pk_mul_f32 v[52:53], v[58:59], v[52:53]
	v_pk_mul_f32 v[54:55], v[122:123], v[54:55]
	v_cvt_pk_bf16_f32 v52, v52, v53
	v_cvt_pk_bf16_f32 v53, v54, v55
	global_store_dwordx2 v[60:61], v[52:53], off offset:64
	ds_read_b64 v[52:53], v164 offset:96
	v_and_b32_e32 v59, 0xffff0000, v117
	v_lshlrev_b32_e32 v56, 16, v117
	v_and_b32_e32 v58, 16, v117
	v_mov_b32_e32 v57, v59
	v_pk_mov_b32 v[58:59], v[58:59], v[56:57] op_sel:[1,0]
	v_and_b32_e32 v54, 0xffff0000, v116
	v_mov_b32_e32 v55, v59
	v_lshlrev_b32_e32 v85, 16, v135
	v_lshlrev_b32_e32 v137, 16, v116
	v_pk_fma_f32 v[116:117], v[66:67], v[54:55], v[68:69] op_sel_hi:[0,1,0]
	v_mov_b32_e32 v59, v85
	v_pk_fma_f32 v[116:117], v[64:65], v[56:57], v[116:117] op_sel_hi:[0,1,1]
	s_waitcnt lgkmcnt(0)
	v_lshlrev_b32_e32 v120, 16, v52
	v_and_b32_e32 v121, 0xffff0000, v52
	v_pk_fma_f32 v[58:59], v[62:63], v[58:59], v[116:117] op_sel_hi:[0,1,1]
	v_pk_fma_f32 v[116:117], v[66:67], v[136:137], v[68:69] op_sel_hi:[0,1,0]
	v_pk_fma_f32 v[48:49], v[134:135], v[120:121], v[48:49] op_sel_hi:[0,1,1]
	v_pk_mov_b32 v[120:121], v[136:137], v[54:55] op_sel:[1,0]
	v_mov_b32_e32 v55, v56
	v_pk_fma_f32 v[116:117], v[64:65], v[120:121], v[116:117] op_sel_hi:[0,1,1]
	v_lshlrev_b32_e32 v52, 16, v53
	v_and_b32_e32 v53, 0xffff0000, v53
	v_pk_fma_f32 v[54:55], v[62:63], v[54:55], v[116:117] op_sel_hi:[0,1,1]
	v_pk_fma_f32 v[50:51], v[134:135], v[52:53], v[50:51] op_sel_hi:[0,1,1]
	v_cndmask_b32_e64 v89, v112, v108, s[12:13]
	v_pk_mul_f32 v[48:49], v[54:55], v[48:49]
	v_pk_mul_f32 v[50:51], v[58:59], v[50:51]
	ds_bpermute_b32 v89, v163, v89
	v_cvt_pk_bf16_f32 v48, v48, v49
	v_cvt_pk_bf16_f32 v49, v50, v51
	global_store_dwordx2 v[60:61], v[48:49], off offset:96
	ds_read_b64 v[48:49], v164 offset:128
	v_and_b32_e32 v55, 0xffff0000, v113
	v_lshlrev_b32_e32 v52, 16, v113
	v_and_b32_e32 v54, 16, v113
	v_mov_b32_e32 v53, v55
	v_pk_mov_b32 v[54:55], v[54:55], v[52:53] op_sel:[1,0]
	s_waitcnt lgkmcnt(0)
	v_lshlrev_b32_e32 v56, 16, v89
	v_and_b32_e32 v50, 0xffff0000, v112
	v_mov_b32_e32 v51, v55
	v_mov_b32_e32 v55, v56
	v_pk_fma_f32 v[56:57], v[66:67], v[50:51], v[68:69] op_sel_hi:[0,1,0]
	v_lshlrev_b32_e32 v119, 16, v112
	v_pk_fma_f32 v[56:57], v[64:65], v[52:53], v[56:57] op_sel_hi:[0,1,1]
	v_lshlrev_b32_e32 v58, 16, v48
	v_and_b32_e32 v59, 0xffff0000, v48
	v_pk_fma_f32 v[54:55], v[62:63], v[54:55], v[56:57] op_sel_hi:[0,1,1]
	v_pk_fma_f32 v[56:57], v[66:67], v[118:119], v[68:69] op_sel_hi:[0,1,0]
	v_pk_fma_f32 v[44:45], v[134:135], v[58:59], v[44:45] op_sel_hi:[0,1,1]
	v_pk_mov_b32 v[58:59], v[118:119], v[50:51] op_sel:[1,0]
	v_mov_b32_e32 v51, v52
	v_pk_fma_f32 v[56:57], v[64:65], v[58:59], v[56:57] op_sel_hi:[0,1,1]
	v_lshlrev_b32_e32 v48, 16, v49
	v_and_b32_e32 v49, 0xffff0000, v49
	v_pk_fma_f32 v[50:51], v[62:63], v[50:51], v[56:57] op_sel_hi:[0,1,1]
	v_pk_fma_f32 v[46:47], v[134:135], v[48:49], v[46:47] op_sel_hi:[0,1,1]
	v_cndmask_b32_e64 v91, v108, v104, s[12:13]
	v_pk_mul_f32 v[44:45], v[50:51], v[44:45]
	v_pk_mul_f32 v[46:47], v[54:55], v[46:47]
	ds_bpermute_b32 v91, v163, v91
	v_cvt_pk_bf16_f32 v44, v44, v45
	v_cvt_pk_bf16_f32 v45, v46, v47
	v_cndmask_b32_e64 v98, v101, v105, s[10:11]
	v_cndmask_b32_e64 v115, v79, v83, s[10:11]
	global_store_dwordx2 v[60:61], v[44:45], off offset:128
	ds_bpermute_b32 v88, v162, v98
	ds_bpermute_b32 v115, v162, v115
	ds_read_b64 v[44:45], v164 offset:160
	v_and_b32_e32 v51, 0xffff0000, v109
	v_lshlrev_b32_e32 v48, 16, v109
	v_and_b32_e32 v50, 16, v109
	v_mov_b32_e32 v49, v51
	v_pk_mov_b32 v[50:51], v[50:51], v[48:49] op_sel:[1,0]
	s_waitcnt lgkmcnt(0)
	v_lshlrev_b32_e32 v52, 16, v91
	v_and_b32_e32 v46, 0xffff0000, v108
	v_mov_b32_e32 v47, v51
	v_cndmask_b32_e64 v106, v93, v97, s[10:11]
	v_mov_b32_e32 v51, v52
	v_pk_fma_f32 v[52:53], v[66:67], v[46:47], v[68:69] op_sel_hi:[0,1,0]
	ds_bpermute_b32 v94, v162, v106
	v_and_b32_e32 v106, 0xffff0000, v88
	v_and_b32_e32 v88, 0xffff0000, v115
	v_lshlrev_b32_e32 v115, 16, v108
	v_pk_fma_f32 v[52:53], v[64:65], v[48:49], v[52:53] op_sel_hi:[0,1,1]
	v_lshlrev_b32_e32 v54, 16, v44
	v_and_b32_e32 v55, 0xffff0000, v44
	v_pk_fma_f32 v[50:51], v[62:63], v[50:51], v[52:53] op_sel_hi:[0,1,1]
	v_pk_fma_f32 v[52:53], v[66:67], v[114:115], v[68:69] op_sel_hi:[0,1,0]
	v_pk_fma_f32 v[40:41], v[134:135], v[54:55], v[40:41] op_sel_hi:[0,1,1]
	v_pk_mov_b32 v[54:55], v[114:115], v[46:47] op_sel:[1,0]
	v_mov_b32_e32 v47, v48
	v_pk_fma_f32 v[52:53], v[64:65], v[54:55], v[52:53] op_sel_hi:[0,1,1]
	v_lshlrev_b32_e32 v44, 16, v45
	v_and_b32_e32 v45, 0xffff0000, v45
	v_pk_fma_f32 v[46:47], v[62:63], v[46:47], v[52:53] op_sel_hi:[0,1,1]
	v_pk_fma_f32 v[42:43], v[134:135], v[44:45], v[42:43] op_sel_hi:[0,1,1]
	v_cndmask_b32_e64 v95, v104, v100, s[12:13]
	v_pk_mul_f32 v[40:41], v[46:47], v[40:41]
	v_pk_mul_f32 v[42:43], v[50:51], v[42:43]
	ds_bpermute_b32 v95, v163, v95
	v_cvt_pk_bf16_f32 v40, v40, v41
	v_cvt_pk_bf16_f32 v41, v42, v43
	v_cndmask_b32_e64 v102, v97, v101, s[10:11]
	global_store_dwordx2 v[60:61], v[40:41], off offset:160
	ds_bpermute_b32 v90, v162, v102
	ds_read_b64 v[40:41], v164 offset:192
	v_and_b32_e32 v47, 0xffff0000, v105
	v_lshlrev_b32_e32 v44, 16, v105
	v_and_b32_e32 v46, 16, v105
	v_mov_b32_e32 v45, v47
	v_pk_mov_b32 v[46:47], v[46:47], v[44:45] op_sel:[1,0]
	s_waitcnt lgkmcnt(0)
	v_lshlrev_b32_e32 v48, 16, v95
	v_and_b32_e32 v42, 0xffff0000, v104
	v_mov_b32_e32 v43, v47
	v_mov_b32_e32 v47, v48
	v_pk_fma_f32 v[48:49], v[66:67], v[42:43], v[68:69] op_sel_hi:[0,1,0]
	v_and_b32_e32 v102, 0xffff0000, v90
	v_and_b32_e32 v90, 0xffff0000, v111
	v_lshlrev_b32_e32 v111, 16, v104
	v_pk_fma_f32 v[48:49], v[64:65], v[44:45], v[48:49] op_sel_hi:[0,1,1]
	v_lshlrev_b32_e32 v50, 16, v40
	v_and_b32_e32 v51, 0xffff0000, v40
	v_pk_fma_f32 v[46:47], v[62:63], v[46:47], v[48:49] op_sel_hi:[0,1,1]
	v_pk_fma_f32 v[48:49], v[66:67], v[110:111], v[68:69] op_sel_hi:[0,1,0]
	v_pk_fma_f32 v[36:37], v[134:135], v[50:51], v[36:37] op_sel_hi:[0,1,1]
	v_pk_mov_b32 v[50:51], v[110:111], v[42:43] op_sel:[1,0]
	v_mov_b32_e32 v43, v44
	v_pk_fma_f32 v[48:49], v[64:65], v[50:51], v[48:49] op_sel_hi:[0,1,1]
	v_lshlrev_b32_e32 v40, 16, v41
	v_and_b32_e32 v41, 0xffff0000, v41
	v_pk_fma_f32 v[42:43], v[62:63], v[42:43], v[48:49] op_sel_hi:[0,1,1]
	v_pk_fma_f32 v[38:39], v[134:135], v[40:41], v[38:39] op_sel_hi:[0,1,1]
	v_cndmask_b32_e64 v99, v100, v96, s[12:13]
	v_pk_mul_f32 v[36:37], v[42:43], v[36:37]
	v_pk_mul_f32 v[38:39], v[46:47], v[38:39]
	ds_bpermute_b32 v99, v163, v99
	v_cvt_pk_bf16_f32 v36, v36, v37
	v_cvt_pk_bf16_f32 v37, v38, v39
	global_store_dwordx2 v[60:61], v[36:37], off offset:192
	ds_read_b64 v[36:37], v164 offset:224
	v_and_b32_e32 v43, 0xffff0000, v101
	v_lshlrev_b32_e32 v40, 16, v101
	v_and_b32_e32 v42, 16, v101
	v_mov_b32_e32 v41, v43
	v_pk_mov_b32 v[42:43], v[42:43], v[40:41] op_sel:[1,0]
	s_waitcnt lgkmcnt(0)
	v_lshlrev_b32_e32 v44, 16, v99
	v_and_b32_e32 v38, 0xffff0000, v100
	v_mov_b32_e32 v39, v43
	v_mov_b32_e32 v43, v44
	v_pk_fma_f32 v[44:45], v[66:67], v[38:39], v[68:69] op_sel_hi:[0,1,0]
	v_and_b32_e32 v98, 0xffff0000, v94
	v_and_b32_e32 v94, 0xffff0000, v107
	v_lshlrev_b32_e32 v107, 16, v100
	v_pk_fma_f32 v[44:45], v[64:65], v[40:41], v[44:45] op_sel_hi:[0,1,1]
	v_lshlrev_b32_e32 v46, 16, v36
	v_and_b32_e32 v47, 0xffff0000, v36
	v_pk_fma_f32 v[42:43], v[62:63], v[42:43], v[44:45] op_sel_hi:[0,1,1]
	v_pk_fma_f32 v[44:45], v[66:67], v[106:107], v[68:69] op_sel_hi:[0,1,0]
	v_pk_fma_f32 v[32:33], v[134:135], v[46:47], v[32:33] op_sel_hi:[0,1,1]
	v_pk_mov_b32 v[46:47], v[106:107], v[38:39] op_sel:[1,0]
	v_mov_b32_e32 v39, v40
	v_pk_fma_f32 v[44:45], v[64:65], v[46:47], v[44:45] op_sel_hi:[0,1,1]
	v_lshlrev_b32_e32 v36, 16, v37
	v_and_b32_e32 v37, 0xffff0000, v37
	v_pk_fma_f32 v[38:39], v[62:63], v[38:39], v[44:45] op_sel_hi:[0,1,1]
	v_pk_fma_f32 v[34:35], v[134:135], v[36:37], v[34:35] op_sel_hi:[0,1,1]
	v_cndmask_b32_e64 v103, v96, v92, s[12:13]
	v_pk_mul_f32 v[32:33], v[38:39], v[32:33]
	v_pk_mul_f32 v[34:35], v[42:43], v[34:35]
	ds_bpermute_b32 v103, v163, v103
	v_cvt_pk_bf16_f32 v32, v32, v33
	v_cvt_pk_bf16_f32 v33, v34, v35
	global_store_dwordx2 v[60:61], v[32:33], off offset:224
	ds_read_b64 v[32:33], v164 offset:256
	v_and_b32_e32 v39, 0xffff0000, v97
	v_lshlrev_b32_e32 v36, 16, v97
	v_and_b32_e32 v38, 16, v97
	v_mov_b32_e32 v37, v39
	v_pk_mov_b32 v[38:39], v[38:39], v[36:37] op_sel:[1,0]
	s_waitcnt lgkmcnt(0)
	v_lshlrev_b32_e32 v40, 16, v103
	v_and_b32_e32 v34, 0xffff0000, v96
	v_mov_b32_e32 v35, v39
	v_mov_b32_e32 v39, v40
	v_pk_fma_f32 v[40:41], v[66:67], v[34:35], v[68:69] op_sel_hi:[0,1,0]
	v_lshlrev_b32_e32 v103, 16, v96
	v_pk_fma_f32 v[40:41], v[64:65], v[36:37], v[40:41] op_sel_hi:[0,1,1]
	v_lshlrev_b32_e32 v42, 16, v32
	v_and_b32_e32 v43, 0xffff0000, v32
	v_pk_fma_f32 v[38:39], v[62:63], v[38:39], v[40:41] op_sel_hi:[0,1,1]
	v_pk_fma_f32 v[40:41], v[66:67], v[102:103], v[68:69] op_sel_hi:[0,1,0]
	v_pk_fma_f32 v[28:29], v[134:135], v[42:43], v[28:29] op_sel_hi:[0,1,1]
	v_pk_mov_b32 v[42:43], v[102:103], v[34:35] op_sel:[1,0]
	v_mov_b32_e32 v35, v36
	v_pk_fma_f32 v[40:41], v[64:65], v[42:43], v[40:41] op_sel_hi:[0,1,1]
	v_lshlrev_b32_e32 v32, 16, v33
	v_and_b32_e32 v33, 0xffff0000, v33
	v_pk_fma_f32 v[34:35], v[62:63], v[34:35], v[40:41] op_sel_hi:[0,1,1]
	v_pk_fma_f32 v[30:31], v[134:135], v[32:33], v[30:31] op_sel_hi:[0,1,1]
	v_pk_mul_f32 v[28:29], v[34:35], v[28:29]
	v_pk_mul_f32 v[30:31], v[38:39], v[30:31]
	v_cvt_pk_bf16_f32 v28, v28, v29
	v_cvt_pk_bf16_f32 v29, v30, v31
	global_store_dwordx2 v[60:61], v[28:29], off offset:256
	ds_read_b64 v[28:29], v164 offset:288
	v_and_b32_e32 v35, 0xffff0000, v93
	v_lshlrev_b32_e32 v32, 16, v93
	v_and_b32_e32 v34, 16, v93
	v_mov_b32_e32 v33, v35
	v_pk_mov_b32 v[34:35], v[34:35], v[32:33] op_sel:[1,0]
	v_lshlrev_b32_e32 v36, 16, v165
	v_and_b32_e32 v30, 0xffff0000, v92
	v_mov_b32_e32 v31, v35
	v_mov_b32_e32 v35, v36
	v_pk_fma_f32 v[36:37], v[66:67], v[30:31], v[68:69] op_sel_hi:[0,1,0]
	v_lshlrev_b32_e32 v99, 16, v92
	v_pk_fma_f32 v[36:37], v[64:65], v[32:33], v[36:37] op_sel_hi:[0,1,1]
	s_waitcnt lgkmcnt(0)
	v_lshlrev_b32_e32 v38, 16, v28
	v_and_b32_e32 v39, 0xffff0000, v28
	v_pk_fma_f32 v[34:35], v[62:63], v[34:35], v[36:37] op_sel_hi:[0,1,1]
	v_pk_fma_f32 v[36:37], v[66:67], v[98:99], v[68:69] op_sel_hi:[0,1,0]
	v_pk_fma_f32 v[24:25], v[134:135], v[38:39], v[24:25] op_sel_hi:[0,1,1]
	v_pk_mov_b32 v[38:39], v[98:99], v[30:31] op_sel:[1,0]
	v_mov_b32_e32 v31, v32
	v_pk_fma_f32 v[36:37], v[64:65], v[38:39], v[36:37] op_sel_hi:[0,1,1]
	v_lshlrev_b32_e32 v28, 16, v29
	v_and_b32_e32 v29, 0xffff0000, v29
	v_pk_fma_f32 v[30:31], v[62:63], v[30:31], v[36:37] op_sel_hi:[0,1,1]
	v_pk_fma_f32 v[26:27], v[134:135], v[28:29], v[26:27] op_sel_hi:[0,1,1]
	v_pk_mul_f32 v[24:25], v[30:31], v[24:25]
	v_pk_mul_f32 v[26:27], v[34:35], v[26:27]
	v_cvt_pk_bf16_f32 v24, v24, v25
	v_cvt_pk_bf16_f32 v25, v26, v27
	global_store_dwordx2 v[60:61], v[24:25], off offset:288
	ds_read_b64 v[24:25], v164 offset:320
	v_and_b32_e32 v31, 0xffff0000, v87
	v_lshlrev_b32_e32 v28, 16, v87
	v_and_b32_e32 v30, 16, v87
	v_mov_b32_e32 v29, v31
	v_pk_mov_b32 v[30:31], v[30:31], v[28:29] op_sel:[1,0]
	v_lshlrev_b32_e32 v32, 16, v81
	v_and_b32_e32 v26, 0xffff0000, v86
	v_mov_b32_e32 v27, v31
	v_mov_b32_e32 v31, v32
	v_pk_fma_f32 v[32:33], v[66:67], v[26:27], v[68:69] op_sel_hi:[0,1,0]
	v_lshlrev_b32_e32 v95, 16, v86
	v_pk_fma_f32 v[32:33], v[64:65], v[28:29], v[32:33] op_sel_hi:[0,1,1]
	s_waitcnt lgkmcnt(0)
	v_lshlrev_b32_e32 v34, 16, v24
	v_and_b32_e32 v35, 0xffff0000, v24
	v_pk_fma_f32 v[30:31], v[62:63], v[30:31], v[32:33] op_sel_hi:[0,1,1]
	v_pk_fma_f32 v[32:33], v[66:67], v[94:95], v[68:69] op_sel_hi:[0,1,0]
	v_pk_fma_f32 v[20:21], v[134:135], v[34:35], v[20:21] op_sel_hi:[0,1,1]
	v_pk_mov_b32 v[34:35], v[94:95], v[26:27] op_sel:[1,0]
	v_mov_b32_e32 v27, v28
	v_pk_fma_f32 v[32:33], v[64:65], v[34:35], v[32:33] op_sel_hi:[0,1,1]
	v_lshlrev_b32_e32 v24, 16, v25
	v_and_b32_e32 v25, 0xffff0000, v25
	v_pk_fma_f32 v[26:27], v[62:63], v[26:27], v[32:33] op_sel_hi:[0,1,1]
	v_pk_fma_f32 v[22:23], v[134:135], v[24:25], v[22:23] op_sel_hi:[0,1,1]
	v_pk_mul_f32 v[20:21], v[26:27], v[20:21]
	v_pk_mul_f32 v[22:23], v[30:31], v[22:23]
	v_cvt_pk_bf16_f32 v20, v20, v21
	v_cvt_pk_bf16_f32 v21, v22, v23
	global_store_dwordx2 v[60:61], v[20:21], off offset:320
	ds_read_b64 v[20:21], v164 offset:352
	v_and_b32_e32 v27, 0xffff0000, v83
	v_lshlrev_b32_e32 v24, 16, v83
	v_and_b32_e32 v26, 16, v83
	v_mov_b32_e32 v25, v27
	v_pk_mov_b32 v[26:27], v[26:27], v[24:25] op_sel:[1,0]
	v_lshlrev_b32_e32 v28, 16, v77
	v_and_b32_e32 v22, 0xffff0000, v82
	v_mov_b32_e32 v23, v27
	v_mov_b32_e32 v27, v28
	v_pk_fma_f32 v[28:29], v[66:67], v[22:23], v[68:69] op_sel_hi:[0,1,0]
	v_lshlrev_b32_e32 v91, 16, v82
	v_pk_fma_f32 v[28:29], v[64:65], v[24:25], v[28:29] op_sel_hi:[0,1,1]
	s_waitcnt lgkmcnt(0)
	v_lshlrev_b32_e32 v30, 16, v20
	v_and_b32_e32 v31, 0xffff0000, v20
	v_pk_fma_f32 v[26:27], v[62:63], v[26:27], v[28:29] op_sel_hi:[0,1,1]
	v_pk_fma_f32 v[28:29], v[66:67], v[90:91], v[68:69] op_sel_hi:[0,1,0]
	v_pk_fma_f32 v[16:17], v[134:135], v[30:31], v[16:17] op_sel_hi:[0,1,1]
	v_pk_mov_b32 v[30:31], v[90:91], v[22:23] op_sel:[1,0]
	v_mov_b32_e32 v23, v24
	v_pk_fma_f32 v[28:29], v[64:65], v[30:31], v[28:29] op_sel_hi:[0,1,1]
	v_lshlrev_b32_e32 v20, 16, v21
	v_and_b32_e32 v21, 0xffff0000, v21
	v_pk_fma_f32 v[22:23], v[62:63], v[22:23], v[28:29] op_sel_hi:[0,1,1]
	v_pk_fma_f32 v[18:19], v[134:135], v[20:21], v[18:19] op_sel_hi:[0,1,1]
	v_pk_mul_f32 v[16:17], v[22:23], v[16:17]
	v_pk_mul_f32 v[18:19], v[26:27], v[18:19]
	v_cvt_pk_bf16_f32 v16, v16, v17
	v_cvt_pk_bf16_f32 v17, v18, v19
	global_store_dwordx2 v[60:61], v[16:17], off offset:352
	ds_read_b64 v[16:17], v164 offset:384
	v_and_b32_e32 v23, 0xffff0000, v79
	v_lshlrev_b32_e32 v20, 16, v79
	v_and_b32_e32 v22, 16, v79
	v_mov_b32_e32 v21, v23
	v_pk_mov_b32 v[22:23], v[22:23], v[20:21] op_sel:[1,0]
	v_lshlrev_b32_e32 v24, 16, v69
	v_and_b32_e32 v18, 0xffff0000, v78
	v_mov_b32_e32 v19, v23
	v_mov_b32_e32 v23, v24
	v_pk_fma_f32 v[24:25], v[66:67], v[18:19], v[68:69] op_sel_hi:[0,1,0]
	v_lshlrev_b32_e32 v89, 16, v78
	v_pk_fma_f32 v[24:25], v[64:65], v[20:21], v[24:25] op_sel_hi:[0,1,1]
	s_waitcnt lgkmcnt(0)
	v_lshlrev_b32_e32 v26, 16, v16
	v_and_b32_e32 v27, 0xffff0000, v16
	v_pk_fma_f32 v[22:23], v[62:63], v[22:23], v[24:25] op_sel_hi:[0,1,1]
	v_pk_fma_f32 v[24:25], v[66:67], v[88:89], v[68:69] op_sel_hi:[0,1,0]
	v_pk_fma_f32 v[12:13], v[134:135], v[26:27], v[12:13] op_sel_hi:[0,1,1]
	v_pk_mov_b32 v[26:27], v[88:89], v[18:19] op_sel:[1,0]
	v_mov_b32_e32 v19, v20
	v_pk_fma_f32 v[24:25], v[64:65], v[26:27], v[24:25] op_sel_hi:[0,1,1]
	v_lshlrev_b32_e32 v16, 16, v17
	v_and_b32_e32 v17, 0xffff0000, v17
	v_pk_fma_f32 v[18:19], v[62:63], v[18:19], v[24:25] op_sel_hi:[0,1,1]
	v_pk_fma_f32 v[14:15], v[134:135], v[16:17], v[14:15] op_sel_hi:[0,1,1]
	v_pk_mul_f32 v[12:13], v[18:19], v[12:13]
	v_pk_mul_f32 v[14:15], v[22:23], v[14:15]
	v_cvt_pk_bf16_f32 v12, v12, v13
	v_cvt_pk_bf16_f32 v13, v14, v15
	global_store_dwordx2 v[60:61], v[12:13], off offset:384
	ds_read_b64 v[12:13], v164 offset:416
	v_and_b32_e32 v19, 0xffff0000, v75
	v_lshlrev_b32_e32 v16, 16, v75
	v_and_b32_e32 v18, 16, v75
	v_mov_b32_e32 v17, v19
	v_pk_mov_b32 v[18:19], v[18:19], v[16:17] op_sel:[1,0]
	v_lshlrev_b32_e32 v20, 16, v67
	v_and_b32_e32 v14, 0xffff0000, v74
	v_mov_b32_e32 v15, v19
	v_mov_b32_e32 v19, v20
	v_pk_fma_f32 v[20:21], v[66:67], v[14:15], v[68:69] op_sel_hi:[0,1,0]
	v_lshlrev_b32_e32 v85, 16, v74
	v_pk_fma_f32 v[20:21], v[64:65], v[16:17], v[20:21] op_sel_hi:[0,1,1]
	s_waitcnt lgkmcnt(0)
	v_lshlrev_b32_e32 v22, 16, v12
	v_and_b32_e32 v23, 0xffff0000, v12
	v_pk_fma_f32 v[18:19], v[62:63], v[18:19], v[20:21] op_sel_hi:[0,1,1]
	v_pk_fma_f32 v[20:21], v[66:67], v[84:85], v[68:69] op_sel_hi:[0,1,0]
	v_pk_fma_f32 v[8:9], v[134:135], v[22:23], v[8:9] op_sel_hi:[0,1,1]
	v_pk_mov_b32 v[22:23], v[84:85], v[14:15] op_sel:[1,0]
	v_mov_b32_e32 v15, v16
	v_pk_fma_f32 v[20:21], v[64:65], v[22:23], v[20:21] op_sel_hi:[0,1,1]
	v_lshlrev_b32_e32 v12, 16, v13
	v_and_b32_e32 v13, 0xffff0000, v13
	v_pk_fma_f32 v[14:15], v[62:63], v[14:15], v[20:21] op_sel_hi:[0,1,1]
	v_pk_fma_f32 v[10:11], v[134:135], v[12:13], v[10:11] op_sel_hi:[0,1,1]
	v_pk_mul_f32 v[8:9], v[14:15], v[8:9]
	v_pk_mul_f32 v[10:11], v[18:19], v[10:11]
	v_cvt_pk_bf16_f32 v8, v8, v9
	v_cvt_pk_bf16_f32 v9, v10, v11
	global_store_dwordx2 v[60:61], v[8:9], off offset:416
	ds_read_b64 v[8:9], v164 offset:448
	v_and_b32_e32 v15, 0xffff0000, v73
	v_lshlrev_b32_e32 v12, 16, v73
	v_and_b32_e32 v14, 16, v73
	v_mov_b32_e32 v13, v15
	v_pk_mov_b32 v[14:15], v[14:15], v[12:13] op_sel:[1,0]
	v_lshlrev_b32_e32 v16, 16, v65
	v_and_b32_e32 v10, 0xffff0000, v72
	v_mov_b32_e32 v11, v15
	v_mov_b32_e32 v15, v16
	v_pk_fma_f32 v[16:17], v[66:67], v[10:11], v[68:69] op_sel_hi:[0,1,0]
	v_lshlrev_b32_e32 v81, 16, v72
	v_pk_fma_f32 v[16:17], v[64:65], v[12:13], v[16:17] op_sel_hi:[0,1,1]
	s_waitcnt lgkmcnt(0)
	v_lshlrev_b32_e32 v18, 16, v8
	v_and_b32_e32 v19, 0xffff0000, v8
	v_pk_fma_f32 v[14:15], v[62:63], v[14:15], v[16:17] op_sel_hi:[0,1,1]
	v_pk_fma_f32 v[16:17], v[66:67], v[80:81], v[68:69] op_sel_hi:[0,1,0]
	v_pk_fma_f32 v[4:5], v[134:135], v[18:19], v[4:5] op_sel_hi:[0,1,1]
	v_pk_mov_b32 v[18:19], v[80:81], v[10:11] op_sel:[1,0]
	v_mov_b32_e32 v11, v12
	v_pk_fma_f32 v[16:17], v[64:65], v[18:19], v[16:17] op_sel_hi:[0,1,1]
	v_lshlrev_b32_e32 v8, 16, v9
	v_and_b32_e32 v9, 0xffff0000, v9
	v_pk_fma_f32 v[10:11], v[62:63], v[10:11], v[16:17] op_sel_hi:[0,1,1]
	v_pk_fma_f32 v[6:7], v[134:135], v[8:9], v[6:7] op_sel_hi:[0,1,1]
	v_pk_mul_f32 v[4:5], v[10:11], v[4:5]
	v_pk_mul_f32 v[6:7], v[14:15], v[6:7]
	v_cvt_pk_bf16_f32 v4, v4, v5
	v_cvt_pk_bf16_f32 v5, v6, v7
	global_store_dwordx2 v[60:61], v[4:5], off offset:448
	ds_read_b64 v[4:5], v164 offset:480
	v_and_b32_e32 v11, 0xffff0000, v71
	v_lshlrev_b32_e32 v8, 16, v71
	v_and_b32_e32 v10, 16, v71
	v_mov_b32_e32 v9, v11
	v_pk_mov_b32 v[10:11], v[10:11], v[8:9] op_sel:[1,0]
	v_lshlrev_b32_e32 v12, 16, v63
	v_and_b32_e32 v6, 0xffff0000, v70
	v_mov_b32_e32 v7, v11
	v_mov_b32_e32 v11, v12
	v_pk_fma_f32 v[12:13], v[66:67], v[6:7], v[68:69] op_sel_hi:[0,1,0]
	v_and_b32_e32 v76, 0xffff0000, v76
	v_lshlrev_b32_e32 v77, 16, v70
	v_pk_fma_f32 v[12:13], v[64:65], v[8:9], v[12:13] op_sel_hi:[0,1,1]
	s_waitcnt lgkmcnt(0)
	v_lshlrev_b32_e32 v14, 16, v4
	v_and_b32_e32 v15, 0xffff0000, v4
	v_pk_fma_f32 v[10:11], v[62:63], v[10:11], v[12:13] op_sel_hi:[0,1,1]
	v_pk_fma_f32 v[12:13], v[66:67], v[76:77], v[68:69] op_sel_hi:[0,1,0]
	v_pk_fma_f32 v[0:1], v[134:135], v[14:15], v[0:1] op_sel_hi:[0,1,1]
	v_pk_mov_b32 v[14:15], v[76:77], v[6:7] op_sel:[1,0]
	v_mov_b32_e32 v7, v8
	v_pk_fma_f32 v[12:13], v[64:65], v[14:15], v[12:13] op_sel_hi:[0,1,1]
	v_lshlrev_b32_e32 v4, 16, v5
	v_and_b32_e32 v5, 0xffff0000, v5
	v_pk_fma_f32 v[6:7], v[62:63], v[6:7], v[12:13] op_sel_hi:[0,1,1]
	v_pk_fma_f32 v[2:3], v[134:135], v[4:5], v[2:3] op_sel_hi:[0,1,1]
	v_pk_mul_f32 v[0:1], v[6:7], v[0:1]
	v_pk_mul_f32 v[2:3], v[10:11], v[2:3]
	v_cvt_pk_bf16_f32 v0, v0, v1
	v_cvt_pk_bf16_f32 v1, v2, v3
	global_store_dwordx2 v[60:61], v[0:1], off offset:480
	s_cbranch_scc1 .LBB0_449

.LBB0_546:
	s_or_b64 exec, exec, s[10:11]
	v_add_u32_e32 v0, s3, v0
	v_cmp_lt_i32_e32 vcc, s56, v0
	v_cvt_pk_bf16_f32 v1, v146, s0
	v_lshl_add_u64 v[12:13], v[14:15], 0, v[144:145]
	s_or_b64 s[4:5], vcc, s[4:5]
	global_store_short v[12:13], v1, off
	s_andn2_b64 exec, exec, s[4:5]
	s_cbranch_execz .LBB0_551
.LBB0_547:
	v_bfe_u32 v1, v0, 6, 1
	v_ashrrev_i32_e32 v14, 11, v0
	v_lshl_add_u32 v2, v1, 5, v14
	v_ashrrev_i32_e32 v15, 31, v14
	v_mul_i32_i24_e32 v12, 33, v2
	v_lshlrev_b64 v[14:15], 10, v[14:15]
	v_lshrrev_b32_e32 v2, 1, v0
	v_ashrrev_i32_e32 v13, 31, v12
	v_and_or_b32 v14, v2, s12, v14
	v_lshlrev_b64 v[12:13], 9, v[12:13]
	v_lshlrev_b64 v[16:17], 10, v[14:15]
	v_lshl_add_u64 v[12:13], v[4:5], 0, v[12:13]
	v_lshl_add_u64 v[16:17], s[22:23], 0, v[16:17]
	v_lshlrev_b32_e32 v2, 9, v1
	v_add_co_u32_e32 v12, vcc, 0x4000, v12
	v_lshl_add_u64 v[16:17], v[16:17], 0, v[2:3]
	v_mad_i64_i32 v[14:15], s[10:11], v14, s13, v[8:9]
	v_lshlrev_b32_e32 v2, 8, v1
	v_addc_co_u32_e32 v13, vcc, 0, v13, vcc
	v_lshl_add_u64 v[142:143], v[16:17], 0, v[6:7]
	v_lshl_add_u64 v[14:15], v[14:15], 0, v[2:3]
	global_load_dwordx2 v[12:13], v[12:13], off
	v_lshl_add_u64 v[14:15], v[14:15], 0, v[10:11]
	v_add_co_u32_e32 v16, vcc, s14, v142
	v_lshl_add_u64 v[14:15], v[14:15], 0, s[8:9]
	s_nop 0
	v_addc_co_u32_e32 v17, vcc, 0, v143, vcc
	s_waitcnt lgkmcnt(0)
	global_load_dword v19, v[142:143], off offset:2048
	global_load_dword v18, v[142:143], off offset:2304
	global_load_dword v20, v[142:143], off offset:3072
	global_load_dword v21, v[142:143], off offset:3328
	global_load_dword v22, v[16:17], off
	global_load_dword v23, v[16:17], off offset:256
	global_load_dword v24, v[16:17], off offset:1024
	global_load_dword v25, v[16:17], off offset:1280
	global_load_dword v26, v[16:17], off offset:2048
	global_load_dword v27, v[16:17], off offset:2304
	global_load_dword v28, v[16:17], off offset:3072
	global_load_dword v29, v[16:17], off offset:3328
	v_add_co_u32_e32 v16, vcc, s15, v142
	v_and_b32_e32 v1, 64, v0
	s_nop 0
	v_addc_co_u32_e32 v17, vcc, 0, v143, vcc
	global_load_dword v30, v[16:17], off
	global_load_dword v31, v[16:17], off offset:256
	global_load_dword v32, v[16:17], off offset:1024
	global_load_dword v33, v[16:17], off offset:1280
	global_load_dword v34, v[16:17], off offset:2048
	global_load_dword v35, v[16:17], off offset:2304
	global_load_dword v36, v[16:17], off offset:3072
	global_load_dword v37, v[16:17], off offset:3328
	v_add_co_u32_e32 v16, vcc, s16, v142
	s_waitcnt vmcnt(0)
	v_pk_mul_f32 v[144:145], v[12:13], 0 op_sel_hi:[1,0]
	v_addc_co_u32_e32 v17, vcc, 0, v143, vcc
	global_load_dword v38, v[16:17], off
	global_load_dword v39, v[16:17], off offset:256
	global_load_dword v40, v[16:17], off offset:1024
	global_load_dword v41, v[16:17], off offset:1280
	global_load_dword v42, v[16:17], off offset:2048
	global_load_dword v43, v[16:17], off offset:2304
	global_load_dword v44, v[16:17], off offset:3072
	global_load_dword v45, v[16:17], off offset:3328
	v_add_co_u32_e32 v16, vcc, s7, v142
	v_add_f32_e32 v2, v145, v144
	s_nop 0
	v_addc_co_u32_e32 v17, vcc, 0, v143, vcc
	global_load_dword v46, v[16:17], off
	global_load_dword v47, v[16:17], off offset:256
	global_load_dword v48, v[16:17], off offset:1024
	global_load_dword v49, v[16:17], off offset:1280
	global_load_dword v50, v[16:17], off offset:2048
	global_load_dword v51, v[16:17], off offset:2304
	global_load_dword v52, v[16:17], off offset:3072
	global_load_dword v53, v[16:17], off offset:3328
	v_add_co_u32_e32 v16, vcc, s17, v142
	s_nop 1
	v_addc_co_u32_e32 v17, vcc, 0, v143, vcc
	global_load_dword v54, v[16:17], off
	global_load_dword v55, v[16:17], off offset:256
	global_load_dword v56, v[16:17], off offset:1024
	global_load_dword v57, v[16:17], off offset:1280
	global_load_dword v58, v[16:17], off offset:2048
	global_load_dword v59, v[16:17], off offset:2304
	global_load_dword v60, v[16:17], off offset:3072
	global_load_dword v61, v[16:17], off offset:3328
	v_add_co_u32_e32 v16, vcc, s33, v142
	s_nop 1
	v_addc_co_u32_e32 v17, vcc, 0, v143, vcc
	global_load_dword v62, v[16:17], off
	global_load_dword v63, v[16:17], off offset:256
	global_load_dword v64, v[16:17], off offset:1024
	global_load_dword v65, v[16:17], off offset:1280
	global_load_dword v66, v[16:17], off offset:2048
	global_load_dword v67, v[16:17], off offset:2304
	global_load_dword v68, v[16:17], off offset:3072
	global_load_dword v69, v[16:17], off offset:3328
	v_add_co_u32_e32 v16, vcc, s34, v142
	s_nop 1
	v_addc_co_u32_e32 v17, vcc, 0, v143, vcc
	global_load_dword v70, v[16:17], off
	global_load_dword v71, v[16:17], off offset:256
	global_load_dword v72, v[16:17], off offset:1024
	global_load_dword v73, v[16:17], off offset:1280
	global_load_dword v74, v[16:17], off offset:2048
	global_load_dword v75, v[16:17], off offset:2304
	global_load_dword v76, v[16:17], off offset:3072
	global_load_dword v77, v[16:17], off offset:3328
	v_add_co_u32_e32 v16, vcc, s35, v142
	s_nop 1
	v_addc_co_u32_e32 v17, vcc, 0, v143, vcc
	global_load_dword v78, v[16:17], off
	global_load_dword v79, v[16:17], off offset:256
	global_load_dword v80, v[16:17], off offset:1024
	global_load_dword v81, v[16:17], off offset:1280
	global_load_dword v82, v[16:17], off offset:2048
	global_load_dword v83, v[16:17], off offset:2304
	global_load_dword v86, v[16:17], off offset:3072
	global_load_dword v87, v[16:17], off offset:3328
	v_add_co_u32_e32 v16, vcc, s38, v142
	s_nop 1
	v_addc_co_u32_e32 v17, vcc, 0, v143, vcc
	global_load_dword v88, v[16:17], off
	global_load_dword v89, v[16:17], off offset:256
	global_load_dword v90, v[16:17], off offset:1024
	global_load_dword v91, v[16:17], off offset:1280
	global_load_dword v92, v[16:17], off offset:2048
	global_load_dword v93, v[16:17], off offset:2304
	global_load_dword v94, v[16:17], off offset:3072
	global_load_dword v95, v[16:17], off offset:3328
	v_add_co_u32_e32 v16, vcc, s39, v142
	s_nop 1
	v_addc_co_u32_e32 v17, vcc, 0, v143, vcc
	global_load_dword v96, v[16:17], off
	global_load_dword v97, v[16:17], off offset:256
	global_load_dword v98, v[16:17], off offset:1024
	global_load_dword v99, v[16:17], off offset:1280
	global_load_dword v100, v[16:17], off offset:2048
	global_load_dword v101, v[16:17], off offset:2304
	global_load_dword v102, v[16:17], off offset:3072
	global_load_dword v103, v[16:17], off offset:3328
	v_add_co_u32_e32 v16, vcc, s40, v142
	s_nop 1
	v_addc_co_u32_e32 v17, vcc, 0, v143, vcc
	global_load_dword v104, v[16:17], off
	global_load_dword v105, v[16:17], off offset:256
	global_load_dword v106, v[16:17], off offset:1024
	global_load_dword v107, v[16:17], off offset:1280
	global_load_dword v108, v[16:17], off offset:2048
	global_load_dword v109, v[16:17], off offset:2304
	global_load_dword v110, v[16:17], off offset:3072
	global_load_dword v111, v[16:17], off offset:3328
	v_add_co_u32_e32 v16, vcc, s41, v142
	s_nop 1
	v_addc_co_u32_e32 v17, vcc, 0, v143, vcc
	global_load_dword v112, v[16:17], off
	global_load_dword v113, v[16:17], off offset:256
	global_load_dword v114, v[16:17], off offset:1024
	global_load_dword v115, v[16:17], off offset:1280
	global_load_dword v116, v[16:17], off offset:2048
	global_load_dword v117, v[16:17], off offset:2304
	global_load_dword v118, v[16:17], off offset:3072
	global_load_dword v119, v[16:17], off offset:3328
	v_add_co_u32_e32 v16, vcc, s42, v142
	s_nop 1
	v_addc_co_u32_e32 v17, vcc, 0, v143, vcc
	global_load_dword v120, v[16:17], off
	global_load_dword v121, v[16:17], off offset:256
	global_load_dword v122, v[16:17], off offset:1024
	global_load_dword v123, v[16:17], off offset:1280
	global_load_dword v124, v[16:17], off offset:2048
	global_load_dword v125, v[16:17], off offset:2304
	global_load_dword v126, v[16:17], off offset:3072
	global_load_dword v127, v[16:17], off offset:3328
	v_add_co_u32_e32 v16, vcc, s43, v142
	s_nop 1
	v_addc_co_u32_e32 v17, vcc, 0, v143, vcc
	global_load_dword v132, v[16:17], off
	global_load_dword v133, v[16:17], off offset:256
	global_load_dword v130, v[16:17], off offset:1024
	global_load_dword v131, v[16:17], off offset:1280
	global_load_dword v134, v[16:17], off offset:2048
	global_load_dword v135, v[16:17], off offset:2304
	global_load_dword v128, v[16:17], off offset:3072
	global_load_dword v129, v[16:17], off offset:3328
	v_add_co_u32_e32 v16, vcc, 0xf000, v142
	s_nop 1
	v_addc_co_u32_e32 v17, vcc, 0, v143, vcc
	global_load_dword v84, v[142:143], off offset:1024
	global_load_dword v85, v[142:143], off offset:1280
	global_load_dword v140, v[16:17], off
	global_load_dword v141, v[16:17], off offset:256
	global_load_dword v139, v[16:17], off offset:1024
	global_load_dword v138, v[16:17], off offset:1280
	global_load_dword v136, v[16:17], off offset:2048
	global_load_dword v137, v[16:17], off offset:2304
	v_pk_mov_b32 v[16:17], v[12:13], v[12:13] op_sel:[1,0]
	v_cmp_ne_u32_e32 vcc, 0, v1
	v_sub_f32_e32 v1, v144, v145
	s_and_saveexec_b64 s[10:11], vcc
	s_xor_b64 s[10:11], exec, s[10:11]
	s_cbranch_execz .LBB0_549
	v_add_co_u32_e32 v142, vcc, 0xf000, v142
	s_nop 1
	v_addc_co_u32_e32 v143, vcc, 0, v143, vcc
	global_load_dword v150, v[142:143], off offset:3072
	global_load_dword v151, v[142:143], off offset:3328
	v_add_co_u32_e32 v142, vcc, s48, v14
	s_waitcnt vmcnt(0) lgkmcnt(0)
	v_add_f32_e32 v150, v1, v150
	v_addc_co_u32_e32 v143, vcc, 0, v15, vcc
	v_add_co_u32_e32 v144, vcc, s49, v14
	v_add_f32_e32 v2, v2, v151
	s_nop 0
	v_addc_co_u32_e32 v145, vcc, 0, v15, vcc
	v_add_co_u32_e32 v146, vcc, s50, v14
	v_cvt_pk_bf16_f32 v1, v150, s0
	s_nop 0
	v_addc_co_u32_e32 v147, vcc, 0, v15, vcc
	v_add_co_u32_e32 v148, vcc, 0x17000, v14
	v_cvt_pk_bf16_f32 v151, v2, s0
	s_nop 0
	v_addc_co_u32_e32 v149, vcc, 0, v15, vcc
	v_pk_mul_f32 v[152:153], v[16:17], v[2:3] op_sel_hi:[1,0]
	global_store_short v[148:149], v3, off offset:2560
	global_store_short v[148:149], v3, off offset:2688
	global_store_short v[148:149], v1, off offset:1024
	global_store_short v[148:149], v151, off offset:1152
	v_pk_fma_f32 v[148:149], v[12:13], v[150:151], v[152:153] neg_lo:[0,0,1] neg_hi:[0,0,1]
	v_pk_fma_f32 v[150:151], v[12:13], v[150:151], v[152:153] op_sel_hi:[1,0,1]
	s_nop 0
	v_mov_b32_e32 v149, v151
	v_pk_add_f32 v[136:137], v[136:137], v[148:149]
	s_nop 0
	v_cvt_pk_bf16_f32 v1, v136, s0
	v_cvt_pk_bf16_f32 v2, v137, s0
	v_pk_mul_f32 v[148:149], v[12:13], v[136:137]
	v_pk_mul_f32 v[136:137], v[16:17], v[136:137]
	global_store_short v[142:143], v1, off offset:3584
	global_store_short v[142:143], v2, off offset:3712
	v_sub_f32_e32 v1, v148, v149
	v_add_f32_e32 v136, v136, v137
	v_add_f32_e32 v2, v139, v1
	v_add_f32_e32 v136, v138, v136
	v_cvt_pk_bf16_f32 v1, v2, s0
	v_cvt_pk_bf16_f32 v138, v136, s0
	v_pk_mul_f32 v[136:137], v[16:17], v[136:137] op_sel_hi:[1,0]
	global_store_short v[142:143], v1, off offset:2048
	global_store_short v[142:143], v138, off offset:2176
	v_pk_fma_f32 v[138:139], v[12:13], v[2:3], v[136:137] neg_lo:[0,0,1] neg_hi:[0,0,1]
	v_pk_fma_f32 v[136:137], v[12:13], v[2:3], v[136:137] op_sel_hi:[1,0,1]
	s_nop 0
	v_mov_b32_e32 v139, v137
	v_pk_add_f32 v[136:137], v[140:141], v[138:139]
	s_nop 0
	v_cvt_pk_bf16_f32 v1, v136, s0
	v_cvt_pk_bf16_f32 v2, v137, s0
	v_pk_mul_f32 v[138:139], v[12:13], v[136:137]
	v_pk_mul_f32 v[136:137], v[16:17], v[136:137]
	global_store_short v[142:143], v1, off offset:512
	global_store_short v[142:143], v2, off offset:640
	v_sub_f32_e32 v1, v138, v139
	v_add_f32_e32 v136, v136, v137
	v_add_f32_e32 v2, v128, v1
	v_add_f32_e32 v128, v129, v136
	v_cvt_pk_bf16_f32 v1, v2, s0
	v_cvt_pk_bf16_f32 v136, v128, s0
	v_pk_mul_f32 v[128:129], v[16:17], v[128:129] op_sel_hi:[1,0]
	global_store_short v[144:145], v1, off offset:3072
	global_store_short v[144:145], v136, off offset:3200
	v_pk_fma_f32 v[136:137], v[12:13], v[2:3], v[128:129] neg_lo:[0,0,1] neg_hi:[0,0,1]
	v_pk_fma_f32 v[128:129], v[12:13], v[2:3], v[128:129] op_sel_hi:[1,0,1]
	s_nop 0
	v_mov_b32_e32 v137, v129
	v_pk_add_f32 v[128:129], v[134:135], v[136:137]
	s_nop 0
	v_cvt_pk_bf16_f32 v1, v128, s0
	v_cvt_pk_bf16_f32 v2, v129, s0
	v_pk_mul_f32 v[134:135], v[12:13], v[128:129]
	v_pk_mul_f32 v[128:129], v[16:17], v[128:129]
	global_store_short v[144:145], v1, off offset:1536
	global_store_short v[144:145], v2, off offset:1664
	v_sub_f32_e32 v1, v134, v135
	v_add_f32_e32 v128, v128, v129
	v_add_f32_e32 v2, v130, v1
	v_add_f32_e32 v128, v131, v128
	v_cvt_pk_bf16_f32 v1, v2, s0
	v_cvt_pk_bf16_f32 v130, v128, s0
	v_pk_mul_f32 v[128:129], v[16:17], v[128:129] op_sel_hi:[1,0]
	global_store_short v[144:145], v1, off
	global_store_short v[144:145], v130, off offset:128
	v_pk_fma_f32 v[130:131], v[12:13], v[2:3], v[128:129] neg_lo:[0,0,1] neg_hi:[0,0,1]
	v_pk_fma_f32 v[128:129], v[12:13], v[2:3], v[128:129] op_sel_hi:[1,0,1]
	s_nop 0
	v_mov_b32_e32 v131, v129
	v_pk_add_f32 v[128:129], v[132:133], v[130:131]
	s_nop 0
	v_cvt_pk_bf16_f32 v1, v128, s0
	v_cvt_pk_bf16_f32 v2, v129, s0
	v_pk_mul_f32 v[130:131], v[12:13], v[128:129]
	v_pk_mul_f32 v[128:129], v[16:17], v[128:129]
	global_store_short v[146:147], v1, off offset:2560
	global_store_short v[146:147], v2, off offset:2688
	v_sub_f32_e32 v1, v130, v131
	v_add_f32_e32 v128, v128, v129
	v_add_f32_e32 v2, v126, v1
	v_add_f32_e32 v126, v127, v128
	v_cvt_pk_bf16_f32 v1, v2, s0
	v_cvt_pk_bf16_f32 v128, v126, s0
	v_pk_mul_f32 v[126:127], v[16:17], v[126:127] op_sel_hi:[1,0]
	global_store_short v[146:147], v1, off offset:1024
	global_store_short v[146:147], v128, off offset:1152
	v_pk_fma_f32 v[128:129], v[12:13], v[2:3], v[126:127] neg_lo:[0,0,1] neg_hi:[0,0,1]
	v_pk_fma_f32 v[126:127], v[12:13], v[2:3], v[126:127] op_sel_hi:[1,0,1]
	s_nop 0
	v_mov_b32_e32 v129, v127
	v_pk_add_f32 v[124:125], v[124:125], v[128:129]
	v_add_co_u32_e32 v126, vcc, s51, v14
	v_cvt_pk_bf16_f32 v1, v124, s0
	s_nop 0
	v_addc_co_u32_e32 v127, vcc, 0, v15, vcc
	global_store_short v[126:127], v1, off offset:3584
	v_cvt_pk_bf16_f32 v1, v125, s0
	v_pk_mul_f32 v[128:129], v[12:13], v[124:125]
	global_store_short v[126:127], v1, off offset:3712
	v_sub_f32_e32 v1, v128, v129
	v_pk_mul_f32 v[124:125], v[16:17], v[124:125]
	v_add_f32_e32 v2, v122, v1
	v_add_f32_e32 v1, v124, v125
	v_add_f32_e32 v122, v123, v1
	v_cvt_pk_bf16_f32 v1, v2, s0
	global_store_short v[126:127], v1, off offset:2048
	v_cvt_pk_bf16_f32 v1, v122, s0
	v_pk_mul_f32 v[122:123], v[16:17], v[122:123] op_sel_hi:[1,0]
	global_store_short v[126:127], v1, off offset:2176
	v_pk_fma_f32 v[124:125], v[12:13], v[2:3], v[122:123] neg_lo:[0,0,1] neg_hi:[0,0,1]
	v_pk_fma_f32 v[122:123], v[12:13], v[2:3], v[122:123] op_sel_hi:[1,0,1]
	s_nop 0
	v_mov_b32_e32 v125, v123
	v_pk_add_f32 v[120:121], v[120:121], v[124:125]
	s_nop 0
	v_cvt_pk_bf16_f32 v1, v120, s0
	global_store_short v[126:127], v1, off offset:512
	v_cvt_pk_bf16_f32 v1, v121, s0
	v_pk_mul_f32 v[122:123], v[12:13], v[120:121]
	global_store_short v[126:127], v1, off offset:640
	v_sub_f32_e32 v1, v122, v123
	v_pk_mul_f32 v[120:121], v[16:17], v[120:121]
	v_add_f32_e32 v2, v118, v1
	v_add_f32_e32 v1, v120, v121
	v_add_co_u32_e32 v120, vcc, s54, v14
	v_add_f32_e32 v118, v119, v1
	v_cvt_pk_bf16_f32 v1, v2, s0
	v_addc_co_u32_e32 v121, vcc, 0, v15, vcc
	global_store_short v[120:121], v1, off offset:3072
	v_cvt_pk_bf16_f32 v1, v118, s0
	v_pk_mul_f32 v[118:119], v[16:17], v[118:119] op_sel_hi:[1,0]
	global_store_short v[120:121], v1, off offset:3200
	v_pk_fma_f32 v[122:123], v[12:13], v[2:3], v[118:119] neg_lo:[0,0,1] neg_hi:[0,0,1]
	v_pk_fma_f32 v[118:119], v[12:13], v[2:3], v[118:119] op_sel_hi:[1,0,1]
	s_nop 0
	v_mov_b32_e32 v123, v119
	v_pk_add_f32 v[116:117], v[116:117], v[122:123]
	s_nop 0
	v_cvt_pk_bf16_f32 v1, v116, s0
	global_store_short v[120:121], v1, off offset:1536
	v_cvt_pk_bf16_f32 v1, v117, s0
	v_pk_mul_f32 v[118:119], v[12:13], v[116:117]
	global_store_short v[120:121], v1, off offset:1664
	v_sub_f32_e32 v1, v118, v119
	v_pk_mul_f32 v[116:117], v[16:17], v[116:117]
	v_add_f32_e32 v2, v114, v1
	v_add_f32_e32 v1, v116, v117
	v_add_f32_e32 v114, v115, v1
	v_cvt_pk_bf16_f32 v1, v2, s0
	global_store_short v[120:121], v1, off
	v_cvt_pk_bf16_f32 v1, v114, s0
	v_pk_mul_f32 v[114:115], v[16:17], v[114:115] op_sel_hi:[1,0]
	global_store_short v[120:121], v1, off offset:128
	v_pk_fma_f32 v[116:117], v[12:13], v[2:3], v[114:115] neg_lo:[0,0,1] neg_hi:[0,0,1]
	v_pk_fma_f32 v[114:115], v[12:13], v[2:3], v[114:115] op_sel_hi:[1,0,1]
	s_nop 0
	v_mov_b32_e32 v117, v115
	v_pk_add_f32 v[112:113], v[112:113], v[116:117]
	v_add_co_u32_e32 v114, vcc, s55, v14
	v_cvt_pk_bf16_f32 v1, v112, s0
	s_nop 0
	v_addc_co_u32_e32 v115, vcc, 0, v15, vcc
	global_store_short v[114:115], v1, off offset:2560
	v_cvt_pk_bf16_f32 v1, v113, s0
	v_pk_mul_f32 v[116:117], v[12:13], v[112:113]
	global_store_short v[114:115], v1, off offset:2688
	v_sub_f32_e32 v1, v116, v117
	v_pk_mul_f32 v[112:113], v[16:17], v[112:113]
	v_add_f32_e32 v2, v110, v1
	v_add_f32_e32 v1, v112, v113
	v_add_f32_e32 v110, v111, v1
	v_cvt_pk_bf16_f32 v1, v2, s0
	global_store_short v[114:115], v1, off offset:1024
	v_cvt_pk_bf16_f32 v1, v110, s0
	v_pk_mul_f32 v[110:111], v[16:17], v[110:111] op_sel_hi:[1,0]
	global_store_short v[114:115], v1, off offset:1152
	v_pk_fma_f32 v[112:113], v[12:13], v[2:3], v[110:111] neg_lo:[0,0,1] neg_hi:[0,0,1]
	v_pk_fma_f32 v[110:111], v[12:13], v[2:3], v[110:111] op_sel_hi:[1,0,1]
	s_nop 0
	v_mov_b32_e32 v113, v111
	v_pk_add_f32 v[108:109], v[108:109], v[112:113]
	v_add_co_u32_e32 v110, vcc, s2, v14
	v_cvt_pk_bf16_f32 v1, v108, s0
	s_nop 0
	v_addc_co_u32_e32 v111, vcc, 0, v15, vcc
	global_store_short v[110:111], v1, off offset:3584
	v_cvt_pk_bf16_f32 v1, v109, s0
	v_pk_mul_f32 v[112:113], v[12:13], v[108:109]
	global_store_short v[110:111], v1, off offset:3712
	v_sub_f32_e32 v1, v112, v113
	v_pk_mul_f32 v[108:109], v[16:17], v[108:109]
	v_add_f32_e32 v2, v106, v1
	v_add_f32_e32 v1, v108, v109
	v_add_f32_e32 v106, v107, v1
	v_cvt_pk_bf16_f32 v1, v2, s0
	global_store_short v[110:111], v1, off offset:2048
	v_cvt_pk_bf16_f32 v1, v106, s0
	v_pk_mul_f32 v[106:107], v[16:17], v[106:107] op_sel_hi:[1,0]
	global_store_short v[110:111], v1, off offset:2176
	v_pk_fma_f32 v[108:109], v[12:13], v[2:3], v[106:107] neg_lo:[0,0,1] neg_hi:[0,0,1]
	v_pk_fma_f32 v[106:107], v[12:13], v[2:3], v[106:107] op_sel_hi:[1,0,1]
	s_nop 0
	v_mov_b32_e32 v109, v107
	v_pk_add_f32 v[104:105], v[104:105], v[108:109]
	s_nop 0
	v_cvt_pk_bf16_f32 v1, v104, s0
	global_store_short v[110:111], v1, off offset:512
	v_cvt_pk_bf16_f32 v1, v105, s0
	v_pk_mul_f32 v[106:107], v[12:13], v[104:105]
	global_store_short v[110:111], v1, off offset:640
	v_sub_f32_e32 v1, v106, v107
	v_pk_mul_f32 v[104:105], v[16:17], v[104:105]
	v_add_f32_e32 v2, v102, v1
	v_add_f32_e32 v1, v104, v105
	v_add_co_u32_e32 v104, vcc, s44, v14
	v_add_f32_e32 v102, v103, v1
	v_cvt_pk_bf16_f32 v1, v2, s0
	v_addc_co_u32_e32 v105, vcc, 0, v15, vcc
	global_store_short v[104:105], v1, off offset:3072
	v_cvt_pk_bf16_f32 v1, v102, s0
	v_pk_mul_f32 v[102:103], v[16:17], v[102:103] op_sel_hi:[1,0]
	global_store_short v[104:105], v1, off offset:3200
	v_pk_fma_f32 v[106:107], v[12:13], v[2:3], v[102:103] neg_lo:[0,0,1] neg_hi:[0,0,1]
	v_pk_fma_f32 v[102:103], v[12:13], v[2:3], v[102:103] op_sel_hi:[1,0,1]
	s_nop 0
	v_mov_b32_e32 v107, v103
	v_pk_add_f32 v[100:101], v[100:101], v[106:107]
	s_nop 0
	v_cvt_pk_bf16_f32 v1, v100, s0
	global_store_short v[104:105], v1, off offset:1536
	v_cvt_pk_bf16_f32 v1, v101, s0
	v_pk_mul_f32 v[102:103], v[12:13], v[100:101]
	global_store_short v[104:105], v1, off offset:1664
	v_sub_f32_e32 v1, v102, v103
	v_pk_mul_f32 v[100:101], v[16:17], v[100:101]
	v_add_f32_e32 v2, v98, v1
	v_add_f32_e32 v1, v100, v101
	v_add_f32_e32 v98, v99, v1
	v_cvt_pk_bf16_f32 v1, v2, s0
	global_store_short v[104:105], v1, off
	v_cvt_pk_bf16_f32 v1, v98, s0
	v_pk_mul_f32 v[98:99], v[16:17], v[98:99] op_sel_hi:[1,0]
	global_store_short v[104:105], v1, off offset:128
	v_pk_fma_f32 v[100:101], v[12:13], v[2:3], v[98:99] neg_lo:[0,0,1] neg_hi:[0,0,1]
	v_pk_fma_f32 v[98:99], v[12:13], v[2:3], v[98:99] op_sel_hi:[1,0,1]
	s_nop 0
	v_mov_b32_e32 v101, v99
	v_pk_add_f32 v[96:97], v[96:97], v[100:101]
	v_add_co_u32_e32 v98, vcc, s43, v14
	v_cvt_pk_bf16_f32 v1, v96, s0
	s_nop 0
	v_addc_co_u32_e32 v99, vcc, 0, v15, vcc
	global_store_short v[98:99], v1, off offset:2560
	v_cvt_pk_bf16_f32 v1, v97, s0
	v_pk_mul_f32 v[100:101], v[12:13], v[96:97]
	global_store_short v[98:99], v1, off offset:2688
	v_sub_f32_e32 v1, v100, v101
	v_pk_mul_f32 v[96:97], v[16:17], v[96:97]
	v_add_f32_e32 v2, v94, v1
	v_add_f32_e32 v1, v96, v97
	v_add_f32_e32 v94, v95, v1
	v_cvt_pk_bf16_f32 v1, v2, s0
	global_store_short v[98:99], v1, off offset:1024
	v_cvt_pk_bf16_f32 v1, v94, s0
	v_pk_mul_f32 v[94:95], v[16:17], v[94:95] op_sel_hi:[1,0]
	global_store_short v[98:99], v1, off offset:1152
	v_pk_fma_f32 v[96:97], v[12:13], v[2:3], v[94:95] neg_lo:[0,0,1] neg_hi:[0,0,1]
	v_pk_fma_f32 v[94:95], v[12:13], v[2:3], v[94:95] op_sel_hi:[1,0,1]
	s_nop 0
	v_mov_b32_e32 v97, v95
	v_pk_add_f32 v[92:93], v[92:93], v[96:97]
	v_add_co_u32_e32 v94, vcc, s42, v14
	v_cvt_pk_bf16_f32 v1, v92, s0
	s_nop 0
	v_addc_co_u32_e32 v95, vcc, 0, v15, vcc
	global_store_short v[94:95], v1, off offset:3584
	v_cvt_pk_bf16_f32 v1, v93, s0
	v_pk_mul_f32 v[96:97], v[12:13], v[92:93]
	global_store_short v[94:95], v1, off offset:3712
	v_sub_f32_e32 v1, v96, v97
	v_pk_mul_f32 v[92:93], v[16:17], v[92:93]
	v_add_f32_e32 v2, v90, v1
	v_add_f32_e32 v1, v92, v93
	v_add_f32_e32 v90, v91, v1
	v_cvt_pk_bf16_f32 v1, v2, s0
	global_store_short v[94:95], v1, off offset:2048
	v_cvt_pk_bf16_f32 v1, v90, s0
	v_pk_mul_f32 v[90:91], v[16:17], v[90:91] op_sel_hi:[1,0]
	global_store_short v[94:95], v1, off offset:2176
	v_pk_fma_f32 v[92:93], v[12:13], v[2:3], v[90:91] neg_lo:[0,0,1] neg_hi:[0,0,1]
	v_pk_fma_f32 v[90:91], v[12:13], v[2:3], v[90:91] op_sel_hi:[1,0,1]
	s_nop 0
	v_mov_b32_e32 v93, v91
	v_pk_add_f32 v[88:89], v[88:89], v[92:93]
	s_nop 0
	v_cvt_pk_bf16_f32 v1, v88, s0
	global_store_short v[94:95], v1, off offset:512
	v_cvt_pk_bf16_f32 v1, v89, s0
	v_pk_mul_f32 v[90:91], v[12:13], v[88:89]
	global_store_short v[94:95], v1, off offset:640
	v_sub_f32_e32 v1, v90, v91
	v_pk_mul_f32 v[88:89], v[16:17], v[88:89]
	v_add_f32_e32 v2, v86, v1
	v_add_f32_e32 v1, v88, v89
	v_add_co_u32_e32 v88, vcc, s41, v14
	v_add_f32_e32 v86, v87, v1
	v_cvt_pk_bf16_f32 v1, v2, s0
	v_addc_co_u32_e32 v89, vcc, 0, v15, vcc
	global_store_short v[88:89], v1, off offset:3072
	v_cvt_pk_bf16_f32 v1, v86, s0
	v_pk_mul_f32 v[86:87], v[16:17], v[86:87] op_sel_hi:[1,0]
	global_store_short v[88:89], v1, off offset:3200
	v_pk_fma_f32 v[90:91], v[12:13], v[2:3], v[86:87] neg_lo:[0,0,1] neg_hi:[0,0,1]
	v_pk_fma_f32 v[86:87], v[12:13], v[2:3], v[86:87] op_sel_hi:[1,0,1]
	s_nop 0
	v_mov_b32_e32 v91, v87
	v_pk_add_f32 v[82:83], v[82:83], v[90:91]
	s_nop 0
	v_cvt_pk_bf16_f32 v1, v82, s0
	global_store_short v[88:89], v1, off offset:1536
	v_cvt_pk_bf16_f32 v1, v83, s0
	v_pk_mul_f32 v[86:87], v[12:13], v[82:83]
	global_store_short v[88:89], v1, off offset:1664
	v_sub_f32_e32 v1, v86, v87
	v_pk_mul_f32 v[82:83], v[16:17], v[82:83]
	v_add_f32_e32 v2, v80, v1
	v_add_f32_e32 v1, v82, v83
	v_add_f32_e32 v80, v81, v1
	v_cvt_pk_bf16_f32 v1, v2, s0
	global_store_short v[88:89], v1, off
	v_cvt_pk_bf16_f32 v1, v80, s0
	v_pk_mul_f32 v[80:81], v[16:17], v[80:81] op_sel_hi:[1,0]
	global_store_short v[88:89], v1, off offset:128
	v_pk_fma_f32 v[82:83], v[12:13], v[2:3], v[80:81] neg_lo:[0,0,1] neg_hi:[0,0,1]
	v_pk_fma_f32 v[80:81], v[12:13], v[2:3], v[80:81] op_sel_hi:[1,0,1]
	s_nop 0
	v_mov_b32_e32 v83, v81
	v_pk_add_f32 v[78:79], v[78:79], v[82:83]
	v_add_co_u32_e32 v80, vcc, s40, v14
	v_cvt_pk_bf16_f32 v1, v78, s0
	s_nop 0
	v_addc_co_u32_e32 v81, vcc, 0, v15, vcc
	global_store_short v[80:81], v1, off offset:2560
	v_cvt_pk_bf16_f32 v1, v79, s0
	v_pk_mul_f32 v[82:83], v[12:13], v[78:79]
	global_store_short v[80:81], v1, off offset:2688
	v_sub_f32_e32 v1, v82, v83
	v_pk_mul_f32 v[78:79], v[16:17], v[78:79]
	v_add_f32_e32 v2, v76, v1
	v_add_f32_e32 v1, v78, v79
	v_add_f32_e32 v76, v77, v1
	v_cvt_pk_bf16_f32 v1, v2, s0
	global_store_short v[80:81], v1, off offset:1024
	v_cvt_pk_bf16_f32 v1, v76, s0
	v_pk_mul_f32 v[76:77], v[16:17], v[76:77] op_sel_hi:[1,0]
	global_store_short v[80:81], v1, off offset:1152
	v_pk_fma_f32 v[78:79], v[12:13], v[2:3], v[76:77] neg_lo:[0,0,1] neg_hi:[0,0,1]
	v_pk_fma_f32 v[76:77], v[12:13], v[2:3], v[76:77] op_sel_hi:[1,0,1]
	s_nop 0
	v_mov_b32_e32 v79, v77
	v_pk_add_f32 v[74:75], v[74:75], v[78:79]
	v_add_co_u32_e32 v76, vcc, s39, v14
	v_cvt_pk_bf16_f32 v1, v74, s0
	s_nop 0
	v_addc_co_u32_e32 v77, vcc, 0, v15, vcc
	global_store_short v[76:77], v1, off offset:3584
	v_cvt_pk_bf16_f32 v1, v75, s0
	v_pk_mul_f32 v[78:79], v[12:13], v[74:75]
	global_store_short v[76:77], v1, off offset:3712
	v_sub_f32_e32 v1, v78, v79
	v_pk_mul_f32 v[74:75], v[16:17], v[74:75]
	v_add_f32_e32 v2, v72, v1
	v_add_f32_e32 v1, v74, v75
	v_add_f32_e32 v72, v73, v1
	v_cvt_pk_bf16_f32 v1, v2, s0
	global_store_short v[76:77], v1, off offset:2048
	v_cvt_pk_bf16_f32 v1, v72, s0
	v_pk_mul_f32 v[72:73], v[16:17], v[72:73] op_sel_hi:[1,0]
	global_store_short v[76:77], v1, off offset:2176
	v_pk_fma_f32 v[74:75], v[12:13], v[2:3], v[72:73] neg_lo:[0,0,1] neg_hi:[0,0,1]
	v_pk_fma_f32 v[72:73], v[12:13], v[2:3], v[72:73] op_sel_hi:[1,0,1]
	s_nop 0
	v_mov_b32_e32 v75, v73
	v_pk_add_f32 v[70:71], v[70:71], v[74:75]
	s_nop 0
	v_cvt_pk_bf16_f32 v1, v70, s0
	global_store_short v[76:77], v1, off offset:512
	v_cvt_pk_bf16_f32 v1, v71, s0
	v_pk_mul_f32 v[72:73], v[12:13], v[70:71]
	global_store_short v[76:77], v1, off offset:640
	v_sub_f32_e32 v1, v72, v73
	v_pk_mul_f32 v[70:71], v[16:17], v[70:71]
	v_add_f32_e32 v2, v68, v1
	v_add_f32_e32 v1, v70, v71
	v_add_co_u32_e32 v70, vcc, s38, v14
	v_add_f32_e32 v68, v69, v1
	v_cvt_pk_bf16_f32 v1, v2, s0
	v_addc_co_u32_e32 v71, vcc, 0, v15, vcc
	global_store_short v[70:71], v1, off offset:3072
	v_cvt_pk_bf16_f32 v1, v68, s0
	v_pk_mul_f32 v[68:69], v[16:17], v[68:69] op_sel_hi:[1,0]
	global_store_short v[70:71], v1, off offset:3200
	v_pk_fma_f32 v[72:73], v[12:13], v[2:3], v[68:69] neg_lo:[0,0,1] neg_hi:[0,0,1]
	v_pk_fma_f32 v[68:69], v[12:13], v[2:3], v[68:69] op_sel_hi:[1,0,1]
	s_nop 0
	v_mov_b32_e32 v73, v69
	v_pk_add_f32 v[66:67], v[66:67], v[72:73]
	s_nop 0
	v_cvt_pk_bf16_f32 v1, v66, s0
	global_store_short v[70:71], v1, off offset:1536
	v_cvt_pk_bf16_f32 v1, v67, s0
	v_pk_mul_f32 v[68:69], v[12:13], v[66:67]
	global_store_short v[70:71], v1, off offset:1664
	v_sub_f32_e32 v1, v68, v69
	v_pk_mul_f32 v[66:67], v[16:17], v[66:67]
	v_add_f32_e32 v2, v64, v1
	v_add_f32_e32 v1, v66, v67
	v_add_f32_e32 v64, v65, v1
	v_cvt_pk_bf16_f32 v1, v2, s0
	global_store_short v[70:71], v1, off
	v_cvt_pk_bf16_f32 v1, v64, s0
	v_pk_mul_f32 v[64:65], v[16:17], v[64:65] op_sel_hi:[1,0]
	global_store_short v[70:71], v1, off offset:128
	v_pk_fma_f32 v[66:67], v[12:13], v[2:3], v[64:65] neg_lo:[0,0,1] neg_hi:[0,0,1]
	v_pk_fma_f32 v[64:65], v[12:13], v[2:3], v[64:65] op_sel_hi:[1,0,1]
	s_nop 0
	v_mov_b32_e32 v67, v65
	v_pk_add_f32 v[62:63], v[62:63], v[66:67]
	v_add_co_u32_e32 v64, vcc, s35, v14
	v_cvt_pk_bf16_f32 v1, v62, s0
	s_nop 0
	v_addc_co_u32_e32 v65, vcc, 0, v15, vcc
	global_store_short v[64:65], v1, off offset:2560
	v_cvt_pk_bf16_f32 v1, v63, s0
	v_pk_mul_f32 v[66:67], v[12:13], v[62:63]
	global_store_short v[64:65], v1, off offset:2688
	v_sub_f32_e32 v1, v66, v67
	v_pk_mul_f32 v[62:63], v[16:17], v[62:63]
	v_add_f32_e32 v2, v60, v1
	v_add_f32_e32 v1, v62, v63
	v_add_f32_e32 v60, v61, v1
	v_cvt_pk_bf16_f32 v1, v2, s0
	global_store_short v[64:65], v1, off offset:1024
	v_cvt_pk_bf16_f32 v1, v60, s0
	v_pk_mul_f32 v[60:61], v[16:17], v[60:61] op_sel_hi:[1,0]
	global_store_short v[64:65], v1, off offset:1152
	v_pk_fma_f32 v[62:63], v[12:13], v[2:3], v[60:61] neg_lo:[0,0,1] neg_hi:[0,0,1]
	v_pk_fma_f32 v[60:61], v[12:13], v[2:3], v[60:61] op_sel_hi:[1,0,1]
	s_nop 0
	v_mov_b32_e32 v63, v61
	v_pk_add_f32 v[58:59], v[58:59], v[62:63]
	v_add_co_u32_e32 v60, vcc, s34, v14
	v_cvt_pk_bf16_f32 v1, v58, s0
	s_nop 0
	v_addc_co_u32_e32 v61, vcc, 0, v15, vcc
	global_store_short v[60:61], v1, off offset:3584
	v_cvt_pk_bf16_f32 v1, v59, s0
	v_pk_mul_f32 v[62:63], v[12:13], v[58:59]
	global_store_short v[60:61], v1, off offset:3712
	v_sub_f32_e32 v1, v62, v63
	v_pk_mul_f32 v[58:59], v[16:17], v[58:59]
	v_add_f32_e32 v2, v56, v1
	v_add_f32_e32 v1, v58, v59
	v_add_f32_e32 v56, v57, v1
	v_cvt_pk_bf16_f32 v1, v2, s0
	global_store_short v[60:61], v1, off offset:2048
	v_cvt_pk_bf16_f32 v1, v56, s0
	v_pk_mul_f32 v[56:57], v[16:17], v[56:57] op_sel_hi:[1,0]
	global_store_short v[60:61], v1, off offset:2176
	v_pk_fma_f32 v[58:59], v[12:13], v[2:3], v[56:57] neg_lo:[0,0,1] neg_hi:[0,0,1]
	v_pk_fma_f32 v[56:57], v[12:13], v[2:3], v[56:57] op_sel_hi:[1,0,1]
	s_nop 0
	v_mov_b32_e32 v59, v57
	v_pk_add_f32 v[54:55], v[54:55], v[58:59]
	s_nop 0
	v_cvt_pk_bf16_f32 v1, v54, s0
	global_store_short v[60:61], v1, off offset:512
	v_cvt_pk_bf16_f32 v1, v55, s0
	v_pk_mul_f32 v[56:57], v[12:13], v[54:55]
	global_store_short v[60:61], v1, off offset:640
	v_sub_f32_e32 v1, v56, v57
	v_pk_mul_f32 v[54:55], v[16:17], v[54:55]
	v_add_f32_e32 v2, v52, v1
	v_add_f32_e32 v1, v54, v55
	v_add_co_u32_e32 v54, vcc, s33, v14
	v_add_f32_e32 v52, v53, v1
	v_cvt_pk_bf16_f32 v1, v2, s0
	v_addc_co_u32_e32 v55, vcc, 0, v15, vcc
	global_store_short v[54:55], v1, off offset:3072
	v_cvt_pk_bf16_f32 v1, v52, s0
	v_pk_mul_f32 v[52:53], v[16:17], v[52:53] op_sel_hi:[1,0]
	global_store_short v[54:55], v1, off offset:3200
	v_pk_fma_f32 v[56:57], v[12:13], v[2:3], v[52:53] neg_lo:[0,0,1] neg_hi:[0,0,1]
	v_pk_fma_f32 v[52:53], v[12:13], v[2:3], v[52:53] op_sel_hi:[1,0,1]
	s_nop 0
	v_mov_b32_e32 v57, v53
	v_pk_add_f32 v[50:51], v[50:51], v[56:57]
	s_nop 0
	v_cvt_pk_bf16_f32 v1, v50, s0
	global_store_short v[54:55], v1, off offset:1536
	v_cvt_pk_bf16_f32 v1, v51, s0
	v_pk_mul_f32 v[52:53], v[12:13], v[50:51]
	global_store_short v[54:55], v1, off offset:1664
	v_sub_f32_e32 v1, v52, v53
	v_pk_mul_f32 v[50:51], v[16:17], v[50:51]
	v_add_f32_e32 v2, v48, v1
	v_add_f32_e32 v1, v50, v51
	v_add_f32_e32 v48, v49, v1
	v_cvt_pk_bf16_f32 v1, v2, s0
	global_store_short v[54:55], v1, off
	v_cvt_pk_bf16_f32 v1, v48, s0
	v_pk_mul_f32 v[48:49], v[16:17], v[48:49] op_sel_hi:[1,0]
	global_store_short v[54:55], v1, off offset:128
	v_pk_fma_f32 v[50:51], v[12:13], v[2:3], v[48:49] neg_lo:[0,0,1] neg_hi:[0,0,1]
	v_pk_fma_f32 v[48:49], v[12:13], v[2:3], v[48:49] op_sel_hi:[1,0,1]
	s_nop 0
	v_mov_b32_e32 v51, v49
	v_pk_add_f32 v[46:47], v[46:47], v[50:51]
	v_add_co_u32_e32 v48, vcc, s17, v14
	v_cvt_pk_bf16_f32 v1, v46, s0
	s_nop 0
	v_addc_co_u32_e32 v49, vcc, 0, v15, vcc
	global_store_short v[48:49], v1, off offset:2560
	v_cvt_pk_bf16_f32 v1, v47, s0
	v_pk_mul_f32 v[50:51], v[12:13], v[46:47]
	global_store_short v[48:49], v1, off offset:2688
	v_sub_f32_e32 v1, v50, v51
	v_pk_mul_f32 v[46:47], v[16:17], v[46:47]
	v_add_f32_e32 v2, v44, v1
	v_add_f32_e32 v1, v46, v47
	v_add_f32_e32 v44, v45, v1
	v_cvt_pk_bf16_f32 v1, v2, s0
	global_store_short v[48:49], v1, off offset:1024
	v_cvt_pk_bf16_f32 v1, v44, s0
	v_pk_mul_f32 v[44:45], v[16:17], v[44:45] op_sel_hi:[1,0]
	global_store_short v[48:49], v1, off offset:1152
	v_pk_fma_f32 v[46:47], v[12:13], v[2:3], v[44:45] neg_lo:[0,0,1] neg_hi:[0,0,1]
	v_pk_fma_f32 v[44:45], v[12:13], v[2:3], v[44:45] op_sel_hi:[1,0,1]
	s_nop 0
	v_mov_b32_e32 v47, v45
	v_pk_add_f32 v[42:43], v[42:43], v[46:47]
	v_add_co_u32_e32 v44, vcc, s7, v14
	v_cvt_pk_bf16_f32 v1, v42, s0
	s_nop 0
	v_addc_co_u32_e32 v45, vcc, 0, v15, vcc
	global_store_short v[44:45], v1, off offset:3584
	v_cvt_pk_bf16_f32 v1, v43, s0
	v_pk_mul_f32 v[46:47], v[12:13], v[42:43]
	global_store_short v[44:45], v1, off offset:3712
	v_sub_f32_e32 v1, v46, v47
	v_pk_mul_f32 v[42:43], v[16:17], v[42:43]
	v_add_f32_e32 v2, v40, v1
	v_add_f32_e32 v1, v42, v43
	v_add_f32_e32 v40, v41, v1
	v_cvt_pk_bf16_f32 v1, v2, s0
	global_store_short v[44:45], v1, off offset:2048
	v_cvt_pk_bf16_f32 v1, v40, s0
	v_pk_mul_f32 v[40:41], v[16:17], v[40:41] op_sel_hi:[1,0]
	global_store_short v[44:45], v1, off offset:2176
	v_pk_fma_f32 v[42:43], v[12:13], v[2:3], v[40:41] neg_lo:[0,0,1] neg_hi:[0,0,1]
	v_pk_fma_f32 v[40:41], v[12:13], v[2:3], v[40:41] op_sel_hi:[1,0,1]
	s_nop 0
	v_mov_b32_e32 v43, v41
	v_pk_add_f32 v[38:39], v[38:39], v[42:43]
	s_nop 0
	v_cvt_pk_bf16_f32 v1, v38, s0
	global_store_short v[44:45], v1, off offset:512
	v_cvt_pk_bf16_f32 v1, v39, s0
	v_pk_mul_f32 v[40:41], v[12:13], v[38:39]
	global_store_short v[44:45], v1, off offset:640
	v_sub_f32_e32 v1, v40, v41
	v_pk_mul_f32 v[38:39], v[16:17], v[38:39]
	v_add_f32_e32 v2, v36, v1
	v_add_f32_e32 v1, v38, v39
	v_add_co_u32_e32 v38, vcc, s16, v14
	v_add_f32_e32 v36, v37, v1
	v_cvt_pk_bf16_f32 v1, v2, s0
	v_addc_co_u32_e32 v39, vcc, 0, v15, vcc
	global_store_short v[38:39], v1, off offset:3072
	v_cvt_pk_bf16_f32 v1, v36, s0
	v_pk_mul_f32 v[36:37], v[16:17], v[36:37] op_sel_hi:[1,0]
	global_store_short v[38:39], v1, off offset:3200
	v_pk_fma_f32 v[40:41], v[12:13], v[2:3], v[36:37] neg_lo:[0,0,1] neg_hi:[0,0,1]
	v_pk_fma_f32 v[36:37], v[12:13], v[2:3], v[36:37] op_sel_hi:[1,0,1]
	s_nop 0
	v_mov_b32_e32 v41, v37
	v_pk_add_f32 v[34:35], v[34:35], v[40:41]
	s_nop 0
	v_cvt_pk_bf16_f32 v1, v34, s0
	global_store_short v[38:39], v1, off offset:1536
	v_cvt_pk_bf16_f32 v1, v35, s0
	v_pk_mul_f32 v[36:37], v[12:13], v[34:35]
	global_store_short v[38:39], v1, off offset:1664
	v_sub_f32_e32 v1, v36, v37
	v_pk_mul_f32 v[34:35], v[16:17], v[34:35]
	v_add_f32_e32 v2, v32, v1
	v_add_f32_e32 v1, v34, v35
	v_add_f32_e32 v32, v33, v1
	v_cvt_pk_bf16_f32 v1, v2, s0
	global_store_short v[38:39], v1, off
	v_cvt_pk_bf16_f32 v1, v32, s0
	v_pk_mul_f32 v[32:33], v[16:17], v[32:33] op_sel_hi:[1,0]
	global_store_short v[38:39], v1, off offset:128
	v_pk_fma_f32 v[34:35], v[12:13], v[2:3], v[32:33] neg_lo:[0,0,1] neg_hi:[0,0,1]
	v_pk_fma_f32 v[32:33], v[12:13], v[2:3], v[32:33] op_sel_hi:[1,0,1]
	s_nop 0
	v_mov_b32_e32 v35, v33
	v_pk_add_f32 v[30:31], v[30:31], v[34:35]
	v_add_co_u32_e32 v32, vcc, s15, v14
	v_cvt_pk_bf16_f32 v1, v30, s0
	s_nop 0
	v_addc_co_u32_e32 v33, vcc, 0, v15, vcc
	global_store_short v[32:33], v1, off offset:2560
	v_cvt_pk_bf16_f32 v1, v31, s0
	v_pk_mul_f32 v[34:35], v[12:13], v[30:31]
	global_store_short v[32:33], v1, off offset:2688
	v_sub_f32_e32 v1, v34, v35
	v_pk_mul_f32 v[30:31], v[16:17], v[30:31]
	v_add_f32_e32 v2, v28, v1
	v_add_f32_e32 v1, v30, v31
	v_add_f32_e32 v28, v29, v1
	v_cvt_pk_bf16_f32 v1, v2, s0
	global_store_short v[32:33], v1, off offset:1024
	v_cvt_pk_bf16_f32 v1, v28, s0
	v_pk_mul_f32 v[28:29], v[16:17], v[28:29] op_sel_hi:[1,0]
	global_store_short v[32:33], v1, off offset:1152
	v_pk_fma_f32 v[30:31], v[12:13], v[2:3], v[28:29] neg_lo:[0,0,1] neg_hi:[0,0,1]
	v_pk_fma_f32 v[28:29], v[12:13], v[2:3], v[28:29] op_sel_hi:[1,0,1]
	s_nop 0
	v_mov_b32_e32 v31, v29
	v_pk_add_f32 v[26:27], v[26:27], v[30:31]
	v_add_co_u32_e32 v28, vcc, s14, v14
	v_cvt_pk_bf16_f32 v1, v26, s0
	s_nop 0
	v_addc_co_u32_e32 v29, vcc, 0, v15, vcc
	global_store_short v[28:29], v1, off offset:3584
	v_cvt_pk_bf16_f32 v1, v27, s0
	v_pk_mul_f32 v[30:31], v[12:13], v[26:27]
	global_store_short v[28:29], v1, off offset:3712
	v_sub_f32_e32 v1, v30, v31
	v_pk_mul_f32 v[26:27], v[16:17], v[26:27]
	v_add_f32_e32 v2, v24, v1
	v_add_f32_e32 v1, v26, v27
	v_add_f32_e32 v24, v25, v1
	v_cvt_pk_bf16_f32 v1, v2, s0
	global_store_short v[28:29], v1, off offset:2048
	v_cvt_pk_bf16_f32 v1, v24, s0
	v_pk_mul_f32 v[24:25], v[16:17], v[24:25] op_sel_hi:[1,0]
	global_store_short v[28:29], v1, off offset:2176
	v_pk_fma_f32 v[26:27], v[12:13], v[2:3], v[24:25] neg_lo:[0,0,1] neg_hi:[0,0,1]
	v_pk_fma_f32 v[24:25], v[12:13], v[2:3], v[24:25] op_sel_hi:[1,0,1]
	s_nop 0
	v_mov_b32_e32 v27, v25
	v_pk_add_f32 v[22:23], v[22:23], v[26:27]
	s_nop 0
	v_cvt_pk_bf16_f32 v1, v22, s0
	global_store_short v[28:29], v1, off offset:512
	v_cvt_pk_bf16_f32 v1, v23, s0
	v_pk_mul_f32 v[24:25], v[12:13], v[22:23]
	global_store_short v[28:29], v1, off offset:640
	v_sub_f32_e32 v1, v24, v25
	v_pk_mul_f32 v[22:23], v[16:17], v[22:23]
	v_add_f32_e32 v2, v20, v1
	v_add_f32_e32 v1, v22, v23
	v_add_f32_e32 v20, v21, v1
	v_cvt_pk_bf16_f32 v1, v2, s0
	global_store_short v[14:15], v1, off offset:3072
	v_cvt_pk_bf16_f32 v1, v20, s0
	v_pk_mul_f32 v[20:21], v[12:13], v[20:21] op_sel_hi:[1,0]
	global_store_short v[14:15], v1, off offset:3200
	v_pk_fma_f32 v[22:23], v[16:17], v[2:3], v[20:21] op_sel_hi:[1,0,1] neg_lo:[0,0,1] neg_hi:[0,0,1]
	v_pk_fma_f32 v[16:17], v[16:17], v[2:3], v[20:21] op_sel_hi:[1,0,1]
	s_nop 0
	v_mov_b32_e32 v17, v23
	v_pk_add_f32 v[16:17], v[18:19], v[16:17]
	s_nop 0
	v_cvt_pk_bf16_f32 v1, v17, s0
	global_store_short v[14:15], v1, off offset:1536
	v_cvt_pk_bf16_f32 v1, v16, s0
	global_store_short v[14:15], v1, off offset:1664
	v_mul_f32_e32 v1, v12, v17
	v_fma_f32 v1, -v13, v16, v1
	v_pk_mul_f32 v[12:13], v[12:13], v[16:17]
	v_add_f32_e32 v1, v84, v1
	v_add_f32_e32 v2, v13, v12
	v_add_f32_e32 v146, v85, v2
	v_cvt_pk_bf16_f32 v1, v1, s0
	global_store_short v[14:15], v1, off
.LBB0_549:
	s_or_saveexec_b64 s[10:11], s[10:11]
	v_mov_b64_e32 v[144:145], 0x80
	s_xor_b64 exec, exec, s[10:11]
	s_cbranch_execz .LBB0_546
	global_load_dword v148, v[142:143], off
	global_load_dword v149, v[142:143], off offset:256
	s_nop 0
	global_store_short v[14:15], v3, off
	global_store_short v[14:15], v3, off offset:128
	v_add_co_u32_e32 v142, vcc, s14, v14
	s_waitcnt vmcnt(0) lgkmcnt(0)
	v_add_f32_e32 v148, v1, v148
	v_add_f32_e32 v2, v2, v149
	v_cvt_pk_bf16_f32 v1, v148, s0
	v_cvt_pk_bf16_f32 v149, v2, s0
	v_pk_mul_f32 v[150:151], v[16:17], v[2:3] op_sel_hi:[1,0]
	global_store_short v[14:15], v1, off offset:1536
	global_store_short v[14:15], v149, off offset:1664
	v_pk_fma_f32 v[152:153], v[12:13], v[148:149], v[150:151] neg_lo:[0,0,1] neg_hi:[0,0,1]
	v_pk_fma_f32 v[148:149], v[12:13], v[148:149], v[150:151] op_sel_hi:[1,0,1]
	v_addc_co_u32_e32 v143, vcc, 0, v15, vcc
	v_mov_b32_e32 v153, v149
	v_pk_add_f32 v[84:85], v[84:85], v[152:153]
	v_add_co_u32_e32 v144, vcc, s15, v14
	v_cvt_pk_bf16_f32 v1, v84, s0
	v_cvt_pk_bf16_f32 v2, v85, s0
	v_pk_mul_f32 v[148:149], v[12:13], v[84:85]
	v_pk_mul_f32 v[84:85], v[16:17], v[84:85]
	global_store_short v[14:15], v1, off offset:3072
	global_store_short v[14:15], v2, off offset:3200
	v_sub_f32_e32 v1, v148, v149
	v_add_f32_e32 v84, v84, v85
	v_add_f32_e32 v2, v19, v1
	v_add_f32_e32 v18, v18, v84
	v_cvt_pk_bf16_f32 v1, v2, s0
	v_cvt_pk_bf16_f32 v84, v18, s0
	v_pk_mul_f32 v[18:19], v[16:17], v[18:19] op_sel_hi:[1,0]
	global_store_short v[142:143], v1, off offset:512
	global_store_short v[142:143], v84, off offset:640
	v_pk_fma_f32 v[84:85], v[12:13], v[2:3], v[18:19] neg_lo:[0,0,1] neg_hi:[0,0,1]
	v_pk_fma_f32 v[18:19], v[12:13], v[2:3], v[18:19] op_sel_hi:[1,0,1]
	v_addc_co_u32_e32 v145, vcc, 0, v15, vcc
	v_mov_b32_e32 v85, v19
	v_pk_add_f32 v[18:19], v[20:21], v[84:85]
	v_add_co_u32_e32 v146, vcc, s16, v14
	v_cvt_pk_bf16_f32 v1, v18, s0
	v_cvt_pk_bf16_f32 v2, v19, s0
	v_pk_mul_f32 v[20:21], v[12:13], v[18:19]
	v_pk_mul_f32 v[18:19], v[16:17], v[18:19]
	global_store_short v[142:143], v1, off offset:2048
	global_store_short v[142:143], v2, off offset:2176
	v_sub_f32_e32 v1, v20, v21
	v_add_f32_e32 v18, v18, v19
	v_add_f32_e32 v2, v22, v1
	v_add_f32_e32 v18, v23, v18
	v_cvt_pk_bf16_f32 v1, v2, s0
	v_cvt_pk_bf16_f32 v20, v18, s0
	v_pk_mul_f32 v[18:19], v[16:17], v[18:19] op_sel_hi:[1,0]
	global_store_short v[142:143], v1, off offset:3584
	global_store_short v[142:143], v20, off offset:3712
	v_pk_fma_f32 v[20:21], v[12:13], v[2:3], v[18:19] neg_lo:[0,0,1] neg_hi:[0,0,1]
	v_pk_fma_f32 v[18:19], v[12:13], v[2:3], v[18:19] op_sel_hi:[1,0,1]
	v_addc_co_u32_e32 v147, vcc, 0, v15, vcc
	v_mov_b32_e32 v21, v19
	v_pk_add_f32 v[18:19], v[24:25], v[20:21]
	s_nop 0
	v_cvt_pk_bf16_f32 v1, v18, s0
	v_cvt_pk_bf16_f32 v2, v19, s0
	v_pk_mul_f32 v[20:21], v[12:13], v[18:19]
	v_pk_mul_f32 v[18:19], v[16:17], v[18:19]
	global_store_short v[144:145], v1, off offset:1024
	global_store_short v[144:145], v2, off offset:1152
	v_sub_f32_e32 v1, v20, v21
	v_add_f32_e32 v18, v18, v19
	v_add_f32_e32 v2, v26, v1
	v_add_f32_e32 v18, v27, v18
	v_cvt_pk_bf16_f32 v1, v2, s0
	v_cvt_pk_bf16_f32 v20, v18, s0
	v_pk_mul_f32 v[18:19], v[16:17], v[18:19] op_sel_hi:[1,0]
	global_store_short v[144:145], v1, off offset:2560
	global_store_short v[144:145], v20, off offset:2688
	v_pk_fma_f32 v[20:21], v[12:13], v[2:3], v[18:19] neg_lo:[0,0,1] neg_hi:[0,0,1]
	v_pk_fma_f32 v[18:19], v[12:13], v[2:3], v[18:19] op_sel_hi:[1,0,1]
	v_mov_b64_e32 v[144:145], 0x17a80
	v_mov_b32_e32 v21, v19
	v_pk_add_f32 v[18:19], v[28:29], v[20:21]
	s_nop 0
	v_cvt_pk_bf16_f32 v1, v18, s0
	v_cvt_pk_bf16_f32 v2, v19, s0
	v_pk_mul_f32 v[20:21], v[12:13], v[18:19]
	v_pk_mul_f32 v[18:19], v[16:17], v[18:19]
	global_store_short v[146:147], v1, off
	global_store_short v[146:147], v2, off offset:128
	v_sub_f32_e32 v1, v20, v21
	v_add_f32_e32 v18, v18, v19
	v_add_f32_e32 v2, v30, v1
	v_add_f32_e32 v18, v31, v18
	v_cvt_pk_bf16_f32 v1, v2, s0
	v_cvt_pk_bf16_f32 v20, v18, s0
	v_pk_mul_f32 v[18:19], v[16:17], v[18:19] op_sel_hi:[1,0]
	global_store_short v[146:147], v1, off offset:1536
	global_store_short v[146:147], v20, off offset:1664
	v_pk_fma_f32 v[20:21], v[12:13], v[2:3], v[18:19] neg_lo:[0,0,1] neg_hi:[0,0,1]
	v_pk_fma_f32 v[18:19], v[12:13], v[2:3], v[18:19] op_sel_hi:[1,0,1]
	s_nop 0
	v_mov_b32_e32 v21, v19
	v_pk_add_f32 v[18:19], v[32:33], v[20:21]
	s_nop 0
	v_cvt_pk_bf16_f32 v1, v18, s0
	v_pk_mul_f32 v[20:21], v[12:13], v[18:19]
	v_cvt_pk_bf16_f32 v2, v19, s0
	v_pk_mul_f32 v[18:19], v[16:17], v[18:19]
	global_store_short v[146:147], v1, off offset:3072
	global_store_short v[146:147], v2, off offset:3200
	v_sub_f32_e32 v1, v20, v21
	v_add_f32_e32 v18, v18, v19
	v_add_f32_e32 v2, v34, v1
	v_add_co_u32_e32 v20, vcc, s7, v14
	v_add_f32_e32 v18, v35, v18
	v_cvt_pk_bf16_f32 v1, v2, s0
	v_addc_co_u32_e32 v21, vcc, 0, v15, vcc
	global_store_short v[20:21], v1, off offset:512
	v_cvt_pk_bf16_f32 v1, v18, s0
	v_pk_mul_f32 v[18:19], v[16:17], v[18:19] op_sel_hi:[1,0]
	global_store_short v[20:21], v1, off offset:640
	v_pk_fma_f32 v[22:23], v[12:13], v[2:3], v[18:19] neg_lo:[0,0,1] neg_hi:[0,0,1]
	v_pk_fma_f32 v[18:19], v[12:13], v[2:3], v[18:19] op_sel_hi:[1,0,1]
	s_nop 0
	v_mov_b32_e32 v23, v19
	v_pk_add_f32 v[18:19], v[36:37], v[22:23]
	s_nop 0
	v_cvt_pk_bf16_f32 v1, v18, s0
	global_store_short v[20:21], v1, off offset:2048
	v_cvt_pk_bf16_f32 v1, v19, s0
	v_pk_mul_f32 v[22:23], v[12:13], v[18:19]
	global_store_short v[20:21], v1, off offset:2176
	v_sub_f32_e32 v1, v22, v23
	v_pk_mul_f32 v[18:19], v[16:17], v[18:19]
	v_add_f32_e32 v2, v38, v1
	v_add_f32_e32 v1, v18, v19
	v_add_f32_e32 v18, v39, v1
	v_cvt_pk_bf16_f32 v1, v2, s0
	global_store_short v[20:21], v1, off offset:3584
	v_cvt_pk_bf16_f32 v1, v18, s0
	v_pk_mul_f32 v[18:19], v[16:17], v[18:19] op_sel_hi:[1,0]
	global_store_short v[20:21], v1, off offset:3712
	v_pk_fma_f32 v[20:21], v[12:13], v[2:3], v[18:19] neg_lo:[0,0,1] neg_hi:[0,0,1]
	v_pk_fma_f32 v[18:19], v[12:13], v[2:3], v[18:19] op_sel_hi:[1,0,1]
	s_nop 0
	v_mov_b32_e32 v21, v19
	v_pk_add_f32 v[18:19], v[40:41], v[20:21]
	v_add_co_u32_e32 v20, vcc, s17, v14
	v_cvt_pk_bf16_f32 v1, v18, s0
	s_nop 0
	v_addc_co_u32_e32 v21, vcc, 0, v15, vcc
	global_store_short v[20:21], v1, off offset:1024
	v_cvt_pk_bf16_f32 v1, v19, s0
	v_pk_mul_f32 v[22:23], v[12:13], v[18:19]
	global_store_short v[20:21], v1, off offset:1152
	v_sub_f32_e32 v1, v22, v23
	v_pk_mul_f32 v[18:19], v[16:17], v[18:19]
	v_add_f32_e32 v2, v42, v1
	v_add_f32_e32 v1, v18, v19
	v_add_f32_e32 v18, v43, v1
	v_cvt_pk_bf16_f32 v1, v2, s0
	global_store_short v[20:21], v1, off offset:2560
	v_cvt_pk_bf16_f32 v1, v18, s0
	v_pk_mul_f32 v[18:19], v[16:17], v[18:19] op_sel_hi:[1,0]
	global_store_short v[20:21], v1, off offset:2688
	v_pk_fma_f32 v[20:21], v[12:13], v[2:3], v[18:19] neg_lo:[0,0,1] neg_hi:[0,0,1]
	v_pk_fma_f32 v[18:19], v[12:13], v[2:3], v[18:19] op_sel_hi:[1,0,1]
	s_nop 0
	v_mov_b32_e32 v21, v19
	v_pk_add_f32 v[18:19], v[44:45], v[20:21]
	v_add_co_u32_e32 v20, vcc, s33, v14
	v_cvt_pk_bf16_f32 v1, v18, s0
	s_nop 0
	v_addc_co_u32_e32 v21, vcc, 0, v15, vcc
	global_store_short v[20:21], v1, off
	v_cvt_pk_bf16_f32 v1, v19, s0
	v_pk_mul_f32 v[22:23], v[12:13], v[18:19]
	global_store_short v[20:21], v1, off offset:128
	v_sub_f32_e32 v1, v22, v23
	v_pk_mul_f32 v[18:19], v[16:17], v[18:19]
	v_add_f32_e32 v2, v46, v1
	v_add_f32_e32 v1, v18, v19
	v_add_f32_e32 v18, v47, v1
	v_cvt_pk_bf16_f32 v1, v2, s0
	global_store_short v[20:21], v1, off offset:1536
	v_cvt_pk_bf16_f32 v1, v18, s0
	v_pk_mul_f32 v[18:19], v[16:17], v[18:19] op_sel_hi:[1,0]
	global_store_short v[20:21], v1, off offset:1664
	v_pk_fma_f32 v[22:23], v[12:13], v[2:3], v[18:19] neg_lo:[0,0,1] neg_hi:[0,0,1]
	v_pk_fma_f32 v[18:19], v[12:13], v[2:3], v[18:19] op_sel_hi:[1,0,1]
	s_nop 0
	v_mov_b32_e32 v23, v19
	v_pk_add_f32 v[18:19], v[48:49], v[22:23]
	s_nop 0
	v_cvt_pk_bf16_f32 v1, v18, s0
	global_store_short v[20:21], v1, off offset:3072
	v_cvt_pk_bf16_f32 v1, v19, s0
	global_store_short v[20:21], v1, off offset:3200
	v_pk_mul_f32 v[20:21], v[12:13], v[18:19]
	v_pk_mul_f32 v[18:19], v[16:17], v[18:19]
	v_sub_f32_e32 v1, v20, v21
	v_add_f32_e32 v2, v50, v1
	v_add_f32_e32 v1, v18, v19
	v_add_co_u32_e32 v20, vcc, s34, v14
	v_add_f32_e32 v18, v51, v1
	v_cvt_pk_bf16_f32 v1, v2, s0
	v_addc_co_u32_e32 v21, vcc, 0, v15, vcc
	global_store_short v[20:21], v1, off offset:512
	v_cvt_pk_bf16_f32 v1, v18, s0
	v_pk_mul_f32 v[18:19], v[16:17], v[18:19] op_sel_hi:[1,0]
	global_store_short v[20:21], v1, off offset:640
	v_pk_fma_f32 v[22:23], v[12:13], v[2:3], v[18:19] neg_lo:[0,0,1] neg_hi:[0,0,1]
	v_pk_fma_f32 v[18:19], v[12:13], v[2:3], v[18:19] op_sel_hi:[1,0,1]
	s_nop 0
	v_mov_b32_e32 v23, v19
	v_pk_add_f32 v[18:19], v[52:53], v[22:23]
	s_nop 0
	v_cvt_pk_bf16_f32 v1, v18, s0
	global_store_short v[20:21], v1, off offset:2048
	v_cvt_pk_bf16_f32 v1, v19, s0
	v_pk_mul_f32 v[22:23], v[12:13], v[18:19]
	global_store_short v[20:21], v1, off offset:2176
	v_sub_f32_e32 v1, v22, v23
	v_pk_mul_f32 v[18:19], v[16:17], v[18:19]
	v_add_f32_e32 v2, v54, v1
	v_add_f32_e32 v1, v18, v19
	v_add_f32_e32 v18, v55, v1
	v_cvt_pk_bf16_f32 v1, v2, s0
	global_store_short v[20:21], v1, off offset:3584
	v_cvt_pk_bf16_f32 v1, v18, s0
	v_pk_mul_f32 v[18:19], v[16:17], v[18:19] op_sel_hi:[1,0]
	global_store_short v[20:21], v1, off offset:3712
	v_pk_fma_f32 v[20:21], v[12:13], v[2:3], v[18:19] neg_lo:[0,0,1] neg_hi:[0,0,1]
	v_pk_fma_f32 v[18:19], v[12:13], v[2:3], v[18:19] op_sel_hi:[1,0,1]
	s_nop 0
	v_mov_b32_e32 v21, v19
	v_pk_add_f32 v[18:19], v[56:57], v[20:21]
	v_add_co_u32_e32 v20, vcc, s35, v14
	v_cvt_pk_bf16_f32 v1, v18, s0
	s_nop 0
	v_addc_co_u32_e32 v21, vcc, 0, v15, vcc
	global_store_short v[20:21], v1, off offset:1024
	v_cvt_pk_bf16_f32 v1, v19, s0
	v_pk_mul_f32 v[22:23], v[12:13], v[18:19]
	global_store_short v[20:21], v1, off offset:1152
	v_sub_f32_e32 v1, v22, v23
	v_pk_mul_f32 v[18:19], v[16:17], v[18:19]
	v_add_f32_e32 v2, v58, v1
	v_add_f32_e32 v1, v18, v19
	v_add_f32_e32 v18, v59, v1
	v_cvt_pk_bf16_f32 v1, v2, s0
	global_store_short v[20:21], v1, off offset:2560
	v_cvt_pk_bf16_f32 v1, v18, s0
	v_pk_mul_f32 v[18:19], v[16:17], v[18:19] op_sel_hi:[1,0]
	global_store_short v[20:21], v1, off offset:2688
	v_pk_fma_f32 v[20:21], v[12:13], v[2:3], v[18:19] neg_lo:[0,0,1] neg_hi:[0,0,1]
	v_pk_fma_f32 v[18:19], v[12:13], v[2:3], v[18:19] op_sel_hi:[1,0,1]
	s_nop 0
	v_mov_b32_e32 v21, v19
	v_pk_add_f32 v[18:19], v[60:61], v[20:21]
	v_add_co_u32_e32 v20, vcc, s38, v14
	v_cvt_pk_bf16_f32 v1, v18, s0
	s_nop 0
	v_addc_co_u32_e32 v21, vcc, 0, v15, vcc
	global_store_short v[20:21], v1, off
	v_cvt_pk_bf16_f32 v1, v19, s0
	v_pk_mul_f32 v[22:23], v[12:13], v[18:19]
	global_store_short v[20:21], v1, off offset:128
	v_sub_f32_e32 v1, v22, v23
	v_pk_mul_f32 v[18:19], v[16:17], v[18:19]
	v_add_f32_e32 v2, v62, v1
	v_add_f32_e32 v1, v18, v19
	v_add_f32_e32 v18, v63, v1
	v_cvt_pk_bf16_f32 v1, v2, s0
	global_store_short v[20:21], v1, off offset:1536
	v_cvt_pk_bf16_f32 v1, v18, s0
	v_pk_mul_f32 v[18:19], v[16:17], v[18:19] op_sel_hi:[1,0]
	global_store_short v[20:21], v1, off offset:1664
	v_pk_fma_f32 v[22:23], v[12:13], v[2:3], v[18:19] neg_lo:[0,0,1] neg_hi:[0,0,1]
	v_pk_fma_f32 v[18:19], v[12:13], v[2:3], v[18:19] op_sel_hi:[1,0,1]
	s_nop 0
	v_mov_b32_e32 v23, v19
	v_pk_add_f32 v[18:19], v[64:65], v[22:23]
	s_nop 0
	v_cvt_pk_bf16_f32 v1, v18, s0
	global_store_short v[20:21], v1, off offset:3072
	v_cvt_pk_bf16_f32 v1, v19, s0
	global_store_short v[20:21], v1, off offset:3200
	v_pk_mul_f32 v[20:21], v[12:13], v[18:19]
	v_pk_mul_f32 v[18:19], v[16:17], v[18:19]
	v_sub_f32_e32 v1, v20, v21
	v_add_f32_e32 v2, v66, v1
	v_add_f32_e32 v1, v18, v19
	v_add_co_u32_e32 v20, vcc, s39, v14
	v_add_f32_e32 v18, v67, v1
	v_cvt_pk_bf16_f32 v1, v2, s0
	v_addc_co_u32_e32 v21, vcc, 0, v15, vcc
	global_store_short v[20:21], v1, off offset:512
	v_cvt_pk_bf16_f32 v1, v18, s0
	v_pk_mul_f32 v[18:19], v[16:17], v[18:19] op_sel_hi:[1,0]
	global_store_short v[20:21], v1, off offset:640
	v_pk_fma_f32 v[22:23], v[12:13], v[2:3], v[18:19] neg_lo:[0,0,1] neg_hi:[0,0,1]
	v_pk_fma_f32 v[18:19], v[12:13], v[2:3], v[18:19] op_sel_hi:[1,0,1]
	s_nop 0
	v_mov_b32_e32 v23, v19
	v_pk_add_f32 v[18:19], v[68:69], v[22:23]
	s_nop 0
	v_cvt_pk_bf16_f32 v1, v18, s0
	global_store_short v[20:21], v1, off offset:2048
	v_cvt_pk_bf16_f32 v1, v19, s0
	v_pk_mul_f32 v[22:23], v[12:13], v[18:19]
	global_store_short v[20:21], v1, off offset:2176
	v_sub_f32_e32 v1, v22, v23
	v_pk_mul_f32 v[18:19], v[16:17], v[18:19]
	v_add_f32_e32 v2, v70, v1
	v_add_f32_e32 v1, v18, v19
	v_add_f32_e32 v18, v71, v1
	v_cvt_pk_bf16_f32 v1, v2, s0
	global_store_short v[20:21], v1, off offset:3584
	v_cvt_pk_bf16_f32 v1, v18, s0
	v_pk_mul_f32 v[18:19], v[16:17], v[18:19] op_sel_hi:[1,0]
	global_store_short v[20:21], v1, off offset:3712
	v_pk_fma_f32 v[20:21], v[12:13], v[2:3], v[18:19] neg_lo:[0,0,1] neg_hi:[0,0,1]
	v_pk_fma_f32 v[18:19], v[12:13], v[2:3], v[18:19] op_sel_hi:[1,0,1]
	s_nop 0
	v_mov_b32_e32 v21, v19
	v_pk_add_f32 v[18:19], v[72:73], v[20:21]
	v_add_co_u32_e32 v20, vcc, s40, v14
	v_cvt_pk_bf16_f32 v1, v18, s0
	s_nop 0
	v_addc_co_u32_e32 v21, vcc, 0, v15, vcc
	global_store_short v[20:21], v1, off offset:1024
	v_cvt_pk_bf16_f32 v1, v19, s0
	v_pk_mul_f32 v[22:23], v[12:13], v[18:19]
	global_store_short v[20:21], v1, off offset:1152
	v_sub_f32_e32 v1, v22, v23
	v_pk_mul_f32 v[18:19], v[16:17], v[18:19]
	v_add_f32_e32 v2, v74, v1
	v_add_f32_e32 v1, v18, v19
	v_add_f32_e32 v18, v75, v1
	v_cvt_pk_bf16_f32 v1, v2, s0
	global_store_short v[20:21], v1, off offset:2560
	v_cvt_pk_bf16_f32 v1, v18, s0
	v_pk_mul_f32 v[18:19], v[16:17], v[18:19] op_sel_hi:[1,0]
	global_store_short v[20:21], v1, off offset:2688
	v_pk_fma_f32 v[20:21], v[12:13], v[2:3], v[18:19] neg_lo:[0,0,1] neg_hi:[0,0,1]
	v_pk_fma_f32 v[18:19], v[12:13], v[2:3], v[18:19] op_sel_hi:[1,0,1]
	s_nop 0
	v_mov_b32_e32 v21, v19
	v_pk_add_f32 v[18:19], v[76:77], v[20:21]
	v_add_co_u32_e32 v20, vcc, s41, v14
	v_cvt_pk_bf16_f32 v1, v18, s0
	s_nop 0
	v_addc_co_u32_e32 v21, vcc, 0, v15, vcc
	global_store_short v[20:21], v1, off
	v_cvt_pk_bf16_f32 v1, v19, s0
	v_pk_mul_f32 v[22:23], v[12:13], v[18:19]
	global_store_short v[20:21], v1, off offset:128
	v_sub_f32_e32 v1, v22, v23
	v_pk_mul_f32 v[18:19], v[16:17], v[18:19]
	v_add_f32_e32 v2, v78, v1
	v_add_f32_e32 v1, v18, v19
	v_add_f32_e32 v18, v79, v1
	v_cvt_pk_bf16_f32 v1, v2, s0
	global_store_short v[20:21], v1, off offset:1536
	v_cvt_pk_bf16_f32 v1, v18, s0
	v_pk_mul_f32 v[18:19], v[16:17], v[18:19] op_sel_hi:[1,0]
	global_store_short v[20:21], v1, off offset:1664
	v_pk_fma_f32 v[22:23], v[12:13], v[2:3], v[18:19] neg_lo:[0,0,1] neg_hi:[0,0,1]
	v_pk_fma_f32 v[18:19], v[12:13], v[2:3], v[18:19] op_sel_hi:[1,0,1]
	s_nop 0
	v_mov_b32_e32 v23, v19
	v_pk_add_f32 v[18:19], v[80:81], v[22:23]
	s_nop 0
	v_cvt_pk_bf16_f32 v1, v18, s0
	global_store_short v[20:21], v1, off offset:3072
	v_cvt_pk_bf16_f32 v1, v19, s0
	global_store_short v[20:21], v1, off offset:3200
	v_pk_mul_f32 v[20:21], v[12:13], v[18:19]
	v_pk_mul_f32 v[18:19], v[16:17], v[18:19]
	v_sub_f32_e32 v1, v20, v21
	v_add_f32_e32 v2, v82, v1
	v_add_f32_e32 v1, v18, v19
	v_add_co_u32_e32 v20, vcc, s42, v14
	v_add_f32_e32 v18, v83, v1
	v_cvt_pk_bf16_f32 v1, v2, s0
	v_addc_co_u32_e32 v21, vcc, 0, v15, vcc
	global_store_short v[20:21], v1, off offset:512
	v_cvt_pk_bf16_f32 v1, v18, s0
	v_pk_mul_f32 v[18:19], v[16:17], v[18:19] op_sel_hi:[1,0]
	global_store_short v[20:21], v1, off offset:640
	v_pk_fma_f32 v[22:23], v[12:13], v[2:3], v[18:19] neg_lo:[0,0,1] neg_hi:[0,0,1]
	v_pk_fma_f32 v[18:19], v[12:13], v[2:3], v[18:19] op_sel_hi:[1,0,1]
	s_nop 0
	v_mov_b32_e32 v23, v19
	v_pk_add_f32 v[18:19], v[86:87], v[22:23]
	s_nop 0
	v_cvt_pk_bf16_f32 v1, v18, s0
	global_store_short v[20:21], v1, off offset:2048
	v_cvt_pk_bf16_f32 v1, v19, s0
	v_pk_mul_f32 v[22:23], v[12:13], v[18:19]
	global_store_short v[20:21], v1, off offset:2176
	v_sub_f32_e32 v1, v22, v23
	v_pk_mul_f32 v[18:19], v[16:17], v[18:19]
	v_add_f32_e32 v2, v88, v1
	v_add_f32_e32 v1, v18, v19
	v_add_f32_e32 v18, v89, v1
	v_cvt_pk_bf16_f32 v1, v2, s0
	global_store_short v[20:21], v1, off offset:3584
	v_cvt_pk_bf16_f32 v1, v18, s0
	v_pk_mul_f32 v[18:19], v[16:17], v[18:19] op_sel_hi:[1,0]
	global_store_short v[20:21], v1, off offset:3712
	v_pk_fma_f32 v[20:21], v[12:13], v[2:3], v[18:19] neg_lo:[0,0,1] neg_hi:[0,0,1]
	v_pk_fma_f32 v[18:19], v[12:13], v[2:3], v[18:19] op_sel_hi:[1,0,1]
	s_nop 0
	v_mov_b32_e32 v21, v19
	v_pk_add_f32 v[18:19], v[90:91], v[20:21]
	v_add_co_u32_e32 v20, vcc, s43, v14
	v_cvt_pk_bf16_f32 v1, v18, s0
	s_nop 0
	v_addc_co_u32_e32 v21, vcc, 0, v15, vcc
	global_store_short v[20:21], v1, off offset:1024
	v_cvt_pk_bf16_f32 v1, v19, s0
	v_pk_mul_f32 v[22:23], v[12:13], v[18:19]
	global_store_short v[20:21], v1, off offset:1152
	v_sub_f32_e32 v1, v22, v23
	v_pk_mul_f32 v[18:19], v[16:17], v[18:19]
	v_add_f32_e32 v2, v92, v1
	v_add_f32_e32 v1, v18, v19
	v_add_f32_e32 v18, v93, v1
	v_cvt_pk_bf16_f32 v1, v2, s0
	global_store_short v[20:21], v1, off offset:2560
	v_cvt_pk_bf16_f32 v1, v18, s0
	v_pk_mul_f32 v[18:19], v[16:17], v[18:19] op_sel_hi:[1,0]
	global_store_short v[20:21], v1, off offset:2688
	v_pk_fma_f32 v[20:21], v[12:13], v[2:3], v[18:19] neg_lo:[0,0,1] neg_hi:[0,0,1]
	v_pk_fma_f32 v[18:19], v[12:13], v[2:3], v[18:19] op_sel_hi:[1,0,1]
	s_nop 0
	v_mov_b32_e32 v21, v19
	v_pk_add_f32 v[18:19], v[94:95], v[20:21]
	v_add_co_u32_e32 v20, vcc, s44, v14
	v_cvt_pk_bf16_f32 v1, v18, s0
	s_nop 0
	v_addc_co_u32_e32 v21, vcc, 0, v15, vcc
	global_store_short v[20:21], v1, off
	v_cvt_pk_bf16_f32 v1, v19, s0
	v_pk_mul_f32 v[22:23], v[12:13], v[18:19]
	global_store_short v[20:21], v1, off offset:128
	v_sub_f32_e32 v1, v22, v23
	v_pk_mul_f32 v[18:19], v[16:17], v[18:19]
	v_add_f32_e32 v2, v96, v1
	v_add_f32_e32 v1, v18, v19
	v_add_f32_e32 v18, v97, v1
	v_cvt_pk_bf16_f32 v1, v2, s0
	global_store_short v[20:21], v1, off offset:1536
	v_cvt_pk_bf16_f32 v1, v18, s0
	v_pk_mul_f32 v[18:19], v[16:17], v[18:19] op_sel_hi:[1,0]
	global_store_short v[20:21], v1, off offset:1664
	v_pk_fma_f32 v[22:23], v[12:13], v[2:3], v[18:19] neg_lo:[0,0,1] neg_hi:[0,0,1]
	v_pk_fma_f32 v[18:19], v[12:13], v[2:3], v[18:19] op_sel_hi:[1,0,1]
	s_nop 0
	v_mov_b32_e32 v23, v19
	v_pk_add_f32 v[18:19], v[98:99], v[22:23]
	s_nop 0
	v_cvt_pk_bf16_f32 v1, v18, s0
	global_store_short v[20:21], v1, off offset:3072
	v_cvt_pk_bf16_f32 v1, v19, s0
	global_store_short v[20:21], v1, off offset:3200
	v_pk_mul_f32 v[20:21], v[12:13], v[18:19]
	v_pk_mul_f32 v[18:19], v[16:17], v[18:19]
	v_sub_f32_e32 v1, v20, v21
	v_add_f32_e32 v2, v100, v1
	v_add_f32_e32 v1, v18, v19
	v_add_co_u32_e32 v20, vcc, s2, v14
	v_add_f32_e32 v18, v101, v1
	v_cvt_pk_bf16_f32 v1, v2, s0
	v_addc_co_u32_e32 v21, vcc, 0, v15, vcc
	global_store_short v[20:21], v1, off offset:512
	v_cvt_pk_bf16_f32 v1, v18, s0
	v_pk_mul_f32 v[18:19], v[16:17], v[18:19] op_sel_hi:[1,0]
	global_store_short v[20:21], v1, off offset:640
	v_pk_fma_f32 v[22:23], v[12:13], v[2:3], v[18:19] neg_lo:[0,0,1] neg_hi:[0,0,1]
	v_pk_fma_f32 v[18:19], v[12:13], v[2:3], v[18:19] op_sel_hi:[1,0,1]
	s_nop 0
	v_mov_b32_e32 v23, v19
	v_pk_add_f32 v[18:19], v[102:103], v[22:23]
	s_nop 0
	v_cvt_pk_bf16_f32 v1, v18, s0
	global_store_short v[20:21], v1, off offset:2048
	v_cvt_pk_bf16_f32 v1, v19, s0
	v_pk_mul_f32 v[22:23], v[12:13], v[18:19]
	global_store_short v[20:21], v1, off offset:2176
	v_sub_f32_e32 v1, v22, v23
	v_pk_mul_f32 v[18:19], v[16:17], v[18:19]
	v_add_f32_e32 v2, v104, v1
	v_add_f32_e32 v1, v18, v19
	v_add_f32_e32 v18, v105, v1
	v_cvt_pk_bf16_f32 v1, v2, s0
	global_store_short v[20:21], v1, off offset:3584
	v_cvt_pk_bf16_f32 v1, v18, s0
	v_pk_mul_f32 v[18:19], v[16:17], v[18:19] op_sel_hi:[1,0]
	global_store_short v[20:21], v1, off offset:3712
	v_pk_fma_f32 v[20:21], v[12:13], v[2:3], v[18:19] neg_lo:[0,0,1] neg_hi:[0,0,1]
	v_pk_fma_f32 v[18:19], v[12:13], v[2:3], v[18:19] op_sel_hi:[1,0,1]
	s_nop 0
	v_mov_b32_e32 v21, v19
	v_pk_add_f32 v[18:19], v[106:107], v[20:21]
	v_add_co_u32_e32 v20, vcc, s55, v14
	v_cvt_pk_bf16_f32 v1, v18, s0
	s_nop 0
	v_addc_co_u32_e32 v21, vcc, 0, v15, vcc
	global_store_short v[20:21], v1, off offset:1024
	v_cvt_pk_bf16_f32 v1, v19, s0
	v_pk_mul_f32 v[22:23], v[12:13], v[18:19]
	global_store_short v[20:21], v1, off offset:1152
	v_sub_f32_e32 v1, v22, v23
	v_pk_mul_f32 v[18:19], v[16:17], v[18:19]
	v_add_f32_e32 v2, v108, v1
	v_add_f32_e32 v1, v18, v19
	v_add_f32_e32 v18, v109, v1
	v_cvt_pk_bf16_f32 v1, v2, s0
	global_store_short v[20:21], v1, off offset:2560
	v_cvt_pk_bf16_f32 v1, v18, s0
	v_pk_mul_f32 v[18:19], v[16:17], v[18:19] op_sel_hi:[1,0]
	global_store_short v[20:21], v1, off offset:2688
	v_pk_fma_f32 v[20:21], v[12:13], v[2:3], v[18:19] neg_lo:[0,0,1] neg_hi:[0,0,1]
	v_pk_fma_f32 v[18:19], v[12:13], v[2:3], v[18:19] op_sel_hi:[1,0,1]
	s_nop 0
	v_mov_b32_e32 v21, v19
	v_pk_add_f32 v[18:19], v[110:111], v[20:21]
	v_add_co_u32_e32 v20, vcc, s54, v14
	v_cvt_pk_bf16_f32 v1, v18, s0
	s_nop 0
	v_addc_co_u32_e32 v21, vcc, 0, v15, vcc
	global_store_short v[20:21], v1, off
	v_cvt_pk_bf16_f32 v1, v19, s0
	v_pk_mul_f32 v[22:23], v[12:13], v[18:19]
	global_store_short v[20:21], v1, off offset:128
	v_sub_f32_e32 v1, v22, v23
	v_pk_mul_f32 v[18:19], v[16:17], v[18:19]
	v_add_f32_e32 v2, v112, v1
	v_add_f32_e32 v1, v18, v19
	v_add_f32_e32 v18, v113, v1
	v_cvt_pk_bf16_f32 v1, v2, s0
	global_store_short v[20:21], v1, off offset:1536
	v_cvt_pk_bf16_f32 v1, v18, s0
	v_pk_mul_f32 v[18:19], v[16:17], v[18:19] op_sel_hi:[1,0]
	global_store_short v[20:21], v1, off offset:1664
	v_pk_fma_f32 v[22:23], v[12:13], v[2:3], v[18:19] neg_lo:[0,0,1] neg_hi:[0,0,1]
	v_pk_fma_f32 v[18:19], v[12:13], v[2:3], v[18:19] op_sel_hi:[1,0,1]
	s_nop 0
	v_mov_b32_e32 v23, v19
	v_pk_add_f32 v[18:19], v[114:115], v[22:23]
	s_nop 0
	v_cvt_pk_bf16_f32 v1, v18, s0
	global_store_short v[20:21], v1, off offset:3072
	v_cvt_pk_bf16_f32 v1, v19, s0
	global_store_short v[20:21], v1, off offset:3200
	v_pk_mul_f32 v[20:21], v[12:13], v[18:19]
	v_pk_mul_f32 v[18:19], v[16:17], v[18:19]
	v_sub_f32_e32 v1, v20, v21
	v_add_f32_e32 v2, v116, v1
	v_add_f32_e32 v1, v18, v19
	v_add_co_u32_e32 v20, vcc, s51, v14
	v_add_f32_e32 v18, v117, v1
	v_cvt_pk_bf16_f32 v1, v2, s0
	v_addc_co_u32_e32 v21, vcc, 0, v15, vcc
	global_store_short v[20:21], v1, off offset:512
	v_cvt_pk_bf16_f32 v1, v18, s0
	v_pk_mul_f32 v[18:19], v[16:17], v[18:19] op_sel_hi:[1,0]
	global_store_short v[20:21], v1, off offset:640
	v_pk_fma_f32 v[22:23], v[12:13], v[2:3], v[18:19] neg_lo:[0,0,1] neg_hi:[0,0,1]
	v_pk_fma_f32 v[18:19], v[12:13], v[2:3], v[18:19] op_sel_hi:[1,0,1]
	s_nop 0
	v_mov_b32_e32 v23, v19
	v_pk_add_f32 v[18:19], v[118:119], v[22:23]
	s_nop 0
	v_cvt_pk_bf16_f32 v1, v18, s0
	global_store_short v[20:21], v1, off offset:2048
	v_cvt_pk_bf16_f32 v1, v19, s0
	v_pk_mul_f32 v[22:23], v[12:13], v[18:19]
	global_store_short v[20:21], v1, off offset:2176
	v_sub_f32_e32 v1, v22, v23
	v_pk_mul_f32 v[18:19], v[16:17], v[18:19]
	v_add_f32_e32 v2, v120, v1
	v_add_f32_e32 v1, v18, v19
	v_add_f32_e32 v18, v121, v1
	v_cvt_pk_bf16_f32 v1, v2, s0
	global_store_short v[20:21], v1, off offset:3584
	v_cvt_pk_bf16_f32 v1, v18, s0
	v_pk_mul_f32 v[18:19], v[16:17], v[18:19] op_sel_hi:[1,0]
	global_store_short v[20:21], v1, off offset:3712
	v_pk_fma_f32 v[20:21], v[12:13], v[2:3], v[18:19] neg_lo:[0,0,1] neg_hi:[0,0,1]
	v_pk_fma_f32 v[18:19], v[12:13], v[2:3], v[18:19] op_sel_hi:[1,0,1]
	s_nop 0
	v_mov_b32_e32 v21, v19
	v_pk_add_f32 v[18:19], v[122:123], v[20:21]
	v_add_co_u32_e32 v20, vcc, s50, v14
	v_cvt_pk_bf16_f32 v1, v18, s0
	s_nop 0
	v_addc_co_u32_e32 v21, vcc, 0, v15, vcc
	global_store_short v[20:21], v1, off offset:1024
	v_cvt_pk_bf16_f32 v1, v19, s0
	v_pk_mul_f32 v[22:23], v[12:13], v[18:19]
	global_store_short v[20:21], v1, off offset:1152
	v_sub_f32_e32 v1, v22, v23
	v_pk_mul_f32 v[18:19], v[16:17], v[18:19]
	v_add_f32_e32 v2, v124, v1
	v_add_f32_e32 v1, v18, v19
	v_add_f32_e32 v18, v125, v1
	v_cvt_pk_bf16_f32 v1, v2, s0
	global_store_short v[20:21], v1, off offset:2560
	v_cvt_pk_bf16_f32 v1, v18, s0
	v_pk_mul_f32 v[18:19], v[16:17], v[18:19] op_sel_hi:[1,0]
	global_store_short v[20:21], v1, off offset:2688
	v_pk_fma_f32 v[20:21], v[12:13], v[2:3], v[18:19] neg_lo:[0,0,1] neg_hi:[0,0,1]
	v_pk_fma_f32 v[18:19], v[12:13], v[2:3], v[18:19] op_sel_hi:[1,0,1]
	s_nop 0
	v_mov_b32_e32 v21, v19
	v_pk_add_f32 v[18:19], v[126:127], v[20:21]
	v_add_co_u32_e32 v20, vcc, s49, v14
	v_cvt_pk_bf16_f32 v1, v18, s0
	s_nop 0
	v_addc_co_u32_e32 v21, vcc, 0, v15, vcc
	global_store_short v[20:21], v1, off
	v_cvt_pk_bf16_f32 v1, v19, s0
	v_pk_mul_f32 v[22:23], v[12:13], v[18:19]
	global_store_short v[20:21], v1, off offset:128
	v_sub_f32_e32 v1, v22, v23
	v_pk_mul_f32 v[18:19], v[16:17], v[18:19]
	v_add_f32_e32 v2, v132, v1
	v_add_f32_e32 v1, v18, v19
	v_add_f32_e32 v18, v133, v1
	v_cvt_pk_bf16_f32 v1, v2, s0
	global_store_short v[20:21], v1, off offset:1536
	v_cvt_pk_bf16_f32 v1, v18, s0
	v_pk_mul_f32 v[18:19], v[16:17], v[18:19] op_sel_hi:[1,0]
	global_store_short v[20:21], v1, off offset:1664
	v_pk_fma_f32 v[22:23], v[12:13], v[2:3], v[18:19] neg_lo:[0,0,1] neg_hi:[0,0,1]
	v_pk_fma_f32 v[18:19], v[12:13], v[2:3], v[18:19] op_sel_hi:[1,0,1]
	s_nop 0
	v_mov_b32_e32 v23, v19
	v_pk_add_f32 v[18:19], v[130:131], v[22:23]
	s_nop 0
	v_cvt_pk_bf16_f32 v1, v18, s0
	global_store_short v[20:21], v1, off offset:3072
	v_cvt_pk_bf16_f32 v1, v19, s0
	global_store_short v[20:21], v1, off offset:3200
	v_pk_mul_f32 v[20:21], v[12:13], v[18:19]
	v_pk_mul_f32 v[18:19], v[16:17], v[18:19]
	v_sub_f32_e32 v1, v20, v21
	v_add_f32_e32 v2, v134, v1
	v_add_f32_e32 v1, v18, v19
	v_add_co_u32_e32 v20, vcc, s48, v14
	v_add_f32_e32 v18, v135, v1
	v_cvt_pk_bf16_f32 v1, v2, s0
	v_addc_co_u32_e32 v21, vcc, 0, v15, vcc
	global_store_short v[20:21], v1, off offset:512
	v_cvt_pk_bf16_f32 v1, v18, s0
	v_pk_mul_f32 v[18:19], v[16:17], v[18:19] op_sel_hi:[1,0]
	global_store_short v[20:21], v1, off offset:640
	v_pk_fma_f32 v[22:23], v[12:13], v[2:3], v[18:19] neg_lo:[0,0,1] neg_hi:[0,0,1]
	v_pk_fma_f32 v[18:19], v[12:13], v[2:3], v[18:19] op_sel_hi:[1,0,1]
	s_nop 0
	v_mov_b32_e32 v23, v19
	v_pk_add_f32 v[18:19], v[128:129], v[22:23]
	s_nop 0
	v_cvt_pk_bf16_f32 v1, v18, s0
	global_store_short v[20:21], v1, off offset:2048
	v_cvt_pk_bf16_f32 v1, v19, s0
	v_pk_mul_f32 v[22:23], v[12:13], v[18:19]
	global_store_short v[20:21], v1, off offset:2176
	v_sub_f32_e32 v1, v22, v23
	v_pk_mul_f32 v[18:19], v[16:17], v[18:19]
	v_add_f32_e32 v2, v140, v1
	v_add_f32_e32 v1, v18, v19
	v_add_f32_e32 v18, v141, v1
	v_cvt_pk_bf16_f32 v1, v2, s0
	global_store_short v[20:21], v1, off offset:3584
	v_cvt_pk_bf16_f32 v1, v18, s0
	v_pk_mul_f32 v[18:19], v[12:13], v[18:19] op_sel_hi:[1,0]
	global_store_short v[20:21], v1, off offset:3712
	v_pk_fma_f32 v[20:21], v[16:17], v[2:3], v[18:19] op_sel_hi:[1,0,1] neg_lo:[0,0,1] neg_hi:[0,0,1]
	v_pk_fma_f32 v[16:17], v[16:17], v[2:3], v[18:19] op_sel_hi:[1,0,1]
	v_add_co_u32_e32 v18, vcc, s45, v14
	v_mov_b32_e32 v17, v21
	v_pk_add_f32 v[16:17], v[138:139], v[16:17]
	v_addc_co_u32_e32 v19, vcc, 0, v15, vcc
	v_cvt_pk_bf16_f32 v1, v17, s0
	global_store_short v[18:19], v1, off offset:1024
	v_cvt_pk_bf16_f32 v1, v16, s0
	global_store_short v[18:19], v1, off offset:1152
	v_mul_f32_e32 v1, v12, v17
	v_fma_f32 v1, -v13, v16, v1
	v_pk_mul_f32 v[12:13], v[12:13], v[16:17]
	v_add_f32_e32 v1, v136, v1
	v_add_f32_e32 v2, v13, v12
	v_add_f32_e32 v146, v137, v2
	v_cvt_pk_bf16_f32 v1, v1, s0
	global_store_short v[18:19], v1, off offset:2560
	s_branch .LBB0_546
